# GEMM K-loops (K=1024) rewritten: triple half-buffer LDS ring, MFMA interleaved with LDS reads/writes and global loads
# speedup vs baseline: 1.0850x; 1.0581x over previous
.LBB0_146:
	s_ashr_i32 s8, s10, 3
	s_lshl_b32 s11, s8, 1
	s_and_b32 s9, s8, -16
	s_and_b32 s11, s11, 14
	s_or_b32 s9, s11, s9
	s_bfe_u32 s11, s8, 0x10003
	s_or_b32 s9, s9, s11
	s_cmp_lt_i32 s8, 0
	s_cselect_b32 s8, s9, s8
	s_lshl_b32 s9, s10, 5
	s_and_b32 s9, s9, 0xe0
	s_add_i32 s8, s8, s9
	s_ashr_i32 s9, s8, 31
	s_lshr_b32 s9, s9, 27
	s_add_i32 s9, s8, s9
	s_and_b32 s11, s9, 0xffffffe0
	s_sub_i32 s8, s8, s11
	s_ashr_i32 s11, s8, 31
	s_lshr_b32 s11, s11, 29
	s_add_i32 s11, s8, s11
	s_ashr_i32 s12, s11, 3
	s_lshl_b32 s9, s9, 5
	s_and_b32 s9, s9, 0xfffffc00
	s_lshl_b32 s11, s12, 8
	s_add_i32 s11, s11, s9
	s_lshl_b32 s9, s12, 10
	s_lshl_b32 s8, s8, 7
	v_mov_b32_e32 v6, v188
	s_sub_i32 s12, s8, s9
	s_mov_b32 s13, 0x30000
	v_ashrrev_i32_e32 v7, 3, v6
	v_lshlrev_b32_e32 v4, 4, v6
	v_and_b32_e32 v176, 0x70, v4
	v_add_u32_e32 v4, s12, v7
	v_ashrrev_i32_e32 v5, 31, v4
	v_add_u32_e32 v0, s11, v7
	v_lshlrev_b64 v[4:5], 11, v[4:5]
	v_ashrrev_i32_e32 v1, 31, v0
	v_lshl_add_u64 v[4:5], s[4:5], 0, v[4:5]
	v_xor_b32_e32 v8, v7, v6
	v_lshlrev_b64 v[0:1], 11, v[0:1]
	v_lshl_add_u64 v[178:179], v[4:5], 0, v[176:177]
	v_lshlrev_b32_e32 v4, 4, v8
	v_lshl_add_u64 v[2:3], s[2:3], 0, v[0:1]
	v_and_b32_e32 v4, 0x70, v4
	v_lshl_add_u64 v[2:3], v[2:3], 0, v[176:177]
	v_lshl_or_b32 v176, v7, 7, v4
	v_lshrrev_b32_e32 v4, 4, v6
	v_and_b32_e32 v15, 7, v6
	v_bitop3_b32 v20, v4, v15, 3 bitop3:0x6c
	v_add_co_u32_e32 v4, vcc, s13, v178
	v_lshlrev_b32_e32 v12, 7, v6
	s_nop 0
	v_addc_co_u32_e32 v5, vcc, 0, v179, vcc
	v_bfe_u32 v14, v6, 4, 2
	v_add_co_u32_e32 v6, vcc, s14, v178
	s_mov_b32 s8, 0x70000
	s_nop 0
	v_addc_co_u32_e32 v7, vcc, 0, v179, vcc
	global_load_dwordx4 v[8:11], v[4:5], off
	global_load_dwordx4 v[16:19], v[6:7], off
	v_add_co_u32_e32 v4, vcc, s31, v178
	v_and_b32_e32 v13, 0xffffc780, v12
	s_nop 0
	v_addc_co_u32_e32 v5, vcc, 0, v179, vcc
	v_add_co_u32_e32 v6, vcc, s8, v2
	s_mov_b32 s8, 0x60000
	s_nop 0
	v_addc_co_u32_e32 v7, vcc, 0, v3, vcc
	global_load_dwordx4 v[32:35], v[4:5], off
	global_load_dwordx4 v[40:43], v[6:7], off
	v_add_co_u32_e32 v4, vcc, s8, v2
	s_mov_b32 s8, 0x50000
	s_nop 0
	v_addc_co_u32_e32 v5, vcc, 0, v3, vcc
	v_add_co_u32_e32 v6, vcc, s8, v2
	v_and_b32_e32 v12, 0x2780, v12
	s_nop 0
	v_addc_co_u32_e32 v7, vcc, 0, v3, vcc
	global_load_dwordx4 v[60:63], v[4:5], off
	global_load_dwordx4 v[68:71], v[6:7], off
	v_add_co_u32_e32 v4, vcc, 0x40000, v2
	v_bitop3_b32 v14, v14, v15, 4 bitop3:0x36
	s_nop 0
	v_addc_co_u32_e32 v5, vcc, 0, v3, vcc
	v_add_co_u32_e32 v6, vcc, s13, v2
	v_lshl_or_b32 v0, v15, 4, v0
	s_nop 0
	v_addc_co_u32_e32 v7, vcc, 0, v3, vcc
	global_load_dwordx4 v[80:83], v[4:5], off
	global_load_dwordx4 v[88:91], v[6:7], off
	v_add_co_u32_e32 v4, vcc, s14, v2
	v_mov_b32_e32 v140, 0
	s_nop 0
	v_addc_co_u32_e32 v5, vcc, 0, v3, vcc
	v_add_co_u32_e32 v6, vcc, 0x10000, v2
	v_lshl_add_u64 v[180:181], s[34:35], 0, v[0:1]
	s_nop 0
	v_addc_co_u32_e32 v7, vcc, 0, v3, vcc
	global_load_dwordx4 v[104:107], v[4:5], off
	global_load_dwordx4 v[112:115], v[6:7], off
	global_load_dwordx4 v[56:59], v[178:179], off
	global_load_dwordx4 v[116:119], v[2:3], off
	v_lshlrev_b32_e32 v2, 4, v20
	v_or_b32_e32 v185, v13, v2
	v_or_b32_e32 v184, v12, v2
	v_lshlrev_b32_e32 v2, 4, v14
	v_or_b32_e32 v183, v13, v2
	v_or_b32_e32 v182, v12, v2
	s_mov_b64 s[8:9], 0
	v_mov_b32_e32 v141, v140
	v_mov_b32_e32 v142, v140
	v_mov_b32_e32 v143, v140
	v_mov_b32_e32 v0, v140
	v_mov_b32_e32 v1, v140
	v_mov_b32_e32 v2, v140
	v_mov_b32_e32 v3, v140
	v_mov_b32_e32 v4, v140
	v_mov_b32_e32 v5, v140
	v_mov_b32_e32 v6, v140
	v_mov_b32_e32 v7, v140
	v_mov_b32_e32 v12, v140
	v_mov_b32_e32 v13, v140
	v_mov_b32_e32 v14, v140
	v_mov_b32_e32 v15, v140
	v_mov_b32_e32 v20, v140
	v_mov_b32_e32 v21, v140
	v_mov_b32_e32 v22, v140
	v_mov_b32_e32 v23, v140
	v_mov_b32_e32 v24, v140
	v_mov_b32_e32 v25, v140
	v_mov_b32_e32 v26, v140
	v_mov_b32_e32 v27, v140
	v_mov_b32_e32 v28, v140
	v_mov_b32_e32 v29, v140
	v_mov_b32_e32 v30, v140
	v_mov_b32_e32 v31, v140
	v_mov_b32_e32 v36, v140
	v_mov_b32_e32 v37, v140
	v_mov_b32_e32 v38, v140
	v_mov_b32_e32 v39, v140
	v_mov_b32_e32 v44, v140
	v_mov_b32_e32 v45, v140
	v_mov_b32_e32 v46, v140
	v_mov_b32_e32 v47, v140
	v_mov_b32_e32 v48, v140
	v_mov_b32_e32 v49, v140
	v_mov_b32_e32 v50, v140
	v_mov_b32_e32 v51, v140
	v_mov_b32_e32 v52, v140
	v_mov_b32_e32 v53, v140
	v_mov_b32_e32 v54, v140
	v_mov_b32_e32 v55, v140
	v_mov_b32_e32 v64, v140
	v_mov_b32_e32 v65, v140
	v_mov_b32_e32 v66, v140
	v_mov_b32_e32 v67, v140
	v_mov_b32_e32 v72, v140
	v_mov_b32_e32 v73, v140
	v_mov_b32_e32 v74, v140
	v_mov_b32_e32 v75, v140
	v_mov_b32_e32 v76, v140
	v_mov_b32_e32 v77, v140
	v_mov_b32_e32 v78, v140
	v_mov_b32_e32 v79, v140
	v_mov_b32_e32 v84, v140
	v_mov_b32_e32 v85, v140
	v_mov_b32_e32 v86, v140
	v_mov_b32_e32 v87, v140
	v_mov_b32_e32 v92, v140
	v_mov_b32_e32 v93, v140
	v_mov_b32_e32 v94, v140
	v_mov_b32_e32 v95, v140
	v_mov_b32_e32 v96, v140
	v_mov_b32_e32 v97, v140
	v_mov_b32_e32 v98, v140
	v_mov_b32_e32 v99, v140
	v_mov_b32_e32 v100, v140
	v_mov_b32_e32 v101, v140
	v_mov_b32_e32 v102, v140
	v_mov_b32_e32 v103, v140
	v_mov_b32_e32 v108, v140
	v_mov_b32_e32 v109, v140
	v_mov_b32_e32 v110, v140
	v_mov_b32_e32 v111, v140
	v_mov_b32_e32 v120, v140
	v_mov_b32_e32 v121, v140
	v_mov_b32_e32 v122, v140
	v_mov_b32_e32 v123, v140
	v_mov_b32_e32 v124, v140
	v_mov_b32_e32 v125, v140
	v_mov_b32_e32 v126, v140
	v_mov_b32_e32 v127, v140
	v_mov_b32_e32 v128, v140
	v_mov_b32_e32 v129, v140
	v_mov_b32_e32 v130, v140
	v_mov_b32_e32 v131, v140
	v_mov_b32_e32 v132, v140
	v_mov_b32_e32 v133, v140
	v_mov_b32_e32 v134, v140
	v_mov_b32_e32 v135, v140
	v_mov_b32_e32 v136, v140
	v_mov_b32_e32 v137, v140
	v_mov_b32_e32 v138, v140
	v_mov_b32_e32 v139, v140
	v_mov_b32_e32 v144, v140
	v_mov_b32_e32 v145, v140
	v_mov_b32_e32 v146, v140
	v_mov_b32_e32 v147, v140
	v_mov_b32_e32 v148, v140
	v_mov_b32_e32 v149, v140
	v_mov_b32_e32 v150, v140
	v_mov_b32_e32 v151, v140
	v_mov_b32_e32 v152, v140
	v_mov_b32_e32 v153, v140
	v_mov_b32_e32 v154, v140
	v_mov_b32_e32 v155, v140
	v_mov_b32_e32 v156, v140
	v_mov_b32_e32 v157, v140
	v_mov_b32_e32 v158, v140
	v_mov_b32_e32 v159, v140
	v_mov_b32_e32 v160, v140
	v_mov_b32_e32 v161, v140
	v_mov_b32_e32 v162, v140
	v_mov_b32_e32 v163, v140
	v_mov_b32_e32 v164, v140
	v_mov_b32_e32 v165, v140
	v_mov_b32_e32 v166, v140
	v_mov_b32_e32 v167, v140
	v_mov_b32_e32 v168, v140
	v_mov_b32_e32 v169, v140
	v_mov_b32_e32 v170, v140
	v_mov_b32_e32 v171, v140
	v_mov_b32_e32 v172, v140
	v_mov_b32_e32 v173, v140
	v_mov_b32_e32 v174, v140
	v_mov_b32_e32 v175, v140
	v_readlane_b32 s98, v253, 3
	v_readlane_b32 s99, v253, 4
	v_and_b32_e32 v224, 15, v188
	v_bfe_u32 v225, v188, 4, 2
	v_lshrrev_b32_e32 v226, 2, v224
	v_sub_u32_e32 v226, 0, v226
	v_and_b32_e32 v226, 3, v226
	v_xor_b32_e32 v225, v225, v226
	v_lshlrev_b32_e32 v225, 4, v225
	v_lshl_or_b32 v225, v224, 6, v225
	v_bfe_u32 v226, v188, 7, 1
	v_lshl_or_b32 v185, v226, 13, v225
	v_bfe_u32 v226, v188, 6, 1
	v_lshl_or_b32 v184, v226, 12, v225
	v_add_u32_e32 v184, 0x4000, v184
	v_lshrrev_b32_e32 v224, 3, v188
	v_bfe_u32 v225, v188, 2, 1
	v_lshrrev_b32_e32 v226, 2, v224
	v_sub_u32_e32 v226, 0, v226
	v_and_b32_e32 v226, 3, v226
	v_and_b32_e32 v227, 3, v188
	v_xor_b32_e32 v226, v227, v226
	v_lshlrev_b32_e32 v226, 4, v226
	v_xor_b32_e32 v224, v224, v225
	v_lshl_or_b32 v226, v224, 6, v226
	v_mul_u32_u24_e32 v225, 0x6000, v225
	v_add_u32_e32 v183, v225, v226
	s_mov_b32 m0, 0
	s_sub_u32 vcc_lo, s8, s98
	v_add_u32_e32 v186, vcc_lo, v178
	v_add_u32_e32 v187, vcc_lo, v180
	s_barrier
	s_waitcnt vmcnt(0)
	ds_write_b128 v183, v[116:119]
	ds_write_b128 v183, v[112:115] offset:2048
	ds_write_b128 v183, v[104:107] offset:4096
	ds_write_b128 v183, v[88:91] offset:6144
	ds_write_b128 v183, v[80:83] offset:8192
	ds_write_b128 v183, v[68:71] offset:10240
	ds_write_b128 v183, v[60:63] offset:12288
	ds_write_b128 v183, v[40:43] offset:14336
	ds_write_b128 v183, v[56:59] offset:16384
	ds_write_b128 v183, v[32:35] offset:18432
	ds_write_b128 v183, v[16:19] offset:20480
	ds_write_b128 v183, v[8:11] offset:22528
	v_cmp_gt_u32_e32 vcc, 0x6000, v183
	v_add_u32_e32 v182, 0xc000, v183
	v_add_u32_e32 v183, 0xffffa000, v183
	s_nop 0
	v_cndmask_b32_e32 v183, v183, v182, vcc
	v_add_u32_e32 v116, s26, v187
	global_load_dwordx4 v[116:119], v116, s[98:99] offset:128
	v_add_u32_e32 v112, s27, v187
	global_load_dwordx4 v[112:115], v112, s[98:99] offset:128
	v_add_u32_e32 v104, s20, v187
	global_load_dwordx4 v[104:107], v104, s[98:99] offset:128
	v_add_u32_e32 v88, s21, v187
	global_load_dwordx4 v[88:91], v88, s[98:99] offset:128
	v_add_u32_e32 v80, s56, v187
	global_load_dwordx4 v[80:83], v80, s[98:99] offset:128
	v_add_u32_e32 v68, s57, v187
	global_load_dwordx4 v[68:71], v68, s[98:99] offset:128
	v_add_u32_e32 v60, s24, v187
	global_load_dwordx4 v[60:63], v60, s[98:99] offset:128
	v_add_u32_e32 v40, s96, v187
	global_load_dwordx4 v[40:43], v40, s[98:99] offset:128
	v_mov_b32_e32 v56, v186
	global_load_dwordx4 v[56:59], v56, s[98:99] offset:128
	v_add_u32_e32 v32, s31, v186
	global_load_dwordx4 v[32:35], v32, s[98:99] offset:128
	v_add_u32_e32 v16, s14, v186
	global_load_dwordx4 v[16:19], v16, s[98:99] offset:128
	v_add_u32_e32 v8, s13, v186
	global_load_dwordx4 v[8:11], v8, s[98:99] offset:128
	s_add_u32 s8, s8, 0x80
	s_addc_u32 s9, s9, 0
.LBB0_147:
	s_waitcnt lgkmcnt(0)
	s_barrier
	ds_read_b128 v[224:227], v184
	ds_read_b128 v[228:231], v184 offset:1024
	ds_read_b128 v[232:235], v184 offset:2048
	ds_read_b128 v[236:239], v184 offset:3072
	ds_read_b128 v[190:193], v185
	ds_read_b128 v[194:197], v185 offset:1024
	ds_read_b128 v[198:201], v185 offset:2048
	ds_read_b128 v[204:207], v185 offset:3072
	ds_read_b128 v[208:211], v185 offset:4096
	ds_read_b128 v[212:215], v185 offset:5120
	ds_read_b128 v[216:219], v185 offset:6144
	ds_read_b128 v[220:223], v185 offset:7168
	s_movk_i32 vcc_lo, 0x6000
	s_cmp_eq_u32 m0, 2
	s_cselect_b32 vcc_lo, 0xffff4000, vcc_lo
	s_add_u32 m0, m0, 1
	s_cmp_eq_u32 m0, 3
	s_cselect_b32 m0, 0, m0
	v_add_u32_e32 v185, vcc_lo, v185
	v_add_u32_e32 v184, vcc_lo, v184
	v_xor_b32_e32 v185, 64, v185
	v_xor_b32_e32 v184, 64, v184
	s_waitcnt lgkmcnt(7)
	v_mfma_f32_16x16x32_bf16 v[172:175], v[224:227], v[190:193], v[172:175]
	v_mfma_f32_16x16x32_bf16 v[168:171], v[228:231], v[190:193], v[168:171]
	v_mfma_f32_16x16x32_bf16 v[164:167], v[232:235], v[190:193], v[164:167]
	v_mfma_f32_16x16x32_bf16 v[160:163], v[236:239], v[190:193], v[160:163]
	ds_read_b128 v[190:193], v185
	s_waitcnt lgkmcnt(7)
	v_mfma_f32_16x16x32_bf16 v[156:159], v[224:227], v[194:197], v[156:159]
	v_mfma_f32_16x16x32_bf16 v[152:155], v[228:231], v[194:197], v[152:155]
	v_mfma_f32_16x16x32_bf16 v[148:151], v[232:235], v[194:197], v[148:151]
	v_mfma_f32_16x16x32_bf16 v[144:147], v[236:239], v[194:197], v[144:147]
	ds_read_b128 v[194:197], v185 offset:1024
	s_waitcnt lgkmcnt(7)
	v_mfma_f32_16x16x32_bf16 v[136:139], v[224:227], v[198:201], v[136:139]
	v_mfma_f32_16x16x32_bf16 v[132:135], v[228:231], v[198:201], v[132:135]
	v_mfma_f32_16x16x32_bf16 v[128:131], v[232:235], v[198:201], v[128:131]
	v_mfma_f32_16x16x32_bf16 v[124:127], v[236:239], v[198:201], v[124:127]
	ds_read_b128 v[198:201], v185 offset:2048
	s_waitcnt lgkmcnt(7)
	v_mfma_f32_16x16x32_bf16 v[120:123], v[224:227], v[204:207], v[120:123]
	v_mfma_f32_16x16x32_bf16 v[108:111], v[228:231], v[204:207], v[108:111]
	v_mfma_f32_16x16x32_bf16 v[100:103], v[232:235], v[204:207], v[100:103]
	v_mfma_f32_16x16x32_bf16 v[96:99], v[236:239], v[204:207], v[96:99]
	ds_read_b128 v[204:207], v185 offset:3072
	s_waitcnt lgkmcnt(7)
	v_mfma_f32_16x16x32_bf16 v[92:95], v[224:227], v[208:211], v[92:95]
	v_mfma_f32_16x16x32_bf16 v[84:87], v[228:231], v[208:211], v[84:87]
	v_mfma_f32_16x16x32_bf16 v[76:79], v[232:235], v[208:211], v[76:79]
	v_mfma_f32_16x16x32_bf16 v[72:75], v[236:239], v[208:211], v[72:75]
	ds_read_b128 v[208:211], v185 offset:4096
	s_waitcnt lgkmcnt(7)
	v_mfma_f32_16x16x32_bf16 v[64:67], v[224:227], v[212:215], v[64:67]
	v_mfma_f32_16x16x32_bf16 v[52:55], v[228:231], v[212:215], v[52:55]
	v_mfma_f32_16x16x32_bf16 v[48:51], v[232:235], v[212:215], v[48:51]
	v_mfma_f32_16x16x32_bf16 v[44:47], v[236:239], v[212:215], v[44:47]
	ds_read_b128 v[212:215], v185 offset:5120
	s_waitcnt lgkmcnt(7)
	v_mfma_f32_16x16x32_bf16 v[36:39], v[224:227], v[216:219], v[36:39]
	v_mfma_f32_16x16x32_bf16 v[28:31], v[228:231], v[216:219], v[28:31]
	v_mfma_f32_16x16x32_bf16 v[24:27], v[232:235], v[216:219], v[24:27]
	v_mfma_f32_16x16x32_bf16 v[20:23], v[236:239], v[216:219], v[20:23]
	ds_read_b128 v[216:219], v185 offset:6144
	s_waitcnt lgkmcnt(7)
	v_mfma_f32_16x16x32_bf16 v[12:15], v[224:227], v[220:223], v[12:15]
	v_mfma_f32_16x16x32_bf16 v[4:7], v[228:231], v[220:223], v[4:7]
	v_mfma_f32_16x16x32_bf16 v[0:3], v[232:235], v[220:223], v[0:3]
	v_mfma_f32_16x16x32_bf16 v[140:143], v[236:239], v[220:223], v[140:143]
	ds_read_b128 v[220:223], v185 offset:7168
	ds_read_b128 v[224:227], v184
	ds_read_b128 v[228:231], v184 offset:1024
	ds_read_b128 v[232:235], v184 offset:2048
	ds_read_b128 v[236:239], v184 offset:3072
	s_movk_i32 vcc_lo, 0x6000
	s_cmp_eq_u32 m0, 2
	s_cselect_b32 vcc_lo, 0xffff4000, vcc_lo
	s_add_u32 m0, m0, 1
	s_cmp_eq_u32 m0, 3
	s_cselect_b32 m0, 0, m0
	v_add_u32_e32 v185, vcc_lo, v185
	v_add_u32_e32 v184, vcc_lo, v184
	v_xor_b32_e32 v185, 64, v185
	v_xor_b32_e32 v184, 64, v184
	s_sub_u32 vcc_lo, s8, s98
	v_add_u32_e32 v186, vcc_lo, v178
	v_add_u32_e32 v187, vcc_lo, v180
	s_barrier
	s_waitcnt lgkmcnt(0)
	v_mfma_f32_16x16x32_bf16 v[172:175], v[224:227], v[190:193], v[172:175]
	v_mfma_f32_16x16x32_bf16 v[168:171], v[228:231], v[190:193], v[168:171]
	v_mfma_f32_16x16x32_bf16 v[164:167], v[232:235], v[190:193], v[164:167]
	v_mfma_f32_16x16x32_bf16 v[160:163], v[236:239], v[190:193], v[160:163]
	s_waitcnt vmcnt(11)
	ds_write_b128 v183, v[116:119]
	v_add_u32_e32 v116, s26, v187
	global_load_dwordx4 v[116:119], v116, s[98:99] offset:128
	s_waitcnt vmcnt(11)
	ds_write_b128 v183, v[112:115] offset:2048
	v_add_u32_e32 v112, s27, v187
	global_load_dwordx4 v[112:115], v112, s[98:99] offset:128
	v_mfma_f32_16x16x32_bf16 v[156:159], v[224:227], v[194:197], v[156:159]
	v_mfma_f32_16x16x32_bf16 v[152:155], v[228:231], v[194:197], v[152:155]
	v_mfma_f32_16x16x32_bf16 v[148:151], v[232:235], v[194:197], v[148:151]
	v_mfma_f32_16x16x32_bf16 v[144:147], v[236:239], v[194:197], v[144:147]
	s_waitcnt vmcnt(11)
	ds_write_b128 v183, v[104:107] offset:4096
	v_add_u32_e32 v104, s20, v187
	global_load_dwordx4 v[104:107], v104, s[98:99] offset:128
	v_mfma_f32_16x16x32_bf16 v[136:139], v[224:227], v[198:201], v[136:139]
	v_mfma_f32_16x16x32_bf16 v[132:135], v[228:231], v[198:201], v[132:135]
	v_mfma_f32_16x16x32_bf16 v[128:131], v[232:235], v[198:201], v[128:131]
	v_mfma_f32_16x16x32_bf16 v[124:127], v[236:239], v[198:201], v[124:127]
	s_waitcnt vmcnt(11)
	ds_write_b128 v183, v[88:91] offset:6144
	v_add_u32_e32 v88, s21, v187
	global_load_dwordx4 v[88:91], v88, s[98:99] offset:128
	s_waitcnt vmcnt(11)
	ds_write_b128 v183, v[80:83] offset:8192
	v_add_u32_e32 v80, s56, v187
	global_load_dwordx4 v[80:83], v80, s[98:99] offset:128
	v_mfma_f32_16x16x32_bf16 v[120:123], v[224:227], v[204:207], v[120:123]
	v_mfma_f32_16x16x32_bf16 v[108:111], v[228:231], v[204:207], v[108:111]
	v_mfma_f32_16x16x32_bf16 v[100:103], v[232:235], v[204:207], v[100:103]
	v_mfma_f32_16x16x32_bf16 v[96:99], v[236:239], v[204:207], v[96:99]
	s_waitcnt vmcnt(11)
	ds_write_b128 v183, v[68:71] offset:10240
	v_add_u32_e32 v68, s57, v187
	global_load_dwordx4 v[68:71], v68, s[98:99] offset:128
	v_mfma_f32_16x16x32_bf16 v[92:95], v[224:227], v[208:211], v[92:95]
	v_mfma_f32_16x16x32_bf16 v[84:87], v[228:231], v[208:211], v[84:87]
	v_mfma_f32_16x16x32_bf16 v[76:79], v[232:235], v[208:211], v[76:79]
	v_mfma_f32_16x16x32_bf16 v[72:75], v[236:239], v[208:211], v[72:75]
	s_waitcnt vmcnt(11)
	ds_write_b128 v183, v[60:63] offset:12288
	v_add_u32_e32 v60, s24, v187
	global_load_dwordx4 v[60:63], v60, s[98:99] offset:128
	s_waitcnt vmcnt(11)
	ds_write_b128 v183, v[40:43] offset:14336
	v_add_u32_e32 v40, s96, v187
	global_load_dwordx4 v[40:43], v40, s[98:99] offset:128
	v_mfma_f32_16x16x32_bf16 v[64:67], v[224:227], v[212:215], v[64:67]
	v_mfma_f32_16x16x32_bf16 v[52:55], v[228:231], v[212:215], v[52:55]
	v_mfma_f32_16x16x32_bf16 v[48:51], v[232:235], v[212:215], v[48:51]
	v_mfma_f32_16x16x32_bf16 v[44:47], v[236:239], v[212:215], v[44:47]
	s_waitcnt vmcnt(11)
	ds_write_b128 v183, v[56:59] offset:16384
	v_mov_b32_e32 v56, v186
	global_load_dwordx4 v[56:59], v56, s[98:99] offset:128
	v_mfma_f32_16x16x32_bf16 v[36:39], v[224:227], v[216:219], v[36:39]
	v_mfma_f32_16x16x32_bf16 v[28:31], v[228:231], v[216:219], v[28:31]
	v_mfma_f32_16x16x32_bf16 v[24:27], v[232:235], v[216:219], v[24:27]
	v_mfma_f32_16x16x32_bf16 v[20:23], v[236:239], v[216:219], v[20:23]
	s_waitcnt vmcnt(11)
	ds_write_b128 v183, v[32:35] offset:18432
	v_add_u32_e32 v32, s31, v186
	global_load_dwordx4 v[32:35], v32, s[98:99] offset:128
	s_waitcnt vmcnt(11)
	ds_write_b128 v183, v[16:19] offset:20480
	v_add_u32_e32 v16, s14, v186
	global_load_dwordx4 v[16:19], v16, s[98:99] offset:128
	v_mfma_f32_16x16x32_bf16 v[12:15], v[224:227], v[220:223], v[12:15]
	v_mfma_f32_16x16x32_bf16 v[4:7], v[228:231], v[220:223], v[4:7]
	v_mfma_f32_16x16x32_bf16 v[0:3], v[232:235], v[220:223], v[0:3]
	v_mfma_f32_16x16x32_bf16 v[140:143], v[236:239], v[220:223], v[140:143]
	s_waitcnt vmcnt(11)
	ds_write_b128 v183, v[8:11] offset:22528
	v_add_u32_e32 v8, s13, v186
	global_load_dwordx4 v[8:11], v8, s[98:99] offset:128
	v_cmp_gt_u32_e32 vcc, 0x6000, v183
	v_add_u32_e32 v182, 0xc000, v183
	v_add_u32_e32 v183, 0xffffa000, v183
	s_nop 0
	v_cndmask_b32_e32 v183, v183, v182, vcc
	s_add_u32 s8, s8, 0x80
	s_addc_u32 s9, s9, 0
	s_cmpk_lg_i32 s8, 0x780
	s_cbranch_scc1 .LBB0_147
	s_waitcnt lgkmcnt(0)
	s_barrier
	ds_read_b128 v[224:227], v184
	ds_read_b128 v[228:231], v184 offset:1024
	ds_read_b128 v[232:235], v184 offset:2048
	ds_read_b128 v[236:239], v184 offset:3072
	ds_read_b128 v[190:193], v185
	ds_read_b128 v[194:197], v185 offset:1024
	ds_read_b128 v[198:201], v185 offset:2048
	ds_read_b128 v[204:207], v185 offset:3072
	ds_read_b128 v[208:211], v185 offset:4096
	ds_read_b128 v[212:215], v185 offset:5120
	ds_read_b128 v[216:219], v185 offset:6144
	ds_read_b128 v[220:223], v185 offset:7168
	s_movk_i32 vcc_lo, 0x6000
	s_cmp_eq_u32 m0, 2
	s_cselect_b32 vcc_lo, 0xffff4000, vcc_lo
	s_add_u32 m0, m0, 1
	s_cmp_eq_u32 m0, 3
	s_cselect_b32 m0, 0, m0
	v_add_u32_e32 v185, vcc_lo, v185
	v_add_u32_e32 v184, vcc_lo, v184
	v_xor_b32_e32 v185, 64, v185
	v_xor_b32_e32 v184, 64, v184
	s_waitcnt lgkmcnt(7)
	v_mfma_f32_16x16x32_bf16 v[172:175], v[224:227], v[190:193], v[172:175]
	v_mfma_f32_16x16x32_bf16 v[168:171], v[228:231], v[190:193], v[168:171]
	v_mfma_f32_16x16x32_bf16 v[164:167], v[232:235], v[190:193], v[164:167]
	v_mfma_f32_16x16x32_bf16 v[160:163], v[236:239], v[190:193], v[160:163]
	ds_read_b128 v[190:193], v185
	s_waitcnt lgkmcnt(7)
	v_mfma_f32_16x16x32_bf16 v[156:159], v[224:227], v[194:197], v[156:159]
	v_mfma_f32_16x16x32_bf16 v[152:155], v[228:231], v[194:197], v[152:155]
	v_mfma_f32_16x16x32_bf16 v[148:151], v[232:235], v[194:197], v[148:151]
	v_mfma_f32_16x16x32_bf16 v[144:147], v[236:239], v[194:197], v[144:147]
	ds_read_b128 v[194:197], v185 offset:1024
	s_waitcnt lgkmcnt(7)
	v_mfma_f32_16x16x32_bf16 v[136:139], v[224:227], v[198:201], v[136:139]
	v_mfma_f32_16x16x32_bf16 v[132:135], v[228:231], v[198:201], v[132:135]
	v_mfma_f32_16x16x32_bf16 v[128:131], v[232:235], v[198:201], v[128:131]
	v_mfma_f32_16x16x32_bf16 v[124:127], v[236:239], v[198:201], v[124:127]
	ds_read_b128 v[198:201], v185 offset:2048
	s_waitcnt lgkmcnt(7)
	v_mfma_f32_16x16x32_bf16 v[120:123], v[224:227], v[204:207], v[120:123]
	v_mfma_f32_16x16x32_bf16 v[108:111], v[228:231], v[204:207], v[108:111]
	v_mfma_f32_16x16x32_bf16 v[100:103], v[232:235], v[204:207], v[100:103]
	v_mfma_f32_16x16x32_bf16 v[96:99], v[236:239], v[204:207], v[96:99]
	ds_read_b128 v[204:207], v185 offset:3072
	s_waitcnt lgkmcnt(7)
	v_mfma_f32_16x16x32_bf16 v[92:95], v[224:227], v[208:211], v[92:95]
	v_mfma_f32_16x16x32_bf16 v[84:87], v[228:231], v[208:211], v[84:87]
	v_mfma_f32_16x16x32_bf16 v[76:79], v[232:235], v[208:211], v[76:79]
	v_mfma_f32_16x16x32_bf16 v[72:75], v[236:239], v[208:211], v[72:75]
	ds_read_b128 v[208:211], v185 offset:4096
	s_waitcnt lgkmcnt(7)
	v_mfma_f32_16x16x32_bf16 v[64:67], v[224:227], v[212:215], v[64:67]
	v_mfma_f32_16x16x32_bf16 v[52:55], v[228:231], v[212:215], v[52:55]
	v_mfma_f32_16x16x32_bf16 v[48:51], v[232:235], v[212:215], v[48:51]
	v_mfma_f32_16x16x32_bf16 v[44:47], v[236:239], v[212:215], v[44:47]
	ds_read_b128 v[212:215], v185 offset:5120
	s_waitcnt lgkmcnt(7)
	v_mfma_f32_16x16x32_bf16 v[36:39], v[224:227], v[216:219], v[36:39]
	v_mfma_f32_16x16x32_bf16 v[28:31], v[228:231], v[216:219], v[28:31]
	v_mfma_f32_16x16x32_bf16 v[24:27], v[232:235], v[216:219], v[24:27]
	v_mfma_f32_16x16x32_bf16 v[20:23], v[236:239], v[216:219], v[20:23]
	ds_read_b128 v[216:219], v185 offset:6144
	s_waitcnt lgkmcnt(7)
	v_mfma_f32_16x16x32_bf16 v[12:15], v[224:227], v[220:223], v[12:15]
	v_mfma_f32_16x16x32_bf16 v[4:7], v[228:231], v[220:223], v[4:7]
	v_mfma_f32_16x16x32_bf16 v[0:3], v[232:235], v[220:223], v[0:3]
	v_mfma_f32_16x16x32_bf16 v[140:143], v[236:239], v[220:223], v[140:143]
	ds_read_b128 v[220:223], v185 offset:7168
	ds_read_b128 v[224:227], v184
	ds_read_b128 v[228:231], v184 offset:1024
	ds_read_b128 v[232:235], v184 offset:2048
	ds_read_b128 v[236:239], v184 offset:3072
	s_movk_i32 vcc_lo, 0x6000
	s_cmp_eq_u32 m0, 2
	s_cselect_b32 vcc_lo, 0xffff4000, vcc_lo
	s_add_u32 m0, m0, 1
	s_cmp_eq_u32 m0, 3
	s_cselect_b32 m0, 0, m0
	v_add_u32_e32 v185, vcc_lo, v185
	v_add_u32_e32 v184, vcc_lo, v184
	v_xor_b32_e32 v185, 64, v185
	v_xor_b32_e32 v184, 64, v184
	s_waitcnt lgkmcnt(0)
	v_mfma_f32_16x16x32_bf16 v[172:175], v[224:227], v[190:193], v[172:175]
	v_mfma_f32_16x16x32_bf16 v[168:171], v[228:231], v[190:193], v[168:171]
	v_mfma_f32_16x16x32_bf16 v[164:167], v[232:235], v[190:193], v[164:167]
	v_mfma_f32_16x16x32_bf16 v[160:163], v[236:239], v[190:193], v[160:163]
	v_mfma_f32_16x16x32_bf16 v[156:159], v[224:227], v[194:197], v[156:159]
	v_mfma_f32_16x16x32_bf16 v[152:155], v[228:231], v[194:197], v[152:155]
	v_mfma_f32_16x16x32_bf16 v[148:151], v[232:235], v[194:197], v[148:151]
	v_mfma_f32_16x16x32_bf16 v[144:147], v[236:239], v[194:197], v[144:147]
	v_mfma_f32_16x16x32_bf16 v[136:139], v[224:227], v[198:201], v[136:139]
	v_mfma_f32_16x16x32_bf16 v[132:135], v[228:231], v[198:201], v[132:135]
	v_mfma_f32_16x16x32_bf16 v[128:131], v[232:235], v[198:201], v[128:131]
	v_mfma_f32_16x16x32_bf16 v[124:127], v[236:239], v[198:201], v[124:127]
	v_mfma_f32_16x16x32_bf16 v[120:123], v[224:227], v[204:207], v[120:123]
	v_mfma_f32_16x16x32_bf16 v[108:111], v[228:231], v[204:207], v[108:111]
	v_mfma_f32_16x16x32_bf16 v[100:103], v[232:235], v[204:207], v[100:103]
	v_mfma_f32_16x16x32_bf16 v[96:99], v[236:239], v[204:207], v[96:99]
	v_mfma_f32_16x16x32_bf16 v[92:95], v[224:227], v[208:211], v[92:95]
	v_mfma_f32_16x16x32_bf16 v[84:87], v[228:231], v[208:211], v[84:87]
	v_mfma_f32_16x16x32_bf16 v[76:79], v[232:235], v[208:211], v[76:79]
	v_mfma_f32_16x16x32_bf16 v[72:75], v[236:239], v[208:211], v[72:75]
	v_mfma_f32_16x16x32_bf16 v[64:67], v[224:227], v[212:215], v[64:67]
	v_mfma_f32_16x16x32_bf16 v[52:55], v[228:231], v[212:215], v[52:55]
	v_mfma_f32_16x16x32_bf16 v[48:51], v[232:235], v[212:215], v[48:51]
	v_mfma_f32_16x16x32_bf16 v[44:47], v[236:239], v[212:215], v[44:47]
	v_mfma_f32_16x16x32_bf16 v[36:39], v[224:227], v[216:219], v[36:39]
	v_mfma_f32_16x16x32_bf16 v[28:31], v[228:231], v[216:219], v[28:31]
	v_mfma_f32_16x16x32_bf16 v[24:27], v[232:235], v[216:219], v[24:27]
	v_mfma_f32_16x16x32_bf16 v[20:23], v[236:239], v[216:219], v[20:23]
	v_mfma_f32_16x16x32_bf16 v[12:15], v[224:227], v[220:223], v[12:15]
	v_mfma_f32_16x16x32_bf16 v[4:7], v[228:231], v[220:223], v[4:7]
	v_mfma_f32_16x16x32_bf16 v[0:3], v[232:235], v[220:223], v[0:3]
	v_mfma_f32_16x16x32_bf16 v[140:143], v[236:239], v[220:223], v[140:143]
	v_lshrrev_b32_e32 v224, 4, v188
	v_and_b32_e32 v225, 7, v188
	v_bitop3_b32 v226, v224, v225, 3 bitop3:0x6c
	v_lshlrev_b32_e32 v227, 7, v188
	v_bfe_u32 v228, v188, 4, 2
	v_and_b32_e32 v229, 0xffffc780, v227
	v_and_b32_e32 v227, 0x2780, v227
	v_bitop3_b32 v228, v228, v225, 4 bitop3:0x36
	v_lshlrev_b32_e32 v226, 4, v226
	v_lshlrev_b32_e32 v228, 4, v228
	v_or_b32_e32 v185, v229, v226
	v_or_b32_e32 v184, v227, v226
	v_or_b32_e32 v183, v229, v228
	v_or_b32_e32 v182, v227, v228
	s_waitcnt vmcnt(0)
	s_barrier
	s_waitcnt vmcnt(10)
	ds_write_b128 v176, v[116:119]
	s_waitcnt vmcnt(9)
	ds_write_b128 v176, v[112:115] offset:4096
	s_waitcnt vmcnt(8)
	ds_write_b128 v176, v[104:107] offset:8192
	s_waitcnt vmcnt(7)
	ds_write_b128 v176, v[88:91] offset:12288
	s_waitcnt vmcnt(6)
	ds_write_b128 v176, v[80:83] offset:16384
	s_waitcnt vmcnt(5)
	ds_write_b128 v176, v[68:71] offset:20480
	s_waitcnt vmcnt(4)
	ds_write_b128 v176, v[60:63] offset:24576
	s_waitcnt vmcnt(3)
	ds_write_b128 v176, v[40:43] offset:28672
	ds_write_b128 v176, v[56:59] offset:32768
	s_waitcnt vmcnt(2)
	ds_write_b128 v176, v[32:35] offset:36864
	s_waitcnt vmcnt(1)
	ds_write_b128 v176, v[16:19] offset:40960
	s_waitcnt vmcnt(0)
	ds_write_b128 v176, v[8:11] offset:45056
	s_waitcnt lgkmcnt(0)
	s_barrier
	ds_read_b128 v[8:11], v185
	ds_read_b128 v[16:19], v185 offset:2048
	ds_read_b128 v[32:35], v185 offset:4096
	ds_read_b128 v[40:43], v185 offset:6144
	ds_read_b128 v[56:59], v185 offset:8192
	ds_read_b128 v[60:63], v185 offset:10240
	ds_read_b128 v[68:71], v185 offset:12288
	ds_read_b128 v[80:83], v185 offset:14336
	ds_read_b128 v[88:91], v184 offset:32768
	ds_read_b128 v[104:107], v184 offset:34816
	ds_read_b128 v[112:115], v184 offset:36864
	ds_read_b128 v[116:119], v184 offset:38912
	s_waitcnt lgkmcnt(3)
	v_mfma_f32_16x16x32_bf16 v[172:175], v[88:91], v[8:11], v[172:175]
	s_waitcnt lgkmcnt(2)
	v_mfma_f32_16x16x32_bf16 v[168:171], v[104:107], v[8:11], v[168:171]
	s_waitcnt lgkmcnt(1)
	v_mfma_f32_16x16x32_bf16 v[164:167], v[112:115], v[8:11], v[164:167]
	s_waitcnt lgkmcnt(0)
	v_mfma_f32_16x16x32_bf16 v[8:11], v[116:119], v[8:11], v[160:163]
	v_mfma_f32_16x16x32_bf16 v[156:159], v[88:91], v[16:19], v[156:159]
	v_mfma_f32_16x16x32_bf16 v[152:155], v[104:107], v[16:19], v[152:155]
	v_mfma_f32_16x16x32_bf16 v[148:151], v[112:115], v[16:19], v[148:151]
	v_mfma_f32_16x16x32_bf16 v[16:19], v[116:119], v[16:19], v[144:147]
	v_mfma_f32_16x16x32_bf16 v[136:139], v[88:91], v[32:35], v[136:139]
	v_mfma_f32_16x16x32_bf16 v[132:135], v[104:107], v[32:35], v[132:135]
	v_mfma_f32_16x16x32_bf16 v[128:131], v[112:115], v[32:35], v[128:131]
	v_mfma_f32_16x16x32_bf16 v[32:35], v[116:119], v[32:35], v[124:127]
	v_mfma_f32_16x16x32_bf16 v[120:123], v[88:91], v[40:43], v[120:123]
	v_mfma_f32_16x16x32_bf16 v[108:111], v[104:107], v[40:43], v[108:111]
	v_mfma_f32_16x16x32_bf16 v[100:103], v[112:115], v[40:43], v[100:103]
	v_mfma_f32_16x16x32_bf16 v[40:43], v[116:119], v[40:43], v[96:99]
	v_mfma_f32_16x16x32_bf16 v[92:95], v[88:91], v[56:59], v[92:95]
	v_mfma_f32_16x16x32_bf16 v[84:87], v[104:107], v[56:59], v[84:87]
	v_mfma_f32_16x16x32_bf16 v[76:79], v[112:115], v[56:59], v[76:79]
	v_mfma_f32_16x16x32_bf16 v[56:59], v[116:119], v[56:59], v[72:75]
	v_mfma_f32_16x16x32_bf16 v[64:67], v[88:91], v[60:63], v[64:67]
	v_mfma_f32_16x16x32_bf16 v[52:55], v[104:107], v[60:63], v[52:55]
	v_mfma_f32_16x16x32_bf16 v[72:75], v[112:115], v[60:63], v[48:51]
	v_mfma_f32_16x16x32_bf16 v[60:63], v[116:119], v[60:63], v[44:47]
	v_mfma_f32_16x16x32_bf16 v[96:99], v[88:91], v[68:71], v[36:39]
	v_mfma_f32_16x16x32_bf16 v[28:31], v[104:107], v[68:71], v[28:31]
	v_mfma_f32_16x16x32_bf16 v[124:127], v[112:115], v[68:71], v[24:27]
	v_mfma_f32_16x16x32_bf16 v[20:23], v[116:119], v[68:71], v[20:23]
	v_mfma_f32_16x16x32_bf16 v[12:15], v[88:91], v[80:83], v[12:15]
	v_mfma_f32_16x16x32_bf16 v[4:7], v[104:107], v[80:83], v[4:7]
	v_mfma_f32_16x16x32_bf16 v[0:3], v[112:115], v[80:83], v[0:3]
	v_mfma_f32_16x16x32_bf16 v[68:71], v[116:119], v[80:83], v[140:143]
	ds_read_b128 v[24:27], v183
	ds_read_b128 v[36:39], v183 offset:2048
	ds_read_b128 v[44:47], v183 offset:4096
	ds_read_b128 v[80:83], v183 offset:6144
	ds_read_b128 v[88:91], v183 offset:8192
	ds_read_b128 v[104:107], v183 offset:10240
	ds_read_b128 v[112:115], v183 offset:12288
	ds_read_b128 v[116:119], v183 offset:14336
	ds_read_b128 v[140:143], v182 offset:32768
	ds_read_b128 v[144:147], v182 offset:34816
	ds_read_b128 v[160:163], v182 offset:36864
	ds_read_b128 v[178:181], v182 offset:38912
	s_waitcnt lgkmcnt(3)
	v_mfma_f32_16x16x32_bf16 v[172:175], v[140:143], v[24:27], v[172:175]
	v_mov_b32_e32 v49, v188
	v_cmp_lt_i32_e32 vcc, v189, v202
	s_waitcnt lgkmcnt(2)
	v_mfma_f32_16x16x32_bf16 v[168:171], v[144:147], v[24:27], v[168:171]
	v_mov_b32_e32 v48, v188
	v_readlane_b32 s8, v253, 24
	s_waitcnt lgkmcnt(1)
	v_mfma_f32_16x16x32_bf16 v[164:167], v[160:163], v[24:27], v[164:167]
	v_and_b32_e32 v50, 0xffffff80, v48
	v_add_u32_e32 v51, s11, v50
	v_and_or_b32 v50, v48, 64, s12
	s_waitcnt lgkmcnt(0)
	v_mfma_f32_16x16x32_bf16 v[8:11], v[178:181], v[24:27], v[8:11]
	v_bfe_u32 v26, v49, 4, 1
	v_cndmask_b32_e32 v24, v203, v189, vcc
	v_cmp_eq_u32_e32 vcc, 0, v26
	v_lshlrev_b32_e32 v186, 2, v24
	v_mfma_f32_16x16x32_bf16 v[182:185], v[178:181], v[36:39], v[16:19]
	v_and_or_b32 v48, v49, 15, v51
	v_ashrrev_i32_e32 v51, 31, v50
	v_lshl_add_u64 v[50:51], v[50:51], 1, s[6:7]
	v_cndmask_b32_e32 v16, v172, v168, vcc
	v_cndmask_b32_e32 v17, v173, v169, vcc
	v_cndmask_b32_e32 v18, v174, v170, vcc
	v_cndmask_b32_e32 v19, v175, v171, vcc
	ds_bpermute_b32 v16, v186, v16
	ds_bpermute_b32 v17, v186, v17
	ds_bpermute_b32 v18, v186, v18
	ds_bpermute_b32 v19, v186, v19
	v_lshlrev_b32_e32 v176, 5, v26
	v_lshrrev_b32_e32 v27, 1, v49
	v_lshl_add_u64 v[24:25], v[50:51], 0, v[176:177]
	v_and_b32_e32 v176, 16, v27
	v_ashrrev_i32_e32 v49, 31, v48
	v_mfma_f32_16x16x32_bf16 v[156:159], v[140:143], v[36:39], v[156:159]
	v_lshl_add_u64 v[50:51], v[24:25], 0, v[176:177]
	v_lshlrev_b64 v[24:25], 11, v[48:49]
	s_waitcnt lgkmcnt(3)
	v_cndmask_b32_e32 v26, v16, v172, vcc
	v_mfma_f32_16x16x32_bf16 v[152:155], v[144:147], v[36:39], v[152:155]
	v_cndmask_b32_e32 v27, v168, v16, vcc
	s_waitcnt lgkmcnt(2)
	v_cndmask_b32_e32 v16, v17, v173, vcc
	v_lshl_add_u64 v[24:25], v[50:51], 0, v[24:25]
	v_mfma_f32_16x16x32_bf16 v[148:151], v[160:163], v[36:39], v[148:151]
	v_cndmask_b32_e32 v36, v169, v17, vcc
	s_waitcnt lgkmcnt(1)
	v_cndmask_b32_e32 v17, v18, v174, vcc
	v_cvt_pk_bf16_f32 v16, v26, v16
	v_mfma_f32_16x16x32_bf16 v[190:193], v[178:181], v[44:47], v[32:35]
	v_readlane_b32 s9, v253, 25
	s_nop 1
	v_cndmask_b32_e32 v32, v170, v18, vcc
	s_waitcnt lgkmcnt(0)
	v_cndmask_b32_e32 v18, v19, v175, vcc
	v_cndmask_b32_e32 v19, v171, v19, vcc
	v_cvt_pk_bf16_f32 v17, v17, v18
	v_cvt_pk_bf16_f32 v18, v27, v36
	v_cvt_pk_bf16_f32 v19, v32, v19
	global_store_dwordx4 v[24:25], v[16:19], off
	v_mfma_f32_16x16x32_bf16 v[120:123], v[140:143], v[80:83], v[120:123]
	s_nop 0
	v_cndmask_b32_e32 v16, v164, v8, vcc
	v_cndmask_b32_e32 v17, v165, v9, vcc
	v_cndmask_b32_e32 v18, v166, v10, vcc
	v_cndmask_b32_e32 v19, v167, v11, vcc
	ds_bpermute_b32 v16, v186, v16
	ds_bpermute_b32 v17, v186, v17
	ds_bpermute_b32 v18, v186, v18
	ds_bpermute_b32 v19, v186, v19
	v_mfma_f32_16x16x32_bf16 v[108:111], v[144:147], v[80:83], v[108:111]
	s_waitcnt lgkmcnt(3)
	v_cndmask_b32_e32 v26, v16, v164, vcc
	v_cndmask_b32_e32 v16, v8, v16, vcc
	s_waitcnt lgkmcnt(2)
	v_cndmask_b32_e32 v8, v17, v165, vcc
	v_cndmask_b32_e32 v17, v9, v17, vcc
	s_waitcnt lgkmcnt(1)
	v_cndmask_b32_e32 v9, v18, v166, vcc
	v_cndmask_b32_e32 v18, v10, v18, vcc
	s_waitcnt lgkmcnt(0)
	v_cndmask_b32_e32 v10, v19, v167, vcc
	v_cndmask_b32_e32 v11, v11, v19, vcc
	v_cvt_pk_bf16_f32 v8, v26, v8
	v_cvt_pk_bf16_f32 v9, v9, v10
	v_cvt_pk_bf16_f32 v10, v16, v17
	v_cvt_pk_bf16_f32 v11, v18, v11
	global_store_dwordx4 v[24:25], v[8:11], off offset:64
	v_mfma_f32_16x16x32_bf16 v[100:103], v[160:163], v[80:83], v[100:103]
	s_nop 0
	v_or_b32_e32 v8, 16, v48
	v_ashrrev_i32_e32 v9, 31, v8
	v_lshlrev_b64 v[8:9], 11, v[8:9]
	v_mfma_f32_16x16x32_bf16 v[80:83], v[178:181], v[80:83], v[40:43]
	v_cndmask_b32_e32 v10, v158, v154, vcc
	v_cndmask_b32_e32 v11, v159, v155, vcc
	ds_bpermute_b32 v10, v186, v10
	v_mfma_f32_16x16x32_bf16 v[40:43], v[140:143], v[104:107], v[64:67]
	ds_bpermute_b32 v11, v186, v11
	s_nop 1
	v_lshl_add_u64 v[64:65], v[50:51], 0, v[8:9]
	v_cndmask_b32_e32 v8, v156, v152, vcc
	v_cndmask_b32_e32 v9, v157, v153, vcc
	ds_bpermute_b32 v8, v186, v8
	ds_bpermute_b32 v9, v186, v9
	v_mfma_f32_16x16x32_bf16 v[136:139], v[140:143], v[44:47], v[136:139]
	s_waitcnt lgkmcnt(1)
	v_cndmask_b32_e32 v49, v8, v156, vcc
	v_mfma_f32_16x16x32_bf16 v[132:135], v[144:147], v[44:47], v[132:135]
	v_mfma_f32_16x16x32_bf16 v[128:131], v[160:163], v[44:47], v[128:131]
	v_mfma_f32_16x16x32_bf16 v[44:47], v[144:147], v[104:107], v[52:55]
	v_mfma_f32_16x16x32_bf16 v[36:39], v[178:181], v[104:107], v[60:63]
	s_nop 1
	v_cndmask_b32_e32 v54, v152, v8, vcc
	s_waitcnt lgkmcnt(0)
	v_cndmask_b32_e32 v8, v9, v157, vcc
	v_cndmask_b32_e32 v55, v153, v9, vcc
	v_cndmask_b32_e32 v53, v10, v158, vcc
	v_cndmask_b32_e32 v60, v154, v10, vcc
	v_cndmask_b32_e32 v61, v11, v159, vcc
	v_cndmask_b32_e32 v62, v155, v11, vcc
	v_cvt_pk_bf16_f32 v52, v49, v8
	v_cvt_pk_bf16_f32 v53, v53, v61
	v_cvt_pk_bf16_f32 v54, v54, v55
	v_cvt_pk_bf16_f32 v55, v60, v62
	v_mfma_f32_16x16x32_bf16 v[8:11], v[140:143], v[116:119], v[12:15]
	global_store_dwordx4 v[64:65], v[52:55], off
	v_cndmask_b32_e32 v49, v149, v183, vcc
	ds_bpermute_b32 v49, v186, v49
	v_mfma_f32_16x16x32_bf16 v[12:15], v[144:147], v[116:119], v[4:7]
	v_cndmask_b32_e32 v52, v150, v184, vcc
	v_cndmask_b32_e32 v53, v151, v185, vcc
	ds_bpermute_b32 v52, v186, v52
	v_cndmask_b32_e32 v4, v148, v182, vcc
	ds_bpermute_b32 v54, v186, v4
	ds_bpermute_b32 v53, v186, v53
	s_waitcnt lgkmcnt(3)
	v_cndmask_b32_e32 v60, v49, v149, vcc
	v_cndmask_b32_e32 v49, v183, v49, vcc
	s_waitcnt lgkmcnt(2)
	v_cndmask_b32_e32 v61, v52, v150, vcc
	s_waitcnt lgkmcnt(1)
	v_cndmask_b32_e32 v55, v54, v148, vcc
	v_cndmask_b32_e32 v54, v182, v54, vcc
	v_cndmask_b32_e32 v62, v184, v52, vcc
	s_waitcnt lgkmcnt(0)
	v_cndmask_b32_e32 v63, v53, v151, vcc
	v_cndmask_b32_e32 v66, v185, v53, vcc
	v_cvt_pk_bf16_f32 v52, v55, v60
	v_cvt_pk_bf16_f32 v53, v61, v63
	v_cvt_pk_bf16_f32 v54, v54, v49
	v_cvt_pk_bf16_f32 v55, v62, v66
	global_store_dwordx4 v[64:65], v[52:55], off offset:64
	v_cndmask_b32_e32 v49, v136, v132, vcc
	ds_bpermute_b32 v49, v186, v49
	v_or_b32_e32 v52, 32, v48
	v_ashrrev_i32_e32 v53, 31, v52
	v_lshlrev_b64 v[52:53], 11, v[52:53]
	v_lshl_add_u64 v[60:61], v[50:51], 0, v[52:53]
	v_cndmask_b32_e32 v52, v137, v133, vcc
	v_cndmask_b32_e32 v53, v138, v134, vcc
	v_cndmask_b32_e32 v54, v139, v135, vcc
	ds_bpermute_b32 v52, v186, v52
	ds_bpermute_b32 v53, v186, v53
	ds_bpermute_b32 v54, v186, v54
	s_waitcnt lgkmcnt(3)
	v_cndmask_b32_e32 v55, v49, v136, vcc
	v_cndmask_b32_e32 v49, v132, v49, vcc
	s_waitcnt lgkmcnt(2)
	v_cndmask_b32_e32 v62, v52, v137, vcc
	v_cndmask_b32_e32 v63, v133, v52, vcc
	s_waitcnt lgkmcnt(1)
	v_cndmask_b32_e32 v64, v53, v138, vcc
	v_cndmask_b32_e32 v65, v134, v53, vcc
	s_waitcnt lgkmcnt(0)
	v_cndmask_b32_e32 v53, v54, v139, vcc
	v_cndmask_b32_e32 v66, v135, v54, vcc
	v_cvt_pk_bf16_f32 v52, v55, v62
	v_cvt_pk_bf16_f32 v53, v64, v53
	v_cvt_pk_bf16_f32 v54, v49, v63
	v_cvt_pk_bf16_f32 v55, v65, v66
	global_store_dwordx4 v[60:61], v[52:55], off
	v_cndmask_b32_e32 v49, v128, v190, vcc
	ds_bpermute_b32 v49, v186, v49
	v_cndmask_b32_e32 v52, v129, v191, vcc
	v_cndmask_b32_e32 v53, v130, v192, vcc
	v_cndmask_b32_e32 v54, v131, v193, vcc
	ds_bpermute_b32 v52, v186, v52
	ds_bpermute_b32 v53, v186, v53
	ds_bpermute_b32 v54, v186, v54
	s_waitcnt lgkmcnt(3)
	v_cndmask_b32_e32 v55, v49, v128, vcc
	v_cndmask_b32_e32 v49, v190, v49, vcc
	s_waitcnt lgkmcnt(2)
	v_cndmask_b32_e32 v62, v52, v129, vcc
	v_cndmask_b32_e32 v63, v191, v52, vcc
	s_waitcnt lgkmcnt(1)
	v_cndmask_b32_e32 v64, v53, v130, vcc
	v_cndmask_b32_e32 v65, v192, v53, vcc
	s_waitcnt lgkmcnt(0)
	v_cndmask_b32_e32 v53, v54, v131, vcc
	v_cndmask_b32_e32 v66, v193, v54, vcc
	v_cvt_pk_bf16_f32 v52, v55, v62
	v_cvt_pk_bf16_f32 v53, v64, v53
	v_cvt_pk_bf16_f32 v54, v49, v63
	v_cvt_pk_bf16_f32 v55, v65, v66
	global_store_dwordx4 v[60:61], v[52:55], off offset:64
	v_cndmask_b32_e32 v49, v120, v108, vcc
	ds_bpermute_b32 v49, v186, v49
	v_or_b32_e32 v52, 48, v48
	v_ashrrev_i32_e32 v53, 31, v52
	v_lshlrev_b64 v[52:53], 11, v[52:53]
	v_lshl_add_u64 v[60:61], v[50:51], 0, v[52:53]
	v_cndmask_b32_e32 v52, v121, v109, vcc
	v_cndmask_b32_e32 v53, v122, v110, vcc
	v_cndmask_b32_e32 v54, v123, v111, vcc
	ds_bpermute_b32 v52, v186, v52
	ds_bpermute_b32 v53, v186, v53
	ds_bpermute_b32 v54, v186, v54
	s_waitcnt lgkmcnt(3)
	v_cndmask_b32_e32 v55, v49, v120, vcc
	v_cndmask_b32_e32 v49, v108, v49, vcc
	s_waitcnt lgkmcnt(2)
	v_cndmask_b32_e32 v62, v52, v121, vcc
	v_cndmask_b32_e32 v63, v109, v52, vcc
	s_waitcnt lgkmcnt(1)
	v_cndmask_b32_e32 v64, v53, v122, vcc
	v_cndmask_b32_e32 v65, v110, v53, vcc
	s_waitcnt lgkmcnt(0)
	v_cndmask_b32_e32 v53, v54, v123, vcc
	v_cndmask_b32_e32 v66, v111, v54, vcc
	v_cvt_pk_bf16_f32 v52, v55, v62
	v_cvt_pk_bf16_f32 v53, v64, v53
	v_cvt_pk_bf16_f32 v54, v49, v63
	v_cvt_pk_bf16_f32 v55, v65, v66
	global_store_dwordx4 v[60:61], v[52:55], off
	v_cndmask_b32_e32 v49, v100, v80, vcc
	ds_bpermute_b32 v49, v186, v49
	v_cndmask_b32_e32 v52, v101, v81, vcc
	v_cndmask_b32_e32 v53, v102, v82, vcc
	v_cndmask_b32_e32 v54, v103, v83, vcc
	ds_bpermute_b32 v52, v186, v52
	ds_bpermute_b32 v53, v186, v53
	ds_bpermute_b32 v54, v186, v54
	s_waitcnt lgkmcnt(3)
	v_cndmask_b32_e32 v55, v49, v100, vcc
	v_cndmask_b32_e32 v49, v80, v49, vcc
	s_waitcnt lgkmcnt(2)
	v_cndmask_b32_e32 v62, v52, v101, vcc
	v_cndmask_b32_e32 v63, v81, v52, vcc
	s_waitcnt lgkmcnt(1)
	v_cndmask_b32_e32 v64, v53, v102, vcc
	v_cndmask_b32_e32 v65, v82, v53, vcc
	s_waitcnt lgkmcnt(0)
	v_cndmask_b32_e32 v53, v54, v103, vcc
	v_cndmask_b32_e32 v66, v83, v54, vcc
	v_mfma_f32_16x16x32_bf16 v[92:95], v[140:143], v[88:91], v[92:95]
	v_cvt_pk_bf16_f32 v52, v55, v62
	v_cvt_pk_bf16_f32 v53, v64, v53
	v_cvt_pk_bf16_f32 v54, v49, v63
	v_mfma_f32_16x16x32_bf16 v[84:87], v[144:147], v[88:91], v[84:87]
	v_cvt_pk_bf16_f32 v55, v65, v66
	global_store_dwordx4 v[60:61], v[52:55], off offset:64
	v_mfma_f32_16x16x32_bf16 v[76:79], v[160:163], v[88:91], v[76:79]
	s_nop 0
	v_or_b32_e32 v52, 64, v48
	v_ashrrev_i32_e32 v53, 31, v52
	v_lshlrev_b64 v[52:53], 11, v[52:53]
	v_lshl_add_u64 v[60:61], v[50:51], 0, v[52:53]
	v_cndmask_b32_e32 v49, v92, v84, vcc
	v_cndmask_b32_e32 v52, v93, v85, vcc
	v_cndmask_b32_e32 v53, v94, v86, vcc
	v_cndmask_b32_e32 v54, v95, v87, vcc
	ds_bpermute_b32 v49, v186, v49
	ds_bpermute_b32 v52, v186, v52
	ds_bpermute_b32 v53, v186, v53
	ds_bpermute_b32 v54, v186, v54
	v_mfma_f32_16x16x32_bf16 v[56:59], v[178:181], v[88:91], v[56:59]
	s_waitcnt lgkmcnt(3)
	v_cndmask_b32_e32 v55, v49, v92, vcc
	v_cndmask_b32_e32 v49, v84, v49, vcc
	s_waitcnt lgkmcnt(2)
	v_cndmask_b32_e32 v62, v52, v93, vcc
	v_cndmask_b32_e32 v63, v85, v52, vcc
	s_waitcnt lgkmcnt(1)
	v_cndmask_b32_e32 v64, v53, v94, vcc
	v_cndmask_b32_e32 v65, v86, v53, vcc
	s_waitcnt lgkmcnt(0)
	v_cndmask_b32_e32 v53, v54, v95, vcc
	v_cndmask_b32_e32 v66, v87, v54, vcc
	v_cvt_pk_bf16_f32 v52, v55, v62
	v_cvt_pk_bf16_f32 v53, v64, v53
	v_cvt_pk_bf16_f32 v54, v49, v63
	v_cvt_pk_bf16_f32 v55, v65, v66
	global_store_dwordx4 v[60:61], v[52:55], off
	v_cndmask_b32_e32 v49, v76, v56, vcc
	ds_bpermute_b32 v49, v186, v49
	v_cndmask_b32_e32 v52, v77, v57, vcc
	v_cndmask_b32_e32 v53, v78, v58, vcc
	v_cndmask_b32_e32 v54, v79, v59, vcc
	ds_bpermute_b32 v52, v186, v52
	ds_bpermute_b32 v53, v186, v53
	ds_bpermute_b32 v54, v186, v54
	s_waitcnt lgkmcnt(3)
	v_cndmask_b32_e32 v55, v49, v76, vcc
	v_cndmask_b32_e32 v49, v56, v49, vcc
	s_waitcnt lgkmcnt(2)
	v_cndmask_b32_e32 v56, v52, v77, vcc
	v_cndmask_b32_e32 v57, v57, v52, vcc
	s_waitcnt lgkmcnt(1)
	v_cndmask_b32_e32 v62, v53, v78, vcc
	v_cndmask_b32_e32 v58, v58, v53, vcc
	s_waitcnt lgkmcnt(0)
	v_cndmask_b32_e32 v53, v54, v79, vcc
	v_cndmask_b32_e32 v59, v59, v54, vcc
	v_cvt_pk_bf16_f32 v52, v55, v56
	v_cvt_pk_bf16_f32 v53, v62, v53
	v_cvt_pk_bf16_f32 v54, v49, v57
	v_cvt_pk_bf16_f32 v55, v58, v59
	global_store_dwordx4 v[60:61], v[52:55], off offset:64
	v_cndmask_b32_e32 v49, v40, v44, vcc
	v_cndmask_b32_e32 v56, v43, v47, vcc
	v_cndmask_b32_e32 v54, v41, v45, vcc
	v_cndmask_b32_e32 v55, v42, v46, vcc
	ds_bpermute_b32 v49, v186, v49
	ds_bpermute_b32 v54, v186, v54
	ds_bpermute_b32 v55, v186, v55
	ds_bpermute_b32 v56, v186, v56
	v_mfma_f32_16x16x32_bf16 v[32:35], v[160:163], v[104:107], v[72:75]
	v_or_b32_e32 v52, 0x50, v48
	v_ashrrev_i32_e32 v53, 31, v52
	v_lshlrev_b64 v[52:53], 11, v[52:53]
	s_waitcnt lgkmcnt(3)
	v_cndmask_b32_e32 v40, v49, v40, vcc
	v_cndmask_b32_e32 v44, v44, v49, vcc
	s_waitcnt lgkmcnt(2)
	v_cndmask_b32_e32 v41, v54, v41, vcc
	v_cndmask_b32_e32 v45, v45, v54, vcc
	s_waitcnt lgkmcnt(1)
	v_cndmask_b32_e32 v42, v55, v42, vcc
	v_cndmask_b32_e32 v46, v46, v55, vcc
	s_waitcnt lgkmcnt(0)
	v_cndmask_b32_e32 v43, v56, v43, vcc
	v_cndmask_b32_e32 v47, v47, v56, vcc
	v_lshl_add_u64 v[52:53], v[50:51], 0, v[52:53]
	v_cvt_pk_bf16_f32 v40, v40, v41
	v_cvt_pk_bf16_f32 v41, v42, v43
	v_cvt_pk_bf16_f32 v42, v44, v45
	v_cvt_pk_bf16_f32 v43, v46, v47
	global_store_dwordx4 v[52:53], v[40:43], off
	v_mfma_f32_16x16x32_bf16 v[24:27], v[140:143], v[112:115], v[96:99]
	s_nop 0
	v_cndmask_b32_e32 v40, v32, v36, vcc
	v_cndmask_b32_e32 v41, v33, v37, vcc
	v_cndmask_b32_e32 v42, v34, v38, vcc
	v_cndmask_b32_e32 v43, v35, v39, vcc
	ds_bpermute_b32 v40, v186, v40
	ds_bpermute_b32 v41, v186, v41
	ds_bpermute_b32 v42, v186, v42
	ds_bpermute_b32 v43, v186, v43
	v_mfma_f32_16x16x32_bf16 v[28:31], v[144:147], v[112:115], v[28:31]
	s_waitcnt lgkmcnt(3)
	v_cndmask_b32_e32 v32, v40, v32, vcc
	v_cndmask_b32_e32 v36, v36, v40, vcc
	s_waitcnt lgkmcnt(2)
	v_cndmask_b32_e32 v33, v41, v33, vcc
	v_cndmask_b32_e32 v37, v37, v41, vcc
	s_waitcnt lgkmcnt(1)
	v_cndmask_b32_e32 v34, v42, v34, vcc
	v_cndmask_b32_e32 v38, v38, v42, vcc
	s_waitcnt lgkmcnt(0)
	v_cndmask_b32_e32 v35, v43, v35, vcc
	v_cndmask_b32_e32 v39, v39, v43, vcc
	v_cvt_pk_bf16_f32 v32, v32, v33
	v_cvt_pk_bf16_f32 v33, v34, v35
	v_cvt_pk_bf16_f32 v34, v36, v37
	v_cvt_pk_bf16_f32 v35, v38, v39
	global_store_dwordx4 v[52:53], v[32:35], off offset:64
	v_cndmask_b32_e32 v36, v26, v30, vcc
	v_cndmask_b32_e32 v37, v27, v31, vcc
	v_cndmask_b32_e32 v34, v24, v28, vcc
	v_cndmask_b32_e32 v35, v25, v29, vcc
	ds_bpermute_b32 v34, v186, v34
	ds_bpermute_b32 v35, v186, v35
	ds_bpermute_b32 v36, v186, v36
	ds_bpermute_b32 v37, v186, v37
	v_mfma_f32_16x16x32_bf16 v[16:19], v[160:163], v[112:115], v[124:127]
	v_or_b32_e32 v32, 0x60, v48
	v_ashrrev_i32_e32 v33, 31, v32
	v_lshlrev_b64 v[32:33], 11, v[32:33]
	v_mfma_f32_16x16x32_bf16 v[20:23], v[178:181], v[112:115], v[20:23]
	s_waitcnt lgkmcnt(3)
	v_cndmask_b32_e32 v24, v34, v24, vcc
	v_cndmask_b32_e32 v28, v28, v34, vcc
	s_waitcnt lgkmcnt(2)
	v_cndmask_b32_e32 v25, v35, v25, vcc
	v_cndmask_b32_e32 v29, v29, v35, vcc
	s_waitcnt lgkmcnt(1)
	v_cndmask_b32_e32 v26, v36, v26, vcc
	v_cndmask_b32_e32 v30, v30, v36, vcc
	s_waitcnt lgkmcnt(0)
	v_cndmask_b32_e32 v27, v37, v27, vcc
	v_cndmask_b32_e32 v31, v31, v37, vcc
	v_lshl_add_u64 v[32:33], v[50:51], 0, v[32:33]
	v_cvt_pk_bf16_f32 v24, v24, v25
	v_cvt_pk_bf16_f32 v25, v26, v27
	v_cvt_pk_bf16_f32 v26, v28, v29
	v_cvt_pk_bf16_f32 v27, v30, v31
	global_store_dwordx4 v[32:33], v[24:27], off
	v_mfma_f32_16x16x32_bf16 v[0:3], v[160:163], v[116:119], v[0:3]
	s_nop 0
	v_cndmask_b32_e32 v24, v16, v20, vcc
	v_cndmask_b32_e32 v25, v17, v21, vcc
	v_cndmask_b32_e32 v26, v18, v22, vcc
	v_cndmask_b32_e32 v27, v19, v23, vcc
	ds_bpermute_b32 v24, v186, v24
	ds_bpermute_b32 v25, v186, v25
	ds_bpermute_b32 v26, v186, v26
	ds_bpermute_b32 v27, v186, v27
	v_mfma_f32_16x16x32_bf16 v[4:7], v[178:181], v[116:119], v[68:71]
	s_waitcnt lgkmcnt(3)
	v_cndmask_b32_e32 v16, v24, v16, vcc
	v_cndmask_b32_e32 v20, v20, v24, vcc
	s_waitcnt lgkmcnt(2)
	v_cndmask_b32_e32 v17, v25, v17, vcc
	v_cndmask_b32_e32 v21, v21, v25, vcc
	s_waitcnt lgkmcnt(1)
	v_cndmask_b32_e32 v18, v26, v18, vcc
	v_cndmask_b32_e32 v22, v22, v26, vcc
	s_waitcnt lgkmcnt(0)
	v_cndmask_b32_e32 v19, v27, v19, vcc
	v_cndmask_b32_e32 v23, v23, v27, vcc
	v_cvt_pk_bf16_f32 v16, v16, v17
	v_cvt_pk_bf16_f32 v17, v18, v19
	v_cvt_pk_bf16_f32 v18, v20, v21
	v_cvt_pk_bf16_f32 v19, v22, v23
	global_store_dwordx4 v[32:33], v[16:19], off offset:64
	v_cndmask_b32_e32 v20, v10, v14, vcc
	v_cndmask_b32_e32 v21, v11, v15, vcc
	v_cndmask_b32_e32 v18, v8, v12, vcc
	v_cndmask_b32_e32 v19, v9, v13, vcc
	ds_bpermute_b32 v18, v186, v18
	ds_bpermute_b32 v19, v186, v19
	ds_bpermute_b32 v20, v186, v20
	ds_bpermute_b32 v21, v186, v21
	v_or_b32_e32 v16, 0x70, v48
	v_ashrrev_i32_e32 v17, 31, v16
	v_lshlrev_b64 v[16:17], 11, v[16:17]
	s_waitcnt lgkmcnt(3)
	v_cndmask_b32_e32 v8, v18, v8, vcc
	v_cndmask_b32_e32 v12, v12, v18, vcc
	s_waitcnt lgkmcnt(2)
	v_cndmask_b32_e32 v9, v19, v9, vcc
	v_cndmask_b32_e32 v13, v13, v19, vcc
	s_waitcnt lgkmcnt(1)
	v_cndmask_b32_e32 v10, v20, v10, vcc
	v_cndmask_b32_e32 v14, v14, v20, vcc
	s_waitcnt lgkmcnt(0)
	v_cndmask_b32_e32 v11, v21, v11, vcc
	v_cndmask_b32_e32 v15, v15, v21, vcc
	v_lshl_add_u64 v[16:17], v[50:51], 0, v[16:17]
	v_cvt_pk_bf16_f32 v8, v8, v9
	v_cvt_pk_bf16_f32 v9, v10, v11
	v_cvt_pk_bf16_f32 v10, v12, v13
	v_cvt_pk_bf16_f32 v11, v14, v15
	global_store_dwordx4 v[16:17], v[8:11], off
	s_nop 1
	v_cndmask_b32_e32 v8, v0, v4, vcc
	v_cndmask_b32_e32 v9, v1, v5, vcc
	v_cndmask_b32_e32 v10, v2, v6, vcc
	v_cndmask_b32_e32 v11, v3, v7, vcc
	ds_bpermute_b32 v8, v186, v8
	ds_bpermute_b32 v9, v186, v9
	ds_bpermute_b32 v10, v186, v10
	ds_bpermute_b32 v11, v186, v11
	s_waitcnt lgkmcnt(3)
	v_cndmask_b32_e32 v0, v8, v0, vcc
	v_cndmask_b32_e32 v4, v4, v8, vcc
	s_waitcnt lgkmcnt(2)
	v_cndmask_b32_e32 v1, v9, v1, vcc
	v_cndmask_b32_e32 v5, v5, v9, vcc
	s_waitcnt lgkmcnt(1)
	v_cndmask_b32_e32 v2, v10, v2, vcc
	v_cndmask_b32_e32 v6, v6, v10, vcc
	s_waitcnt lgkmcnt(0)
	v_cndmask_b32_e32 v3, v11, v3, vcc
	v_cndmask_b32_e32 v7, v7, v11, vcc
	v_cvt_pk_bf16_f32 v0, v0, v1
	v_cvt_pk_bf16_f32 v1, v2, v3
	v_cvt_pk_bf16_f32 v2, v4, v5
	v_cvt_pk_bf16_f32 v3, v6, v7
	global_store_dwordx4 v[16:17], v[0:3], off offset:64
	s_load_dword s8, s[8:9], 0x0
	s_waitcnt lgkmcnt(0)
	s_add_i32 s10, s8, s10
	s_cmpk_gt_i32 s10, 0xff
	s_cbranch_scc0 .LBB0_146

.LBB0_361:
	s_add_i32 s5, s4, -1
	s_bitcmp1_b32 s5, 0
	s_cselect_b32 s30, 0x5c00, 0
	s_bitcmp1_b32 s4, 0
	s_cselect_b32 s6, 0x5c00, 0
	v_add_u32_e32 v212, s30, v185
	v_add_u32_e32 v211, 0x1a00, v212
	v_add_u32_e32 v205, v211, v210
	v_add_u32_e32 v204, v212, v210
	ds_read_b128 v[136:139], v205
	ds_read_b128 v[140:143], v204
	ds_read_b128 v[144:147], v204 offset:64
	v_lshlrev_b32_e32 v132, 1, v178
	v_lshlrev_b32_e32 v133, 1, v152
	v_add3_u32 v132, s6, v132, v133
	s_waitcnt vmcnt(4)
	ds_write_b128 v132, v[112:115]
	v_lshlrev_b32_e32 v112, 1, v179
	v_lshlrev_b32_e32 v113, 1, v154
	v_add3_u32 v112, s6, v112, v113
	s_waitcnt vmcnt(3)
	ds_write_b128 v112, v[116:119]
	v_lshlrev_b32_e32 v112, 1, v180
	v_lshlrev_b32_e32 v113, 1, v156
	v_add3_u32 v112, s6, v112, v113
	s_waitcnt vmcnt(2)
	ds_write_b128 v112, v[128:131]
	v_lshlrev_b32_e32 v112, 1, v181
	v_lshlrev_b32_e32 v113, 1, v158
	v_add3_u32 v112, s6, v112, v113
	s_waitcnt vmcnt(1)
	ds_write_b128 v112, v[124:127] offset:13312
	v_lshlrev_b32_e32 v112, 1, v182
	v_lshlrev_b32_e32 v113, 1, v164
	s_min_u32 s5, s5, 5
	v_add3_u32 v112, s6, v112, v113
	s_lshl_b32 s6, s5, 5
	s_add_i32 s31, s6, 64
	s_waitcnt vmcnt(0)
	ds_write_b128 v112, v[120:123] offset:13312
	v_add_u32_e32 v112, s31, v161
	v_add_u32_e32 v114, s31, v174
	v_add_u32_e32 v120, s31, v175
	v_mad_i64_i32 v[112:113], s[6:7], v112, s18, v[168:169]
	v_mad_i64_i32 v[116:117], s[6:7], v114, s18, v[170:171]
	v_mad_i64_i32 v[120:121], s[6:7], v120, s18, v[172:173]
	s_lshl_b32 s36, s5, 6
	global_load_dwordx4 v[112:115], v[112:113], off
	s_nop 0
	global_load_dwordx4 v[116:119], v[116:117], off
	v_lshl_add_u64 v[122:123], v[162:163], 0, s[36:37]
	global_load_dwordx4 v[128:131], v[120:121], off
	global_load_dwordx4 v[124:127], v[122:123], off offset:128
	v_lshl_add_u64 v[120:121], v[166:167], 0, s[36:37]
	global_load_dwordx4 v[120:123], v[120:121], off offset:128
	v_xor_b32_e32 v132, 0x80000000, v187
	v_mov_b32_e32 v133, v132
	v_mov_b32_e32 v134, v132
	v_mov_b32_e32 v135, v132
	v_xor_b32_e32 v190, 0x80000000, v186
	v_mov_b32_e32 v191, v190
	v_mov_b32_e32 v192, v190
	v_mov_b32_e32 v193, v190
	s_waitcnt lgkmcnt(6)
	v_mfma_f32_16x16x32_bf16 v[194:197], v[140:143], v[40:43], v[132:135]
	v_mfma_f32_16x16x32_bf16 v[140:143], v[140:143], v[44:47], v[190:193]
	ds_read_b128 v[198:201], v205 offset:64
	v_mfma_f32_16x16x32_bf16 v[132:135], v[136:139], v[40:43], v[132:135]
	v_mfma_f32_16x16x32_bf16 v[136:139], v[136:139], v[44:47], v[190:193]
	s_nop 2
	ds_read_b128 v[190:193], v204 offset:128
	s_waitcnt lgkmcnt(2)
	v_mfma_f32_16x16x32_bf16 v[140:143], v[144:147], v[36:39], v[140:143]
	v_mfma_f32_16x16x32_bf16 v[194:197], v[144:147], v[32:35], v[194:197]
	ds_read_b128 v[144:147], v205 offset:128
	s_waitcnt lgkmcnt(2)
	v_mfma_f32_16x16x32_bf16 v[132:135], v[198:201], v[32:35], v[132:135]
	v_mfma_f32_16x16x32_bf16 v[136:139], v[198:201], v[36:39], v[136:139]
	ds_read_b128 v[198:201], v204 offset:192
	s_waitcnt lgkmcnt(2)
	v_mfma_f32_16x16x32_bf16 v[140:143], v[190:193], v[28:31], v[140:143]
	v_mfma_f32_16x16x32_bf16 v[194:197], v[190:193], v[24:27], v[194:197]
	ds_read_b128 v[190:193], v205 offset:192
	s_waitcnt lgkmcnt(2)
	v_mfma_f32_16x16x32_bf16 v[132:135], v[144:147], v[24:27], v[132:135]
	v_mfma_f32_16x16x32_bf16 v[136:139], v[144:147], v[28:31], v[136:139]
	ds_read_b128 v[144:147], v204 offset:256
	s_waitcnt lgkmcnt(2)
	v_mfma_f32_16x16x32_bf16 v[140:143], v[198:201], v[20:23], v[140:143]
	v_mfma_f32_16x16x32_bf16 v[194:197], v[198:201], v[16:19], v[194:197]
	ds_read_b128 v[198:201], v205 offset:256
	s_waitcnt lgkmcnt(2)
	v_mfma_f32_16x16x32_bf16 v[132:135], v[190:193], v[16:19], v[132:135]
	v_mfma_f32_16x16x32_bf16 v[136:139], v[190:193], v[20:23], v[136:139]
	ds_read_b128 v[190:193], v204 offset:320
	s_waitcnt lgkmcnt(2)
	v_mfma_f32_16x16x32_bf16 v[140:143], v[144:147], v[12:15], v[140:143]
	v_mfma_f32_16x16x32_bf16 v[194:197], v[144:147], v[4:7], v[194:197]
	ds_read_b128 v[204:207], v205 offset:320
	s_waitcnt lgkmcnt(2)
	v_mfma_f32_16x16x32_bf16 v[132:135], v[198:201], v[4:7], v[132:135]
	v_mfma_f32_16x16x32_bf16 v[198:201], v[198:201], v[12:15], v[136:139]
	s_waitcnt lgkmcnt(1)
	v_mfma_f32_16x16x32_bf16 v[144:147], v[190:193], v[0:3], v[194:197]
	v_mfma_f32_16x16x32_bf16 v[136:139], v[190:193], v[8:11], v[140:143]
	s_waitcnt lgkmcnt(0)
	v_mfma_f32_16x16x32_bf16 v[140:143], v[204:207], v[0:3], v[132:135]
	v_mfma_f32_16x16x32_bf16 v[132:135], v[204:207], v[8:11], v[198:201]
	s_nop 3
	v_max_f32_e32 v190, v145, v145
	v_max_f32_e32 v191, v144, v144
	v_max_f32_e32 v198, v137, v137
	v_max_f32_e32 v199, v136, v136
	v_max_f32_e32 v190, v191, v190
	v_max_f32_e32 v198, v199, v198
	v_max3_f32 v190, v190, v146, v147
	v_max3_f32 v198, v198, v138, v139
	v_max3_f32 v190, v190, v140, v141
	v_max3_f32 v198, v198, v132, v133
	v_max3_f32 v190, v190, v142, v143
	v_max3_f32 v198, v198, v134, v135
	ds_bpermute_b32 v191, v155, v190
	ds_bpermute_b32 v199, v155, v198
	s_waitcnt lgkmcnt(0)
	v_max_f32_e32 v191, v191, v191
	v_max_f32_e32 v199, v199, v199
	v_max_f32_e32 v190, v190, v191
	v_max_f32_e32 v198, v198, v199
	ds_bpermute_b32 v191, v153, v190
	ds_bpermute_b32 v199, v153, v198
	s_waitcnt lgkmcnt(0)
	v_max_f32_e32 v191, v191, v191
	v_max_f32_e32 v199, v199, v199
	v_max_f32_e32 v213, v190, v191
	v_max_f32_e32 v200, v198, v199
	v_cmp_lt_f32_e32 vcc, s79, v213
	s_cbranch_vccz .LBB0_363
	s_nop 0
	v_cndmask_b32_e32 v191, 0, v213, vcc
	v_exp_f32_e64 v190, -v191
	v_add_f32_e32 v187, v187, v191
	v_sub_f32_e32 v144, v144, v191
	v_sub_f32_e32 v145, v145, v191
	v_pk_mul_f32 v[70:71], v[70:71], v[190:191] op_sel_hi:[1,0]
	v_pk_mul_f32 v[68:69], v[68:69], v[190:191] op_sel_hi:[1,0]
	v_pk_mul_f32 v[74:75], v[74:75], v[190:191] op_sel_hi:[1,0]
	v_pk_mul_f32 v[72:73], v[72:73], v[190:191] op_sel_hi:[1,0]
	v_pk_mul_f32 v[78:79], v[78:79], v[190:191] op_sel_hi:[1,0]
	v_pk_mul_f32 v[76:77], v[76:77], v[190:191] op_sel_hi:[1,0]
	v_pk_mul_f32 v[102:103], v[102:103], v[190:191] op_sel_hi:[1,0]
	v_pk_mul_f32 v[100:101], v[100:101], v[190:191] op_sel_hi:[1,0]
	v_pk_mul_f32 v[82:83], v[82:83], v[190:191] op_sel_hi:[1,0]
	v_pk_mul_f32 v[80:81], v[80:81], v[190:191] op_sel_hi:[1,0]
	v_pk_mul_f32 v[106:107], v[106:107], v[190:191] op_sel_hi:[1,0]
	v_pk_mul_f32 v[104:105], v[104:105], v[190:191] op_sel_hi:[1,0]
	v_pk_mul_f32 v[110:111], v[110:111], v[190:191] op_sel_hi:[1,0]
	v_pk_mul_f32 v[108:109], v[108:109], v[190:191] op_sel_hi:[1,0]
	v_pk_mul_f32 v[86:87], v[86:87], v[190:191] op_sel_hi:[1,0]
	v_pk_mul_f32 v[84:85], v[84:85], v[190:191] op_sel_hi:[1,0]
	v_mul_f32_e32 v165, v165, v190
	v_sub_f32_e32 v146, v146, v191
	v_sub_f32_e32 v147, v147, v191
	v_sub_f32_e32 v140, v140, v191
	v_sub_f32_e32 v141, v141, v191
	v_sub_f32_e32 v142, v142, v191
	v_sub_f32_e32 v143, v143, v191
.LBB0_363:
	v_mov_b32_e32 v213, v200
	v_cmp_lt_f32_e32 vcc, s79, v200
	s_cbranch_vccz .LBB0_360
	s_nop 0
	v_cndmask_b32_e32 v191, 0, v213, vcc
	v_exp_f32_e64 v190, -v191
	v_add_f32_e32 v186, v186, v191
	v_sub_f32_e32 v136, v136, v191
	v_sub_f32_e32 v137, v137, v191
	v_pk_mul_f32 v[50:51], v[50:51], v[190:191] op_sel_hi:[1,0]
	v_pk_mul_f32 v[48:49], v[48:49], v[190:191] op_sel_hi:[1,0]
	v_pk_mul_f32 v[54:55], v[54:55], v[190:191] op_sel_hi:[1,0]
	v_pk_mul_f32 v[52:53], v[52:53], v[190:191] op_sel_hi:[1,0]
	v_pk_mul_f32 v[58:59], v[58:59], v[190:191] op_sel_hi:[1,0]
	v_pk_mul_f32 v[56:57], v[56:57], v[190:191] op_sel_hi:[1,0]
	v_pk_mul_f32 v[90:91], v[90:91], v[190:191] op_sel_hi:[1,0]
	v_pk_mul_f32 v[88:89], v[88:89], v[190:191] op_sel_hi:[1,0]
	v_pk_mul_f32 v[62:63], v[62:63], v[190:191] op_sel_hi:[1,0]
	v_pk_mul_f32 v[60:61], v[60:61], v[190:191] op_sel_hi:[1,0]
	v_pk_mul_f32 v[94:95], v[94:95], v[190:191] op_sel_hi:[1,0]
	v_pk_mul_f32 v[92:93], v[92:93], v[190:191] op_sel_hi:[1,0]
	v_pk_mul_f32 v[98:99], v[98:99], v[190:191] op_sel_hi:[1,0]
	v_pk_mul_f32 v[96:97], v[96:97], v[190:191] op_sel_hi:[1,0]
	v_pk_mul_f32 v[66:67], v[66:67], v[190:191] op_sel_hi:[1,0]
	v_pk_mul_f32 v[64:65], v[64:65], v[190:191] op_sel_hi:[1,0]
	v_mul_f32_e32 v160, v160, v190
	v_sub_f32_e32 v138, v138, v191
	v_sub_f32_e32 v139, v139, v191
	v_sub_f32_e32 v132, v132, v191
	v_sub_f32_e32 v133, v133, v191
	v_sub_f32_e32 v134, v134, v191
	v_sub_f32_e32 v135, v135, v191
	s_branch .LBB0_360

.LBB0_377:
	s_add_i32 s5, s4, -1
	s_bitcmp1_b32 s5, 0
	s_cselect_b32 s30, 0x5c00, 0
	s_bitcmp1_b32 s4, 0
	s_cselect_b32 s6, 0x5c00, 0
	v_add_u32_e32 v212, s30, v185
	v_add_u32_e32 v211, 0x1a00, v212
	v_add_u32_e32 v205, v211, v210
	v_add_u32_e32 v204, v212, v210
	ds_read_b128 v[136:139], v205
	ds_read_b128 v[140:143], v204
	ds_read_b128 v[144:147], v204 offset:64
	v_lshlrev_b32_e32 v132, 1, v178
	v_lshlrev_b32_e32 v133, 1, v152
	v_add3_u32 v132, s6, v132, v133
	s_waitcnt vmcnt(4)
	ds_write_b128 v132, v[112:115]
	v_lshlrev_b32_e32 v112, 1, v179
	v_lshlrev_b32_e32 v113, 1, v154
	v_add3_u32 v112, s6, v112, v113
	s_waitcnt vmcnt(3)
	ds_write_b128 v112, v[116:119]
	v_lshlrev_b32_e32 v112, 1, v180
	v_lshlrev_b32_e32 v113, 1, v156
	v_add3_u32 v112, s6, v112, v113
	s_waitcnt vmcnt(2)
	ds_write_b128 v112, v[128:131]
	v_lshlrev_b32_e32 v112, 1, v181
	v_lshlrev_b32_e32 v113, 1, v158
	v_add3_u32 v112, s6, v112, v113
	s_waitcnt vmcnt(1)
	ds_write_b128 v112, v[124:127] offset:13312
	v_lshlrev_b32_e32 v112, 1, v182
	v_lshlrev_b32_e32 v113, 1, v164
	s_min_u32 s5, s5, 37
	v_add3_u32 v112, s6, v112, v113
	s_lshl_b32 s6, s5, 5
	s_add_i32 s31, s6, 64
	s_waitcnt vmcnt(0)
	ds_write_b128 v112, v[120:123] offset:13312
	v_add_u32_e32 v112, s31, v161
	v_add_u32_e32 v114, s31, v174
	v_add_u32_e32 v120, s31, v175
	v_mad_i64_i32 v[112:113], s[6:7], v112, s18, v[168:169]
	v_mad_i64_i32 v[116:117], s[6:7], v114, s18, v[170:171]
	v_mad_i64_i32 v[120:121], s[6:7], v120, s18, v[172:173]
	s_lshl_b32 s36, s5, 6
	global_load_dwordx4 v[112:115], v[112:113], off
	s_nop 0
	global_load_dwordx4 v[116:119], v[116:117], off
	v_lshl_add_u64 v[122:123], v[162:163], 0, s[36:37]
	global_load_dwordx4 v[128:131], v[120:121], off
	global_load_dwordx4 v[124:127], v[122:123], off offset:128
	v_lshl_add_u64 v[120:121], v[166:167], 0, s[36:37]
	global_load_dwordx4 v[120:123], v[120:121], off offset:128
	v_xor_b32_e32 v132, 0x80000000, v187
	v_mov_b32_e32 v133, v132
	v_mov_b32_e32 v134, v132
	v_mov_b32_e32 v135, v132
	v_xor_b32_e32 v190, 0x80000000, v186
	v_mov_b32_e32 v191, v190
	v_mov_b32_e32 v192, v190
	v_mov_b32_e32 v193, v190
	s_waitcnt lgkmcnt(6)
	v_mfma_f32_16x16x32_bf16 v[194:197], v[140:143], v[40:43], v[132:135]
	v_mfma_f32_16x16x32_bf16 v[140:143], v[140:143], v[44:47], v[190:193]
	ds_read_b128 v[198:201], v205 offset:64
	v_mfma_f32_16x16x32_bf16 v[132:135], v[136:139], v[40:43], v[132:135]
	v_mfma_f32_16x16x32_bf16 v[136:139], v[136:139], v[44:47], v[190:193]
	s_nop 2
	ds_read_b128 v[190:193], v204 offset:128
	s_waitcnt lgkmcnt(2)
	v_mfma_f32_16x16x32_bf16 v[140:143], v[144:147], v[36:39], v[140:143]
	v_mfma_f32_16x16x32_bf16 v[194:197], v[144:147], v[32:35], v[194:197]
	ds_read_b128 v[144:147], v205 offset:128
	s_waitcnt lgkmcnt(2)
	v_mfma_f32_16x16x32_bf16 v[132:135], v[198:201], v[32:35], v[132:135]
	v_mfma_f32_16x16x32_bf16 v[136:139], v[198:201], v[36:39], v[136:139]
	ds_read_b128 v[198:201], v204 offset:192
	s_waitcnt lgkmcnt(2)
	v_mfma_f32_16x16x32_bf16 v[140:143], v[190:193], v[28:31], v[140:143]
	v_mfma_f32_16x16x32_bf16 v[194:197], v[190:193], v[24:27], v[194:197]
	ds_read_b128 v[190:193], v205 offset:192
	s_waitcnt lgkmcnt(2)
	v_mfma_f32_16x16x32_bf16 v[132:135], v[144:147], v[24:27], v[132:135]
	v_mfma_f32_16x16x32_bf16 v[136:139], v[144:147], v[28:31], v[136:139]
	ds_read_b128 v[144:147], v204 offset:256
	s_waitcnt lgkmcnt(2)
	v_mfma_f32_16x16x32_bf16 v[140:143], v[198:201], v[20:23], v[140:143]
	v_mfma_f32_16x16x32_bf16 v[194:197], v[198:201], v[16:19], v[194:197]
	ds_read_b128 v[198:201], v205 offset:256
	s_waitcnt lgkmcnt(2)
	v_mfma_f32_16x16x32_bf16 v[132:135], v[190:193], v[16:19], v[132:135]
	v_mfma_f32_16x16x32_bf16 v[136:139], v[190:193], v[20:23], v[136:139]
	ds_read_b128 v[190:193], v204 offset:320
	s_waitcnt lgkmcnt(2)
	v_mfma_f32_16x16x32_bf16 v[140:143], v[144:147], v[12:15], v[140:143]
	v_mfma_f32_16x16x32_bf16 v[194:197], v[144:147], v[4:7], v[194:197]
	ds_read_b128 v[204:207], v205 offset:320
	s_waitcnt lgkmcnt(2)
	v_mfma_f32_16x16x32_bf16 v[132:135], v[198:201], v[4:7], v[132:135]
	v_mfma_f32_16x16x32_bf16 v[198:201], v[198:201], v[12:15], v[136:139]
	s_waitcnt lgkmcnt(1)
	v_mfma_f32_16x16x32_bf16 v[144:147], v[190:193], v[0:3], v[194:197]
	v_mfma_f32_16x16x32_bf16 v[136:139], v[190:193], v[8:11], v[140:143]
	s_waitcnt lgkmcnt(0)
	v_mfma_f32_16x16x32_bf16 v[140:143], v[204:207], v[0:3], v[132:135]
	v_mfma_f32_16x16x32_bf16 v[132:135], v[204:207], v[8:11], v[198:201]
	s_nop 3
	v_max_f32_e32 v190, v145, v145
	v_max_f32_e32 v191, v144, v144
	v_max_f32_e32 v198, v137, v137
	v_max_f32_e32 v199, v136, v136
	v_max_f32_e32 v190, v191, v190
	v_max_f32_e32 v198, v199, v198
	v_max3_f32 v190, v190, v146, v147
	v_max3_f32 v198, v198, v138, v139
	v_max3_f32 v190, v190, v140, v141
	v_max3_f32 v198, v198, v132, v133
	v_max3_f32 v190, v190, v142, v143
	v_max3_f32 v198, v198, v134, v135
	ds_bpermute_b32 v191, v155, v190
	ds_bpermute_b32 v199, v155, v198
	s_waitcnt lgkmcnt(0)
	v_max_f32_e32 v191, v191, v191
	v_max_f32_e32 v199, v199, v199
	v_max_f32_e32 v190, v190, v191
	v_max_f32_e32 v198, v198, v199
	ds_bpermute_b32 v191, v153, v190
	ds_bpermute_b32 v199, v153, v198
	s_waitcnt lgkmcnt(0)
	v_max_f32_e32 v191, v191, v191
	v_max_f32_e32 v199, v199, v199
	v_max_f32_e32 v213, v190, v191
	v_max_f32_e32 v200, v198, v199
	v_cmp_lt_f32_e32 vcc, s79, v213
	s_cbranch_vccz .LBB0_379
	s_nop 0
	v_cndmask_b32_e32 v191, 0, v213, vcc
	v_exp_f32_e64 v190, -v191
	v_add_f32_e32 v187, v187, v191
	v_sub_f32_e32 v144, v144, v191
	v_sub_f32_e32 v145, v145, v191
	v_pk_mul_f32 v[70:71], v[70:71], v[190:191] op_sel_hi:[1,0]
	v_pk_mul_f32 v[68:69], v[68:69], v[190:191] op_sel_hi:[1,0]
	v_pk_mul_f32 v[74:75], v[74:75], v[190:191] op_sel_hi:[1,0]
	v_pk_mul_f32 v[72:73], v[72:73], v[190:191] op_sel_hi:[1,0]
	v_pk_mul_f32 v[78:79], v[78:79], v[190:191] op_sel_hi:[1,0]
	v_pk_mul_f32 v[76:77], v[76:77], v[190:191] op_sel_hi:[1,0]
	v_pk_mul_f32 v[102:103], v[102:103], v[190:191] op_sel_hi:[1,0]
	v_pk_mul_f32 v[100:101], v[100:101], v[190:191] op_sel_hi:[1,0]
	v_pk_mul_f32 v[82:83], v[82:83], v[190:191] op_sel_hi:[1,0]
	v_pk_mul_f32 v[80:81], v[80:81], v[190:191] op_sel_hi:[1,0]
	v_pk_mul_f32 v[106:107], v[106:107], v[190:191] op_sel_hi:[1,0]
	v_pk_mul_f32 v[104:105], v[104:105], v[190:191] op_sel_hi:[1,0]
	v_pk_mul_f32 v[110:111], v[110:111], v[190:191] op_sel_hi:[1,0]
	v_pk_mul_f32 v[108:109], v[108:109], v[190:191] op_sel_hi:[1,0]
	v_pk_mul_f32 v[86:87], v[86:87], v[190:191] op_sel_hi:[1,0]
	v_pk_mul_f32 v[84:85], v[84:85], v[190:191] op_sel_hi:[1,0]
	v_mul_f32_e32 v165, v165, v190
	v_sub_f32_e32 v146, v146, v191
	v_sub_f32_e32 v147, v147, v191
	v_sub_f32_e32 v140, v140, v191
	v_sub_f32_e32 v141, v141, v191
	v_sub_f32_e32 v142, v142, v191
	v_sub_f32_e32 v143, v143, v191

.LBB0_486:
	s_ashr_i32 s30, s36, 3
	s_lshl_b32 s40, s30, 1
	s_and_b32 s31, s30, -16
	s_and_b32 s40, s40, 14
	s_or_b32 s31, s40, s31
	s_bfe_u32 s40, s30, 0x10003
	s_or_b32 s31, s31, s40
	s_cmp_lt_i32 s30, 0
	s_cselect_b32 s30, s31, s30
	s_and_b32 s31, s36, 7
	s_mul_i32 s31, s31, 56
	s_add_i32 s30, s30, s31
	s_mul_hi_i32 s31, s30, 0x92492493
	s_add_i32 s31, s31, s30
	s_ashr_i32 s40, s31, 4
	s_lshr_b32 s41, s31, 31
	s_add_i32 s40, s40, s41
	s_mul_i32 s42, s40, 0xffffffe4
	s_add_i32 s42, s42, s30
	s_ashr_i32 s30, s31, 5
	s_mul_hi_i32 s31, s42, 0x92492493
	s_add_i32 s31, s31, s42
	s_add_i32 s30, s30, s41
	s_lshr_b32 s41, s31, 31
	s_ashr_i32 s31, s31, 2
	s_add_i32 s31, s31, s41
	s_lshl_b32 s41, s30, 1
	s_add_i32 s41, s41, s31
	s_sub_i32 s40, s40, s41
	s_mul_i32 s40, s40, 7
	s_add_i32 s41, s40, s42
	v_mov_b32_e32 v8, v188
	s_lshl_b32 s30, s30, 10
	s_lshl_b32 s40, s31, 8
	s_lshl_b32 s41, s41, 7
	s_add_i32 s40, s40, s30
	v_ashrrev_i32_e32 v9, 3, v8
	v_lshlrev_b32_e32 v4, 4, v8
	v_and_b32_e32 v176, 0x70, v4
	v_add_u32_e32 v4, s41, v9
	v_add_u32_e32 v0, s40, v9
	v_ashrrev_i32_e32 v5, 31, v4
	v_ashrrev_i32_e32 v1, 31, v0
	v_lshlrev_b64 v[4:5], 11, v[4:5]
	v_xor_b32_e32 v10, v9, v8
	v_lshlrev_b64 v[0:1], 11, v[0:1]
	v_lshl_add_u64 v[6:7], s[22:23], 0, v[4:5]
	v_lshlrev_b32_e32 v10, 4, v10
	v_lshl_add_u64 v[2:3], s[0:1], 0, v[0:1]
	v_lshl_add_u64 v[6:7], v[6:7], 0, v[176:177]
	v_and_b32_e32 v10, 0x70, v10
	s_mov_b32 s30, 0x30000
	v_lshl_add_u64 v[2:3], v[2:3], 0, v[176:177]
	v_lshl_or_b32 v176, v9, 7, v10
	v_lshlrev_b32_e32 v12, 7, v8
	v_lshrrev_b32_e32 v9, 4, v8
	v_bfe_u32 v14, v8, 4, 2
	v_and_b32_e32 v15, 7, v8
	v_add_co_u32_e32 v8, vcc, s30, v6
	v_bitop3_b32 v16, v9, v15, 3 bitop3:0x6c
	s_nop 0
	v_addc_co_u32_e32 v9, vcc, 0, v7, vcc
	s_mov_b32 s31, 0x20000
	v_add_co_u32_e32 v10, vcc, s31, v6
	s_mov_b32 s42, 0x10000
	s_nop 0
	v_addc_co_u32_e32 v11, vcc, 0, v7, vcc
	global_load_dwordx4 v[56:59], v[8:9], off
	global_load_dwordx4 v[64:67], v[10:11], off
	v_add_co_u32_e32 v8, vcc, s42, v6
	s_mov_b32 s43, 0x70000
	s_nop 0
	v_addc_co_u32_e32 v9, vcc, 0, v7, vcc
	v_add_co_u32_e32 v10, vcc, s43, v2
	s_mov_b32 s43, 0x60000
	s_nop 0
	v_addc_co_u32_e32 v11, vcc, 0, v3, vcc
	global_load_dwordx4 v[76:79], v[8:9], off
	global_load_dwordx4 v[84:87], v[10:11], off
	v_add_co_u32_e32 v8, vcc, s43, v2
	s_mov_b32 s43, 0x50000
	s_nop 0
	v_addc_co_u32_e32 v9, vcc, 0, v3, vcc
	v_add_co_u32_e32 v10, vcc, s43, v2
	s_mov_b32 s43, 0x40000
	s_nop 0
	v_addc_co_u32_e32 v11, vcc, 0, v3, vcc
	global_load_dwordx4 v[100:103], v[8:9], off
	global_load_dwordx4 v[104:107], v[10:11], off
	v_add_co_u32_e32 v8, vcc, s43, v2
	v_and_b32_e32 v13, 0xffffc780, v12
	s_nop 0
	v_addc_co_u32_e32 v9, vcc, 0, v3, vcc
	v_add_co_u32_e32 v10, vcc, s30, v2
	v_and_b32_e32 v12, 0x2780, v12
	s_nop 0
	v_addc_co_u32_e32 v11, vcc, 0, v3, vcc
	global_load_dwordx4 v[124:127], v[8:9], off
	global_load_dwordx4 v[128:131], v[10:11], off
	v_add_co_u32_e32 v8, vcc, s31, v2
	v_bitop3_b32 v14, v14, v15, 4 bitop3:0x36
	s_nop 0
	v_addc_co_u32_e32 v9, vcc, 0, v3, vcc
	v_add_co_u32_e32 v10, vcc, s42, v2
	v_mov_b32_e32 v116, 0
	s_nop 0
	v_addc_co_u32_e32 v11, vcc, 0, v3, vcc
	global_load_dwordx4 v[148:151], v[8:9], off
	global_load_dwordx4 v[152:155], v[10:11], off
	global_load_dwordx4 v[140:143], v[6:7], off
	global_load_dwordx4 v[160:163], v[2:3], off
	v_lshlrev_b32_e32 v2, 4, v16
	v_or_b32_e32 v185, v13, v2
	v_or_b32_e32 v184, v12, v2
	v_lshlrev_b32_e32 v2, 4, v14
	v_or_b32_e32 v183, v13, v2
	v_or_b32_e32 v182, v12, v2
	v_lshlrev_b32_e32 v2, 4, v15
	v_or_b32_e32 v0, v0, v2
	v_or_b32_e32 v4, v4, v2
	v_lshl_add_u64 v[178:179], s[34:35], 0, v[0:1]
	v_lshl_add_u64 v[180:181], s[2:3], 0, v[4:5]
	s_mov_b64 s[30:31], 0
	v_mov_b32_e32 v117, v116
	v_mov_b32_e32 v118, v116
	v_mov_b32_e32 v119, v116
	v_mov_b32_e32 v0, v116
	v_mov_b32_e32 v1, v116
	v_mov_b32_e32 v2, v116
	v_mov_b32_e32 v3, v116
	v_mov_b32_e32 v4, v116
	v_mov_b32_e32 v5, v116
	v_mov_b32_e32 v6, v116
	v_mov_b32_e32 v7, v116
	v_mov_b32_e32 v8, v116
	v_mov_b32_e32 v9, v116
	v_mov_b32_e32 v10, v116
	v_mov_b32_e32 v11, v116
	v_mov_b32_e32 v12, v116
	v_mov_b32_e32 v13, v116
	v_mov_b32_e32 v14, v116
	v_mov_b32_e32 v15, v116
	v_mov_b32_e32 v16, v116
	v_mov_b32_e32 v17, v116
	v_mov_b32_e32 v18, v116
	v_mov_b32_e32 v19, v116
	v_mov_b32_e32 v20, v116
	v_mov_b32_e32 v21, v116
	v_mov_b32_e32 v22, v116
	v_mov_b32_e32 v23, v116
	v_mov_b32_e32 v24, v116
	v_mov_b32_e32 v25, v116
	v_mov_b32_e32 v26, v116
	v_mov_b32_e32 v27, v116
	v_mov_b32_e32 v28, v116
	v_mov_b32_e32 v29, v116
	v_mov_b32_e32 v30, v116
	v_mov_b32_e32 v31, v116
	v_mov_b32_e32 v32, v116
	v_mov_b32_e32 v33, v116
	v_mov_b32_e32 v34, v116
	v_mov_b32_e32 v35, v116
	v_mov_b32_e32 v36, v116
	v_mov_b32_e32 v37, v116
	v_mov_b32_e32 v38, v116
	v_mov_b32_e32 v39, v116
	v_mov_b32_e32 v40, v116
	v_mov_b32_e32 v41, v116
	v_mov_b32_e32 v42, v116
	v_mov_b32_e32 v43, v116
	v_mov_b32_e32 v44, v116
	v_mov_b32_e32 v45, v116
	v_mov_b32_e32 v46, v116
	v_mov_b32_e32 v47, v116
	v_mov_b32_e32 v48, v116
	v_mov_b32_e32 v49, v116
	v_mov_b32_e32 v50, v116
	v_mov_b32_e32 v51, v116
	v_mov_b32_e32 v52, v116
	v_mov_b32_e32 v53, v116
	v_mov_b32_e32 v54, v116
	v_mov_b32_e32 v55, v116
	v_mov_b32_e32 v60, v116
	v_mov_b32_e32 v61, v116
	v_mov_b32_e32 v62, v116
	v_mov_b32_e32 v63, v116
	v_mov_b32_e32 v68, v116
	v_mov_b32_e32 v69, v116
	v_mov_b32_e32 v70, v116
	v_mov_b32_e32 v71, v116
	v_mov_b32_e32 v72, v116
	v_mov_b32_e32 v73, v116
	v_mov_b32_e32 v74, v116
	v_mov_b32_e32 v75, v116
	v_mov_b32_e32 v80, v116
	v_mov_b32_e32 v81, v116
	v_mov_b32_e32 v82, v116
	v_mov_b32_e32 v83, v116
	v_mov_b32_e32 v88, v116
	v_mov_b32_e32 v89, v116
	v_mov_b32_e32 v90, v116
	v_mov_b32_e32 v91, v116
	v_mov_b32_e32 v92, v116
	v_mov_b32_e32 v93, v116
	v_mov_b32_e32 v94, v116
	v_mov_b32_e32 v95, v116
	v_mov_b32_e32 v96, v116
	v_mov_b32_e32 v97, v116
	v_mov_b32_e32 v98, v116
	v_mov_b32_e32 v99, v116
	v_mov_b32_e32 v108, v116
	v_mov_b32_e32 v109, v116
	v_mov_b32_e32 v110, v116
	v_mov_b32_e32 v111, v116
	v_mov_b32_e32 v112, v116
	v_mov_b32_e32 v113, v116
	v_mov_b32_e32 v114, v116
	v_mov_b32_e32 v115, v116
	v_mov_b32_e32 v120, v116
	v_mov_b32_e32 v121, v116
	v_mov_b32_e32 v122, v116
	v_mov_b32_e32 v123, v116
	v_mov_b32_e32 v132, v116
	v_mov_b32_e32 v133, v116
	v_mov_b32_e32 v134, v116
	v_mov_b32_e32 v135, v116
	v_mov_b32_e32 v136, v116
	v_mov_b32_e32 v137, v116
	v_mov_b32_e32 v138, v116
	v_mov_b32_e32 v139, v116
	v_mov_b32_e32 v144, v116
	v_mov_b32_e32 v145, v116
	v_mov_b32_e32 v146, v116
	v_mov_b32_e32 v147, v116
	v_mov_b32_e32 v156, v116
	v_mov_b32_e32 v157, v116
	v_mov_b32_e32 v158, v116
	v_mov_b32_e32 v159, v116
	v_mov_b32_e32 v164, v116
	v_mov_b32_e32 v165, v116
	v_mov_b32_e32 v166, v116
	v_mov_b32_e32 v167, v116
	v_mov_b32_e32 v168, v116
	v_mov_b32_e32 v169, v116
	v_mov_b32_e32 v170, v116
	v_mov_b32_e32 v171, v116
	v_mov_b32_e32 v172, v116
	v_mov_b32_e32 v173, v116
	v_mov_b32_e32 v174, v116
	v_mov_b32_e32 v175, v116
	v_readlane_b32 s98, v253, 3
	v_readlane_b32 s99, v253, 4
	v_and_b32_e32 v224, 15, v188
	v_bfe_u32 v225, v188, 4, 2
	v_lshrrev_b32_e32 v226, 2, v224
	v_sub_u32_e32 v226, 0, v226
	v_and_b32_e32 v226, 3, v226
	v_xor_b32_e32 v225, v225, v226
	v_lshlrev_b32_e32 v225, 4, v225
	v_lshl_or_b32 v225, v224, 6, v225
	v_bfe_u32 v226, v188, 7, 1
	v_lshl_or_b32 v185, v226, 13, v225
	v_bfe_u32 v226, v188, 6, 1
	v_lshl_or_b32 v184, v226, 12, v225
	v_add_u32_e32 v184, 0x4000, v184
	v_lshrrev_b32_e32 v224, 3, v188
	v_bfe_u32 v225, v188, 2, 1
	v_lshrrev_b32_e32 v226, 2, v224
	v_sub_u32_e32 v226, 0, v226
	v_and_b32_e32 v226, 3, v226
	v_and_b32_e32 v227, 3, v188
	v_xor_b32_e32 v226, v227, v226
	v_lshlrev_b32_e32 v226, 4, v226
	v_xor_b32_e32 v224, v224, v225
	v_lshl_or_b32 v226, v224, 6, v226
	v_mul_u32_u24_e32 v225, 0x6000, v225
	v_add_u32_e32 v183, v225, v226
	s_mov_b32 m0, 0
	s_sub_u32 vcc_lo, s30, s98
	v_add_u32_e32 v186, vcc_lo, v178
	v_add_u32_e32 v187, vcc_lo, v180
	s_barrier
	s_waitcnt vmcnt(0)
	ds_write_b128 v183, v[160:163]
	ds_write_b128 v183, v[152:155] offset:2048
	ds_write_b128 v183, v[148:151] offset:4096
	ds_write_b128 v183, v[128:131] offset:6144
	ds_write_b128 v183, v[124:127] offset:8192
	ds_write_b128 v183, v[104:107] offset:10240
	ds_write_b128 v183, v[100:103] offset:12288
	ds_write_b128 v183, v[84:87] offset:14336
	ds_write_b128 v183, v[140:143] offset:16384
	ds_write_b128 v183, v[76:79] offset:18432
	ds_write_b128 v183, v[64:67] offset:20480
	ds_write_b128 v183, v[56:59] offset:22528
	v_cmp_gt_u32_e32 vcc, 0x6000, v183
	v_add_u32_e32 v182, 0xc000, v183
	v_add_u32_e32 v183, 0xffffa000, v183
	s_nop 0
	v_cndmask_b32_e32 v183, v183, v182, vcc
	v_add_u32_e32 v160, s26, v186
	global_load_dwordx4 v[160:163], v160, s[98:99] offset:128
	v_add_u32_e32 v152, s27, v186
	global_load_dwordx4 v[152:155], v152, s[98:99] offset:128
	v_add_u32_e32 v148, s20, v186
	global_load_dwordx4 v[148:151], v148, s[98:99] offset:128
	v_add_u32_e32 v128, s21, v186
	global_load_dwordx4 v[128:131], v128, s[98:99] offset:128
	v_add_u32_e32 v124, s56, v186
	global_load_dwordx4 v[124:127], v124, s[98:99] offset:128
	v_add_u32_e32 v104, s57, v186
	global_load_dwordx4 v[104:107], v104, s[98:99] offset:128
	v_add_u32_e32 v100, s24, v186
	global_load_dwordx4 v[100:103], v100, s[98:99] offset:128
	v_add_u32_e32 v84, s96, v186
	global_load_dwordx4 v[84:87], v84, s[98:99] offset:128
	v_add_u32_e32 v140, 0x1800000, v187
	global_load_dwordx4 v[140:143], v140, s[98:99] offset:128
	v_add_u32_e32 v76, 0x1810000, v187
	global_load_dwordx4 v[76:79], v76, s[98:99] offset:128
	v_add_u32_e32 v64, 0x1820000, v187
	global_load_dwordx4 v[64:67], v64, s[98:99] offset:128
	v_add_u32_e32 v56, 0x1830000, v187
	global_load_dwordx4 v[56:59], v56, s[98:99] offset:128
	s_add_u32 s30, s30, 0x80
	s_addc_u32 s31, s31, 0
.LBB0_487:
	s_waitcnt lgkmcnt(0)
	s_barrier
	ds_read_b128 v[224:227], v184
	ds_read_b128 v[228:231], v184 offset:1024
	ds_read_b128 v[232:235], v184 offset:2048
	ds_read_b128 v[236:239], v184 offset:3072
	ds_read_b128 v[190:193], v185
	ds_read_b128 v[194:197], v185 offset:1024
	ds_read_b128 v[198:201], v185 offset:2048
	ds_read_b128 v[204:207], v185 offset:3072
	ds_read_b128 v[208:211], v185 offset:4096
	ds_read_b128 v[212:215], v185 offset:5120
	ds_read_b128 v[216:219], v185 offset:6144
	ds_read_b128 v[220:223], v185 offset:7168
	s_movk_i32 vcc_lo, 0x6000
	s_cmp_eq_u32 m0, 2
	s_cselect_b32 vcc_lo, 0xffff4000, vcc_lo
	s_add_u32 m0, m0, 1
	s_cmp_eq_u32 m0, 3
	s_cselect_b32 m0, 0, m0
	v_add_u32_e32 v185, vcc_lo, v185
	v_add_u32_e32 v184, vcc_lo, v184
	v_xor_b32_e32 v185, 64, v185
	v_xor_b32_e32 v184, 64, v184
	s_waitcnt lgkmcnt(7)
	v_mfma_f32_16x16x32_bf16 v[172:175], v[224:227], v[190:193], v[172:175]
	v_mfma_f32_16x16x32_bf16 v[168:171], v[228:231], v[190:193], v[168:171]
	v_mfma_f32_16x16x32_bf16 v[164:167], v[232:235], v[190:193], v[164:167]
	v_mfma_f32_16x16x32_bf16 v[156:159], v[236:239], v[190:193], v[156:159]
	ds_read_b128 v[190:193], v185
	s_waitcnt lgkmcnt(7)
	v_mfma_f32_16x16x32_bf16 v[144:147], v[224:227], v[194:197], v[144:147]
	v_mfma_f32_16x16x32_bf16 v[136:139], v[228:231], v[194:197], v[136:139]
	v_mfma_f32_16x16x32_bf16 v[132:135], v[232:235], v[194:197], v[132:135]
	v_mfma_f32_16x16x32_bf16 v[120:123], v[236:239], v[194:197], v[120:123]
	ds_read_b128 v[194:197], v185 offset:1024
	s_waitcnt lgkmcnt(7)
	v_mfma_f32_16x16x32_bf16 v[112:115], v[224:227], v[198:201], v[112:115]
	v_mfma_f32_16x16x32_bf16 v[108:111], v[228:231], v[198:201], v[108:111]
	v_mfma_f32_16x16x32_bf16 v[96:99], v[232:235], v[198:201], v[96:99]
	v_mfma_f32_16x16x32_bf16 v[92:95], v[236:239], v[198:201], v[92:95]
	ds_read_b128 v[198:201], v185 offset:2048
	s_waitcnt lgkmcnt(7)
	v_mfma_f32_16x16x32_bf16 v[88:91], v[224:227], v[204:207], v[88:91]
	v_mfma_f32_16x16x32_bf16 v[80:83], v[228:231], v[204:207], v[80:83]
	v_mfma_f32_16x16x32_bf16 v[72:75], v[232:235], v[204:207], v[72:75]
	v_mfma_f32_16x16x32_bf16 v[68:71], v[236:239], v[204:207], v[68:71]
	ds_read_b128 v[204:207], v185 offset:3072
	s_waitcnt lgkmcnt(7)
	v_mfma_f32_16x16x32_bf16 v[60:63], v[224:227], v[208:211], v[60:63]
	v_mfma_f32_16x16x32_bf16 v[52:55], v[228:231], v[208:211], v[52:55]
	v_mfma_f32_16x16x32_bf16 v[48:51], v[232:235], v[208:211], v[48:51]
	v_mfma_f32_16x16x32_bf16 v[44:47], v[236:239], v[208:211], v[44:47]
	ds_read_b128 v[208:211], v185 offset:4096
	s_waitcnt lgkmcnt(7)
	v_mfma_f32_16x16x32_bf16 v[40:43], v[224:227], v[212:215], v[40:43]
	v_mfma_f32_16x16x32_bf16 v[36:39], v[228:231], v[212:215], v[36:39]
	v_mfma_f32_16x16x32_bf16 v[32:35], v[232:235], v[212:215], v[32:35]
	v_mfma_f32_16x16x32_bf16 v[28:31], v[236:239], v[212:215], v[28:31]
	ds_read_b128 v[212:215], v185 offset:5120
	s_waitcnt lgkmcnt(7)
	v_mfma_f32_16x16x32_bf16 v[24:27], v[224:227], v[216:219], v[24:27]
	v_mfma_f32_16x16x32_bf16 v[20:23], v[228:231], v[216:219], v[20:23]
	v_mfma_f32_16x16x32_bf16 v[16:19], v[232:235], v[216:219], v[16:19]
	v_mfma_f32_16x16x32_bf16 v[12:15], v[236:239], v[216:219], v[12:15]
	ds_read_b128 v[216:219], v185 offset:6144
	s_waitcnt lgkmcnt(7)
	v_mfma_f32_16x16x32_bf16 v[8:11], v[224:227], v[220:223], v[8:11]
	v_mfma_f32_16x16x32_bf16 v[4:7], v[228:231], v[220:223], v[4:7]
	v_mfma_f32_16x16x32_bf16 v[0:3], v[232:235], v[220:223], v[0:3]
	v_mfma_f32_16x16x32_bf16 v[116:119], v[236:239], v[220:223], v[116:119]
	ds_read_b128 v[220:223], v185 offset:7168
	ds_read_b128 v[224:227], v184
	ds_read_b128 v[228:231], v184 offset:1024
	ds_read_b128 v[232:235], v184 offset:2048
	ds_read_b128 v[236:239], v184 offset:3072
	s_movk_i32 vcc_lo, 0x6000
	s_cmp_eq_u32 m0, 2
	s_cselect_b32 vcc_lo, 0xffff4000, vcc_lo
	s_add_u32 m0, m0, 1
	s_cmp_eq_u32 m0, 3
	s_cselect_b32 m0, 0, m0
	v_add_u32_e32 v185, vcc_lo, v185
	v_add_u32_e32 v184, vcc_lo, v184
	v_xor_b32_e32 v185, 64, v185
	v_xor_b32_e32 v184, 64, v184
	s_sub_u32 vcc_lo, s30, s98
	v_add_u32_e32 v186, vcc_lo, v178
	v_add_u32_e32 v187, vcc_lo, v180
	s_barrier
	s_waitcnt lgkmcnt(0)
	v_mfma_f32_16x16x32_bf16 v[172:175], v[224:227], v[190:193], v[172:175]
	v_mfma_f32_16x16x32_bf16 v[168:171], v[228:231], v[190:193], v[168:171]
	v_mfma_f32_16x16x32_bf16 v[164:167], v[232:235], v[190:193], v[164:167]
	v_mfma_f32_16x16x32_bf16 v[156:159], v[236:239], v[190:193], v[156:159]
	s_waitcnt vmcnt(11)
	ds_write_b128 v183, v[160:163]
	v_add_u32_e32 v160, s26, v186
	global_load_dwordx4 v[160:163], v160, s[98:99] offset:128
	s_waitcnt vmcnt(11)
	ds_write_b128 v183, v[152:155] offset:2048
	v_add_u32_e32 v152, s27, v186
	global_load_dwordx4 v[152:155], v152, s[98:99] offset:128
	v_mfma_f32_16x16x32_bf16 v[144:147], v[224:227], v[194:197], v[144:147]
	v_mfma_f32_16x16x32_bf16 v[136:139], v[228:231], v[194:197], v[136:139]
	v_mfma_f32_16x16x32_bf16 v[132:135], v[232:235], v[194:197], v[132:135]
	v_mfma_f32_16x16x32_bf16 v[120:123], v[236:239], v[194:197], v[120:123]
	s_waitcnt vmcnt(11)
	ds_write_b128 v183, v[148:151] offset:4096
	v_add_u32_e32 v148, s20, v186
	global_load_dwordx4 v[148:151], v148, s[98:99] offset:128
	v_mfma_f32_16x16x32_bf16 v[112:115], v[224:227], v[198:201], v[112:115]
	v_mfma_f32_16x16x32_bf16 v[108:111], v[228:231], v[198:201], v[108:111]
	v_mfma_f32_16x16x32_bf16 v[96:99], v[232:235], v[198:201], v[96:99]
	v_mfma_f32_16x16x32_bf16 v[92:95], v[236:239], v[198:201], v[92:95]
	s_waitcnt vmcnt(11)
	ds_write_b128 v183, v[128:131] offset:6144
	v_add_u32_e32 v128, s21, v186
	global_load_dwordx4 v[128:131], v128, s[98:99] offset:128
	s_waitcnt vmcnt(11)
	ds_write_b128 v183, v[124:127] offset:8192
	v_add_u32_e32 v124, s56, v186
	global_load_dwordx4 v[124:127], v124, s[98:99] offset:128
	v_mfma_f32_16x16x32_bf16 v[88:91], v[224:227], v[204:207], v[88:91]
	v_mfma_f32_16x16x32_bf16 v[80:83], v[228:231], v[204:207], v[80:83]
	v_mfma_f32_16x16x32_bf16 v[72:75], v[232:235], v[204:207], v[72:75]
	v_mfma_f32_16x16x32_bf16 v[68:71], v[236:239], v[204:207], v[68:71]
	s_waitcnt vmcnt(11)
	ds_write_b128 v183, v[104:107] offset:10240
	v_add_u32_e32 v104, s57, v186
	global_load_dwordx4 v[104:107], v104, s[98:99] offset:128
	v_mfma_f32_16x16x32_bf16 v[60:63], v[224:227], v[208:211], v[60:63]
	v_mfma_f32_16x16x32_bf16 v[52:55], v[228:231], v[208:211], v[52:55]
	v_mfma_f32_16x16x32_bf16 v[48:51], v[232:235], v[208:211], v[48:51]
	v_mfma_f32_16x16x32_bf16 v[44:47], v[236:239], v[208:211], v[44:47]
	s_waitcnt vmcnt(11)
	ds_write_b128 v183, v[100:103] offset:12288
	v_add_u32_e32 v100, s24, v186
	global_load_dwordx4 v[100:103], v100, s[98:99] offset:128
	s_waitcnt vmcnt(11)
	ds_write_b128 v183, v[84:87] offset:14336
	v_add_u32_e32 v84, s96, v186
	global_load_dwordx4 v[84:87], v84, s[98:99] offset:128
	v_mfma_f32_16x16x32_bf16 v[40:43], v[224:227], v[212:215], v[40:43]
	v_mfma_f32_16x16x32_bf16 v[36:39], v[228:231], v[212:215], v[36:39]
	v_mfma_f32_16x16x32_bf16 v[32:35], v[232:235], v[212:215], v[32:35]
	v_mfma_f32_16x16x32_bf16 v[28:31], v[236:239], v[212:215], v[28:31]
	s_waitcnt vmcnt(11)
	ds_write_b128 v183, v[140:143] offset:16384
	v_add_u32_e32 v140, 0x1800000, v187
	global_load_dwordx4 v[140:143], v140, s[98:99] offset:128
	v_mfma_f32_16x16x32_bf16 v[24:27], v[224:227], v[216:219], v[24:27]
	v_mfma_f32_16x16x32_bf16 v[20:23], v[228:231], v[216:219], v[20:23]
	v_mfma_f32_16x16x32_bf16 v[16:19], v[232:235], v[216:219], v[16:19]
	v_mfma_f32_16x16x32_bf16 v[12:15], v[236:239], v[216:219], v[12:15]
	s_waitcnt vmcnt(11)
	ds_write_b128 v183, v[76:79] offset:18432
	v_add_u32_e32 v76, 0x1810000, v187
	global_load_dwordx4 v[76:79], v76, s[98:99] offset:128
	s_waitcnt vmcnt(11)
	ds_write_b128 v183, v[64:67] offset:20480
	v_add_u32_e32 v64, 0x1820000, v187
	global_load_dwordx4 v[64:67], v64, s[98:99] offset:128
	v_mfma_f32_16x16x32_bf16 v[8:11], v[224:227], v[220:223], v[8:11]
	v_mfma_f32_16x16x32_bf16 v[4:7], v[228:231], v[220:223], v[4:7]
	v_mfma_f32_16x16x32_bf16 v[0:3], v[232:235], v[220:223], v[0:3]
	v_mfma_f32_16x16x32_bf16 v[116:119], v[236:239], v[220:223], v[116:119]
	s_waitcnt vmcnt(11)
	ds_write_b128 v183, v[56:59] offset:22528
	v_add_u32_e32 v56, 0x1830000, v187
	global_load_dwordx4 v[56:59], v56, s[98:99] offset:128
	v_cmp_gt_u32_e32 vcc, 0x6000, v183
	v_add_u32_e32 v182, 0xc000, v183
	v_add_u32_e32 v183, 0xffffa000, v183
	s_nop 0
	v_cndmask_b32_e32 v183, v183, v182, vcc
	s_add_u32 s30, s30, 0x80
	s_addc_u32 s31, s31, 0
	s_cmpk_lg_i32 s30, 0x780
	s_cbranch_scc1 .LBB0_487
	s_waitcnt lgkmcnt(0)
	s_barrier
	ds_read_b128 v[224:227], v184
	ds_read_b128 v[228:231], v184 offset:1024
	ds_read_b128 v[232:235], v184 offset:2048
	ds_read_b128 v[236:239], v184 offset:3072
	ds_read_b128 v[190:193], v185
	ds_read_b128 v[194:197], v185 offset:1024
	ds_read_b128 v[198:201], v185 offset:2048
	ds_read_b128 v[204:207], v185 offset:3072
	ds_read_b128 v[208:211], v185 offset:4096
	ds_read_b128 v[212:215], v185 offset:5120
	ds_read_b128 v[216:219], v185 offset:6144
	ds_read_b128 v[220:223], v185 offset:7168
	s_movk_i32 vcc_lo, 0x6000
	s_cmp_eq_u32 m0, 2
	s_cselect_b32 vcc_lo, 0xffff4000, vcc_lo
	s_add_u32 m0, m0, 1
	s_cmp_eq_u32 m0, 3
	s_cselect_b32 m0, 0, m0
	v_add_u32_e32 v185, vcc_lo, v185
	v_add_u32_e32 v184, vcc_lo, v184
	v_xor_b32_e32 v185, 64, v185
	v_xor_b32_e32 v184, 64, v184
	s_waitcnt lgkmcnt(7)
	v_mfma_f32_16x16x32_bf16 v[172:175], v[224:227], v[190:193], v[172:175]
	v_mfma_f32_16x16x32_bf16 v[168:171], v[228:231], v[190:193], v[168:171]
	v_mfma_f32_16x16x32_bf16 v[164:167], v[232:235], v[190:193], v[164:167]
	v_mfma_f32_16x16x32_bf16 v[156:159], v[236:239], v[190:193], v[156:159]
	ds_read_b128 v[190:193], v185
	s_waitcnt lgkmcnt(7)
	v_mfma_f32_16x16x32_bf16 v[144:147], v[224:227], v[194:197], v[144:147]
	v_mfma_f32_16x16x32_bf16 v[136:139], v[228:231], v[194:197], v[136:139]
	v_mfma_f32_16x16x32_bf16 v[132:135], v[232:235], v[194:197], v[132:135]
	v_mfma_f32_16x16x32_bf16 v[120:123], v[236:239], v[194:197], v[120:123]
	ds_read_b128 v[194:197], v185 offset:1024
	s_waitcnt lgkmcnt(7)
	v_mfma_f32_16x16x32_bf16 v[112:115], v[224:227], v[198:201], v[112:115]
	v_mfma_f32_16x16x32_bf16 v[108:111], v[228:231], v[198:201], v[108:111]
	v_mfma_f32_16x16x32_bf16 v[96:99], v[232:235], v[198:201], v[96:99]
	v_mfma_f32_16x16x32_bf16 v[92:95], v[236:239], v[198:201], v[92:95]
	ds_read_b128 v[198:201], v185 offset:2048
	s_waitcnt lgkmcnt(7)
	v_mfma_f32_16x16x32_bf16 v[88:91], v[224:227], v[204:207], v[88:91]
	v_mfma_f32_16x16x32_bf16 v[80:83], v[228:231], v[204:207], v[80:83]
	v_mfma_f32_16x16x32_bf16 v[72:75], v[232:235], v[204:207], v[72:75]
	v_mfma_f32_16x16x32_bf16 v[68:71], v[236:239], v[204:207], v[68:71]
	ds_read_b128 v[204:207], v185 offset:3072
	s_waitcnt lgkmcnt(7)
	v_mfma_f32_16x16x32_bf16 v[60:63], v[224:227], v[208:211], v[60:63]
	v_mfma_f32_16x16x32_bf16 v[52:55], v[228:231], v[208:211], v[52:55]
	v_mfma_f32_16x16x32_bf16 v[48:51], v[232:235], v[208:211], v[48:51]
	v_mfma_f32_16x16x32_bf16 v[44:47], v[236:239], v[208:211], v[44:47]
	ds_read_b128 v[208:211], v185 offset:4096
	s_waitcnt lgkmcnt(7)
	v_mfma_f32_16x16x32_bf16 v[40:43], v[224:227], v[212:215], v[40:43]
	v_mfma_f32_16x16x32_bf16 v[36:39], v[228:231], v[212:215], v[36:39]
	v_mfma_f32_16x16x32_bf16 v[32:35], v[232:235], v[212:215], v[32:35]
	v_mfma_f32_16x16x32_bf16 v[28:31], v[236:239], v[212:215], v[28:31]
	ds_read_b128 v[212:215], v185 offset:5120
	s_waitcnt lgkmcnt(7)
	v_mfma_f32_16x16x32_bf16 v[24:27], v[224:227], v[216:219], v[24:27]
	v_mfma_f32_16x16x32_bf16 v[20:23], v[228:231], v[216:219], v[20:23]
	v_mfma_f32_16x16x32_bf16 v[16:19], v[232:235], v[216:219], v[16:19]
	v_mfma_f32_16x16x32_bf16 v[12:15], v[236:239], v[216:219], v[12:15]
	ds_read_b128 v[216:219], v185 offset:6144
	s_waitcnt lgkmcnt(7)
	v_mfma_f32_16x16x32_bf16 v[8:11], v[224:227], v[220:223], v[8:11]
	v_mfma_f32_16x16x32_bf16 v[4:7], v[228:231], v[220:223], v[4:7]
	v_mfma_f32_16x16x32_bf16 v[0:3], v[232:235], v[220:223], v[0:3]
	v_mfma_f32_16x16x32_bf16 v[116:119], v[236:239], v[220:223], v[116:119]
	ds_read_b128 v[220:223], v185 offset:7168
	ds_read_b128 v[224:227], v184
	ds_read_b128 v[228:231], v184 offset:1024
	ds_read_b128 v[232:235], v184 offset:2048
	ds_read_b128 v[236:239], v184 offset:3072
	s_movk_i32 vcc_lo, 0x6000
	s_cmp_eq_u32 m0, 2
	s_cselect_b32 vcc_lo, 0xffff4000, vcc_lo
	s_add_u32 m0, m0, 1
	s_cmp_eq_u32 m0, 3
	s_cselect_b32 m0, 0, m0
	v_add_u32_e32 v185, vcc_lo, v185
	v_add_u32_e32 v184, vcc_lo, v184
	v_xor_b32_e32 v185, 64, v185
	v_xor_b32_e32 v184, 64, v184
	s_waitcnt lgkmcnt(0)
	v_mfma_f32_16x16x32_bf16 v[172:175], v[224:227], v[190:193], v[172:175]
	v_mfma_f32_16x16x32_bf16 v[168:171], v[228:231], v[190:193], v[168:171]
	v_mfma_f32_16x16x32_bf16 v[164:167], v[232:235], v[190:193], v[164:167]
	v_mfma_f32_16x16x32_bf16 v[156:159], v[236:239], v[190:193], v[156:159]
	v_mfma_f32_16x16x32_bf16 v[144:147], v[224:227], v[194:197], v[144:147]
	v_mfma_f32_16x16x32_bf16 v[136:139], v[228:231], v[194:197], v[136:139]
	v_mfma_f32_16x16x32_bf16 v[132:135], v[232:235], v[194:197], v[132:135]
	v_mfma_f32_16x16x32_bf16 v[120:123], v[236:239], v[194:197], v[120:123]
	v_mfma_f32_16x16x32_bf16 v[112:115], v[224:227], v[198:201], v[112:115]
	v_mfma_f32_16x16x32_bf16 v[108:111], v[228:231], v[198:201], v[108:111]
	v_mfma_f32_16x16x32_bf16 v[96:99], v[232:235], v[198:201], v[96:99]
	v_mfma_f32_16x16x32_bf16 v[92:95], v[236:239], v[198:201], v[92:95]
	v_mfma_f32_16x16x32_bf16 v[88:91], v[224:227], v[204:207], v[88:91]
	v_mfma_f32_16x16x32_bf16 v[80:83], v[228:231], v[204:207], v[80:83]
	v_mfma_f32_16x16x32_bf16 v[72:75], v[232:235], v[204:207], v[72:75]
	v_mfma_f32_16x16x32_bf16 v[68:71], v[236:239], v[204:207], v[68:71]
	v_mfma_f32_16x16x32_bf16 v[60:63], v[224:227], v[208:211], v[60:63]
	v_mfma_f32_16x16x32_bf16 v[52:55], v[228:231], v[208:211], v[52:55]
	v_mfma_f32_16x16x32_bf16 v[48:51], v[232:235], v[208:211], v[48:51]
	v_mfma_f32_16x16x32_bf16 v[44:47], v[236:239], v[208:211], v[44:47]
	v_mfma_f32_16x16x32_bf16 v[40:43], v[224:227], v[212:215], v[40:43]
	v_mfma_f32_16x16x32_bf16 v[36:39], v[228:231], v[212:215], v[36:39]
	v_mfma_f32_16x16x32_bf16 v[32:35], v[232:235], v[212:215], v[32:35]
	v_mfma_f32_16x16x32_bf16 v[28:31], v[236:239], v[212:215], v[28:31]
	v_mfma_f32_16x16x32_bf16 v[24:27], v[224:227], v[216:219], v[24:27]
	v_mfma_f32_16x16x32_bf16 v[20:23], v[228:231], v[216:219], v[20:23]
	v_mfma_f32_16x16x32_bf16 v[16:19], v[232:235], v[216:219], v[16:19]
	v_mfma_f32_16x16x32_bf16 v[12:15], v[236:239], v[216:219], v[12:15]
	v_mfma_f32_16x16x32_bf16 v[8:11], v[224:227], v[220:223], v[8:11]
	v_mfma_f32_16x16x32_bf16 v[4:7], v[228:231], v[220:223], v[4:7]
	v_mfma_f32_16x16x32_bf16 v[0:3], v[232:235], v[220:223], v[0:3]
	v_mfma_f32_16x16x32_bf16 v[116:119], v[236:239], v[220:223], v[116:119]
	v_lshrrev_b32_e32 v224, 4, v188
	v_and_b32_e32 v225, 7, v188
	v_bitop3_b32 v226, v224, v225, 3 bitop3:0x6c
	v_lshlrev_b32_e32 v227, 7, v188
	v_bfe_u32 v228, v188, 4, 2
	v_and_b32_e32 v229, 0xffffc780, v227
	v_and_b32_e32 v227, 0x2780, v227
	v_bitop3_b32 v228, v228, v225, 4 bitop3:0x36
	v_lshlrev_b32_e32 v226, 4, v226
	v_lshlrev_b32_e32 v228, 4, v228
	v_or_b32_e32 v185, v229, v226
	v_or_b32_e32 v184, v227, v226
	v_or_b32_e32 v183, v229, v228
	v_or_b32_e32 v182, v227, v228
	s_waitcnt vmcnt(0)
	s_barrier
	s_waitcnt vmcnt(11)
	ds_write_b128 v176, v[160:163]
	s_waitcnt vmcnt(10)
	ds_write_b128 v176, v[152:155] offset:4096
	s_waitcnt vmcnt(9)
	ds_write_b128 v176, v[148:151] offset:8192
	s_waitcnt vmcnt(8)
	ds_write_b128 v176, v[128:131] offset:12288
	s_waitcnt vmcnt(7)
	ds_write_b128 v176, v[124:127] offset:16384
	s_waitcnt vmcnt(6)
	ds_write_b128 v176, v[104:107] offset:20480
	s_waitcnt vmcnt(5)
	ds_write_b128 v176, v[100:103] offset:24576
	s_waitcnt vmcnt(4)
	ds_write_b128 v176, v[84:87] offset:28672
	s_waitcnt vmcnt(3)
	ds_write_b128 v176, v[140:143] offset:32768
	s_waitcnt vmcnt(2)
	ds_write_b128 v176, v[76:79] offset:36864
	s_waitcnt vmcnt(1)
	ds_write_b128 v176, v[64:67] offset:40960
	s_waitcnt vmcnt(0)
	ds_write_b128 v176, v[56:59] offset:45056
	s_waitcnt lgkmcnt(0)
	s_barrier
	ds_read_b128 v[56:59], v185
	ds_read_b128 v[64:67], v185 offset:2048
	ds_read_b128 v[76:79], v185 offset:4096
	ds_read_b128 v[84:87], v185 offset:6144
	ds_read_b128 v[100:103], v185 offset:8192
	ds_read_b128 v[104:107], v185 offset:10240
	ds_read_b128 v[124:127], v185 offset:12288
	ds_read_b128 v[128:131], v185 offset:14336
	ds_read_b128 v[140:143], v184 offset:32768
	ds_read_b128 v[148:151], v184 offset:34816
	ds_read_b128 v[152:155], v184 offset:36864
	ds_read_b128 v[160:163], v184 offset:38912
	s_waitcnt lgkmcnt(3)
	v_mfma_f32_16x16x32_bf16 v[172:175], v[140:143], v[56:59], v[172:175]
	s_waitcnt lgkmcnt(2)
	v_mfma_f32_16x16x32_bf16 v[168:171], v[148:151], v[56:59], v[168:171]
	s_waitcnt lgkmcnt(1)
	v_mfma_f32_16x16x32_bf16 v[164:167], v[152:155], v[56:59], v[164:167]
	s_waitcnt lgkmcnt(0)
	v_mfma_f32_16x16x32_bf16 v[56:59], v[160:163], v[56:59], v[156:159]
	v_mfma_f32_16x16x32_bf16 v[144:147], v[140:143], v[64:67], v[144:147]
	v_mfma_f32_16x16x32_bf16 v[136:139], v[148:151], v[64:67], v[136:139]
	v_mfma_f32_16x16x32_bf16 v[132:135], v[152:155], v[64:67], v[132:135]
	v_mfma_f32_16x16x32_bf16 v[64:67], v[160:163], v[64:67], v[120:123]
	v_mfma_f32_16x16x32_bf16 v[156:159], v[140:143], v[76:79], v[112:115]
	v_mfma_f32_16x16x32_bf16 v[178:181], v[148:151], v[76:79], v[108:111]
	v_mfma_f32_16x16x32_bf16 v[184:187], v[152:155], v[76:79], v[96:99]
	v_mfma_f32_16x16x32_bf16 v[76:79], v[160:163], v[76:79], v[92:95]
	v_mfma_f32_16x16x32_bf16 v[60:63], v[140:143], v[100:103], v[60:63]
	v_mfma_f32_16x16x32_bf16 v[52:55], v[148:151], v[100:103], v[52:55]
	v_mfma_f32_16x16x32_bf16 v[48:51], v[152:155], v[100:103], v[48:51]
	v_mfma_f32_16x16x32_bf16 v[44:47], v[160:163], v[100:103], v[44:47]
	v_mfma_f32_16x16x32_bf16 v[40:43], v[140:143], v[104:107], v[40:43]
	v_mfma_f32_16x16x32_bf16 v[36:39], v[148:151], v[104:107], v[36:39]
	v_mfma_f32_16x16x32_bf16 v[32:35], v[152:155], v[104:107], v[32:35]
	v_mfma_f32_16x16x32_bf16 v[28:31], v[160:163], v[104:107], v[28:31]
	v_mfma_f32_16x16x32_bf16 v[24:27], v[140:143], v[124:127], v[24:27]
	v_mfma_f32_16x16x32_bf16 v[20:23], v[148:151], v[124:127], v[20:23]
	v_mfma_f32_16x16x32_bf16 v[16:19], v[152:155], v[124:127], v[16:19]
	v_mfma_f32_16x16x32_bf16 v[12:15], v[160:163], v[124:127], v[12:15]
	v_mfma_f32_16x16x32_bf16 v[8:11], v[140:143], v[128:131], v[8:11]
	v_mfma_f32_16x16x32_bf16 v[4:7], v[148:151], v[128:131], v[4:7]
	v_mfma_f32_16x16x32_bf16 v[0:3], v[152:155], v[128:131], v[0:3]
	v_mfma_f32_16x16x32_bf16 v[190:193], v[140:143], v[84:87], v[88:91]
	v_mfma_f32_16x16x32_bf16 v[194:197], v[148:151], v[84:87], v[80:83]
	v_mfma_f32_16x16x32_bf16 v[198:201], v[152:155], v[84:87], v[72:75]
	v_mfma_f32_16x16x32_bf16 v[204:207], v[160:163], v[84:87], v[68:71]
	v_mfma_f32_16x16x32_bf16 v[140:143], v[160:163], v[128:131], v[116:119]
	s_nop 1
	ds_read_b128 v[68:71], v183
	ds_read_b128 v[72:75], v183 offset:2048
	ds_read_b128 v[80:83], v183 offset:4096
	ds_read_b128 v[128:131], v183 offset:6144
	ds_read_b128 v[148:151], v183 offset:8192
	ds_read_b128 v[152:155], v183 offset:10240
	ds_read_b128 v[160:163], v183 offset:12288
	ds_read_b128 v[208:211], v183 offset:14336
	ds_read_b128 v[212:215], v182 offset:32768
	ds_read_b128 v[216:219], v182 offset:34816
	ds_read_b128 v[220:223], v182 offset:36864
	ds_read_b128 v[224:227], v182 offset:38912
	s_waitcnt lgkmcnt(3)
	v_mfma_f32_16x16x32_bf16 v[124:127], v[212:215], v[68:71], v[172:175]
	s_movk_i32 s30, 0x6c0
	s_waitcnt lgkmcnt(2)
	v_mfma_f32_16x16x32_bf16 v[120:123], v[216:219], v[68:71], v[168:171]
	s_waitcnt lgkmcnt(1)
	v_mfma_f32_16x16x32_bf16 v[116:119], v[220:223], v[68:71], v[164:167]
	s_waitcnt lgkmcnt(0)
	v_mfma_f32_16x16x32_bf16 v[112:115], v[224:227], v[68:71], v[56:59]
	v_mfma_f32_16x16x32_bf16 v[108:111], v[212:215], v[72:75], v[144:147]
	v_mfma_f32_16x16x32_bf16 v[104:107], v[216:219], v[72:75], v[136:139]
	v_mfma_f32_16x16x32_bf16 v[100:103], v[220:223], v[72:75], v[132:135]
	v_mfma_f32_16x16x32_bf16 v[96:99], v[224:227], v[72:75], v[64:67]
	v_mfma_f32_16x16x32_bf16 v[92:95], v[212:215], v[80:83], v[156:159]
	v_mfma_f32_16x16x32_bf16 v[88:91], v[216:219], v[80:83], v[178:181]
	v_mfma_f32_16x16x32_bf16 v[84:87], v[220:223], v[80:83], v[184:187]
	v_mfma_f32_16x16x32_bf16 v[80:83], v[224:227], v[80:83], v[76:79]
	v_mfma_f32_16x16x32_bf16 v[76:79], v[212:215], v[128:131], v[190:193]
	v_mfma_f32_16x16x32_bf16 v[72:75], v[216:219], v[128:131], v[194:197]
	v_mfma_f32_16x16x32_bf16 v[68:71], v[220:223], v[128:131], v[198:201]
	v_mfma_f32_16x16x32_bf16 v[64:67], v[224:227], v[128:131], v[204:207]
	v_mov_b32_e32 v128, v188
	v_mov_b32_e32 v129, v188
	v_mfma_f32_16x16x32_bf16 v[60:63], v[212:215], v[148:151], v[60:63]
	s_nop 0
	v_and_or_b32 v134, v129, 64, s41
	v_mfma_f32_16x16x32_bf16 v[56:59], v[216:219], v[148:151], v[52:55]
	v_cmp_gt_i32_e32 vcc, s30, v134
	v_mfma_f32_16x16x32_bf16 v[52:55], v[220:223], v[148:151], v[48:51]
	v_mfma_f32_16x16x32_bf16 v[48:51], v[224:227], v[148:151], v[44:47]
	v_mfma_f32_16x16x32_bf16 v[44:47], v[212:215], v[152:155], v[40:43]
	v_mfma_f32_16x16x32_bf16 v[40:43], v[216:219], v[152:155], v[36:39]
	v_mfma_f32_16x16x32_bf16 v[36:39], v[220:223], v[152:155], v[32:35]
	v_mfma_f32_16x16x32_bf16 v[32:35], v[224:227], v[152:155], v[28:31]
	v_mfma_f32_16x16x32_bf16 v[28:31], v[212:215], v[160:163], v[24:27]
	v_mfma_f32_16x16x32_bf16 v[24:27], v[216:219], v[160:163], v[20:23]
	v_mfma_f32_16x16x32_bf16 v[20:23], v[220:223], v[160:163], v[16:19]
	v_mfma_f32_16x16x32_bf16 v[16:19], v[224:227], v[160:163], v[12:15]
	v_mfma_f32_16x16x32_bf16 v[12:15], v[212:215], v[208:211], v[8:11]
	v_mfma_f32_16x16x32_bf16 v[8:11], v[216:219], v[208:211], v[4:7]
	v_mfma_f32_16x16x32_bf16 v[4:7], v[220:223], v[208:211], v[0:3]
	v_mfma_f32_16x16x32_bf16 v[0:3], v[224:227], v[208:211], v[140:143]
	s_and_saveexec_b64 s[92:93], vcc
	s_cbranch_execz .LBB0_485
	v_and_b32_e32 v130, 0xffffff80, v129
	v_add_u32_e32 v183, s40, v130
	s_movk_i32 s30, 0xfff
	v_cmp_lt_i32_e64 s[48:49], s30, v183
	s_movk_i32 s30, 0x1000
	v_cmp_gt_i32_e64 s[44:45], s30, v183
	v_add_u32_e32 v130, 0xfffff000, v183
	v_bfe_u32 v141, v128, 4, 2
	s_movk_i32 s30, 0x27f
	v_ashrrev_i32_e32 v135, 10, v130
	v_ashrrev_i32_e32 v132, 8, v183
	v_cmp_lt_i32_e64 s[52:53], s30, v134
	s_movk_i32 s30, 0x280
	v_lshlrev_b32_e32 v130, 4, v141
	v_mov_b32_e32 v131, v177
	v_and_b32_e32 v140, 0x80, v129
	v_cmp_ne_u32_e64 s[50:51], s30, v134
	v_lshl_add_u64 v[138:139], s[84:85], 0, v[130:131]
	v_lshl_add_u64 v[136:137], s[82:83], 0, v[130:131]
	v_lshlrev_b32_e32 v130, 9, v132
	v_readlane_b32 s30, v255, 49
	v_and_b32_e32 v182, 15, v128
	v_and_b32_e32 v181, 0x380, v183
	v_or3_b32 v178, v130, s30, v140
	v_lshlrev_b32_e32 v130, 3, v132
	v_ashrrev_i32_e32 v131, 31, v130
	v_lshlrev_b64 v[132:133], 8, v[130:131]
	v_lshlrev_b32_e32 v130, 3, v135
	s_movk_i32 s30, 0x500
	v_bfe_u32 v129, v128, 4, 1
	v_lshrrev_b32_e32 v128, 2, v128
	v_mad_i64_i32 v[130:131], s[30:31], v130, s30, 0
	v_mov_b32_e32 v176, v134
	v_cmp_eq_u32_e64 s[40:41], 0, v129
	v_lshlrev_b32_e32 v180, 4, v129
	v_and_b32_e32 v179, 8, v128
	v_lshlrev_b32_e32 v128, 2, v141
	v_mov_b32_e32 v129, v177
	v_or_b32_e32 v132, v132, v140
	v_or_b32_e32 v130, v130, v181
	v_cmp_lt_i32_e64 s[46:47], s97, v134
	v_cmp_eq_u32_e64 s[42:43], 0, v141
	v_or_b32_e32 v140, v183, v182
	s_and_saveexec_b64 s[30:31], s[52:53]
	s_xor_b64 s[94:95], exec, s[30:31]
	s_cbranch_execz .LBB0_513
	s_and_saveexec_b64 s[30:31], s[50:51]
	s_xor_b64 s[30:31], exec, s[30:31]
	s_cbranch_execz .LBB0_492
	v_mul_f32_e32 v142, 0xbfb8aa3b, v124
	v_mul_f32_e32 v144, 0xbfb8aa3b, v120
	v_mul_f32_e32 v145, 0xbfb8aa3b, v125
	v_exp_f32_e32 v142, v142
	v_exp_f32_e32 v144, v144
	v_exp_f32_e32 v145, v145
	v_mul_f32_e32 v146, 0xbfb8aa3b, v121
	v_add_f32_e32 v142, 1.0, v142
	v_add_f32_e32 v144, 1.0, v144
	v_add_f32_e32 v145, 1.0, v145
	v_rcp_f32_e32 v142, v142
	v_rcp_f32_e32 v144, v144
	v_rcp_f32_e32 v145, v145
	v_exp_f32_e32 v146, v146
	v_mul_f32_e32 v142, v124, v142
	v_mul_f32_e32 v144, v120, v144
	v_mul_f32_e32 v145, v125, v145
	v_add_f32_e32 v120, 1.0, v146
	v_mul_f32_e32 v124, 0xbfb8aa3b, v126
	v_mul_f32_e32 v125, 0xbfb8aa3b, v122
	v_rcp_f32_e32 v120, v120
	v_exp_f32_e32 v124, v124
	v_exp_f32_e32 v125, v125
	v_ashrrev_i32_e32 v141, 31, v140
	v_mul_f32_e32 v146, v121, v120
	v_add_f32_e32 v120, 1.0, v124
	v_add_f32_e32 v121, 1.0, v125
	v_mul_f32_e32 v124, 0xbfb8aa3b, v127
	v_mul_f32_e32 v125, 0xbfb8aa3b, v123
	v_exp_f32_e32 v124, v124
	v_exp_f32_e32 v125, v125
	v_rcp_f32_e32 v120, v120
	v_rcp_f32_e32 v121, v121
	v_add_f32_e32 v124, 1.0, v124
	v_add_f32_e32 v125, 1.0, v125
	v_rcp_f32_e32 v124, v124
	v_rcp_f32_e32 v125, v125
	v_lshlrev_b64 v[140:141], 11, v[140:141]
	v_cmp_lt_i32_e32 vcc, v189, v202
	v_mul_f32_e32 v126, v126, v120
	v_mul_f32_e32 v122, v122, v121
	v_cndmask_b32_e32 v143, v203, v189, vcc
	v_mul_f32_e32 v127, v127, v124
	v_mul_f32_e32 v123, v123, v125
	v_lshl_add_u64 v[120:121], s[34:35], 0, v[140:141]
	v_lshlrev_b32_e32 v143, 2, v143
	v_lshl_add_u64 v[124:125], v[176:177], 1, v[120:121]
	v_cndmask_b32_e64 v120, v142, v144, s[40:41]
	v_cndmask_b32_e64 v121, v145, v146, s[40:41]
	v_cndmask_b32_e64 v140, v126, v122, s[40:41]
	v_cndmask_b32_e64 v141, v127, v123, s[40:41]
	ds_bpermute_b32 v120, v143, v120
	ds_bpermute_b32 v121, v143, v121
	ds_bpermute_b32 v140, v143, v140
	ds_bpermute_b32 v141, v143, v141
	s_mov_b32 s58, 0x96ff000
	s_waitcnt lgkmcnt(3)
	v_cndmask_b32_e64 v142, v120, v142, s[40:41]
	v_cndmask_b32_e64 v144, v144, v120, s[40:41]
	s_waitcnt lgkmcnt(2)
	v_cndmask_b32_e64 v120, v121, v145, s[40:41]
	v_cndmask_b32_e64 v145, v146, v121, s[40:41]
	s_waitcnt lgkmcnt(1)
	v_cndmask_b32_e64 v121, v140, v126, s[40:41]
	v_cndmask_b32_e64 v126, v122, v140, s[40:41]
	s_waitcnt lgkmcnt(0)
	v_cndmask_b32_e64 v123, v123, v141, s[40:41]
	v_cndmask_b32_e64 v122, v141, v127, s[40:41]
	v_cvt_pk_bf16_f32 v123, v126, v123
	v_lshlrev_b32_e32 v126, 1, v180
	v_mov_b32_e32 v127, v177
	v_lshlrev_b32_e32 v140, 1, v179
	v_mov_b32_e32 v141, v177
	v_lshl_add_u64 v[124:125], v[124:125], 0, v[126:127]
	v_lshl_add_u64 v[124:125], v[124:125], 0, v[140:141]
	v_add_co_u32_e32 v124, vcc, s58, v124
	v_cvt_pk_bf16_f32 v120, v142, v120
	v_cvt_pk_bf16_f32 v121, v121, v122
	v_cvt_pk_bf16_f32 v122, v144, v145
	v_addc_co_u32_e32 v125, vcc, 0, v125, vcc
	v_mul_f32_e32 v126, 0xbfb8aa3b, v116
	global_store_dwordx4 v[124:125], v[120:123], off offset:2688
	v_exp_f32_e32 v126, v126
	s_nop 0
	v_mul_f32_e32 v121, 0xbfb8aa3b, v112
	v_mul_f32_e32 v122, 0xbfb8aa3b, v117
	v_exp_f32_e32 v121, v121
	v_exp_f32_e32 v122, v122
	v_add_f32_e32 v120, 1.0, v126
	v_mul_f32_e32 v123, 0xbfb8aa3b, v113
	v_add_f32_e32 v121, 1.0, v121
	v_add_f32_e32 v122, 1.0, v122
	v_rcp_f32_e32 v120, v120
	v_rcp_f32_e32 v121, v121
	v_rcp_f32_e32 v122, v122
	v_exp_f32_e32 v123, v123
	v_mul_f32_e32 v116, v116, v120
	v_mul_f32_e32 v112, v112, v121
	v_mul_f32_e32 v117, v117, v122
	v_add_f32_e32 v120, 1.0, v123
	v_mul_f32_e32 v121, 0xbfb8aa3b, v118
	v_mul_f32_e32 v122, 0xbfb8aa3b, v114
	v_rcp_f32_e32 v120, v120
	v_exp_f32_e32 v121, v121
	v_exp_f32_e32 v122, v122
	v_mul_f32_e32 v123, 0xbfb8aa3b, v115
	v_mul_f32_e32 v113, v113, v120
	v_add_f32_e32 v120, 1.0, v121
	v_add_f32_e32 v121, 1.0, v122
	v_mul_f32_e32 v122, 0xbfb8aa3b, v119
	v_exp_f32_e32 v122, v122
	v_exp_f32_e32 v123, v123
	v_rcp_f32_e32 v120, v120
	v_rcp_f32_e32 v121, v121
	v_add_f32_e32 v122, 1.0, v122
	v_add_f32_e32 v123, 1.0, v123
	v_rcp_f32_e32 v122, v122
	v_rcp_f32_e32 v123, v123
	v_mul_f32_e32 v118, v118, v120
	v_mul_f32_e32 v114, v114, v121
	v_mul_f32_e32 v119, v119, v122
	v_mul_f32_e32 v115, v115, v123
	v_cndmask_b32_e64 v120, v116, v112, s[40:41]
	v_cndmask_b32_e64 v121, v117, v113, s[40:41]
	v_cndmask_b32_e64 v122, v118, v114, s[40:41]
	v_cndmask_b32_e64 v123, v119, v115, s[40:41]
	ds_bpermute_b32 v120, v143, v120
	ds_bpermute_b32 v121, v143, v121
	ds_bpermute_b32 v122, v143, v122
	ds_bpermute_b32 v123, v143, v123
	s_waitcnt lgkmcnt(3)
	v_cndmask_b32_e64 v116, v120, v116, s[40:41]
	v_cndmask_b32_e64 v120, v112, v120, s[40:41]
	s_waitcnt lgkmcnt(2)
	v_cndmask_b32_e64 v112, v121, v117, s[40:41]
	v_cndmask_b32_e64 v117, v113, v121, s[40:41]
	s_waitcnt lgkmcnt(1)
	v_cndmask_b32_e64 v113, v122, v118, s[40:41]
	v_cndmask_b32_e64 v118, v114, v122, s[40:41]
	s_waitcnt lgkmcnt(0)
	v_cndmask_b32_e64 v114, v123, v119, s[40:41]
	v_cndmask_b32_e64 v115, v115, v123, s[40:41]
	v_cvt_pk_bf16_f32 v112, v116, v112
	v_cvt_pk_bf16_f32 v113, v113, v114
	v_cvt_pk_bf16_f32 v114, v120, v117
	v_cvt_pk_bf16_f32 v115, v118, v115
	global_store_dwordx4 v[124:125], v[112:115], off offset:2752

.LBB0_801:
	s_waitcnt lgkmcnt(0)
	s_ashr_i32 s6, s8, 3
	s_lshl_b32 s9, s6, 1
	s_and_b32 s7, s6, -16
	s_and_b32 s9, s9, 14
	s_or_b32 s7, s9, s7
	s_bfe_u32 s9, s6, 0x10003
	s_or_b32 s7, s7, s9
	s_cmp_lt_i32 s6, 0
	s_cselect_b32 s6, s7, s6
	s_lshl_b32 s7, s8, 5
	s_and_b32 s7, s7, 0xe0
	s_add_i32 s6, s6, s7
	s_ashr_i32 s7, s6, 31
	s_lshr_b32 s7, s7, 27
	s_add_i32 s7, s6, s7
	s_and_b32 s9, s7, 0xffffffe0
	s_sub_i32 s6, s6, s9
	s_ashr_i32 s9, s6, 31
	s_lshr_b32 s9, s9, 29
	s_add_i32 s9, s6, s9
	s_ashr_i32 s10, s9, 3
	s_lshl_b32 s7, s7, 5
	s_and_b32 s7, s7, 0xfffffc00
	s_lshl_b32 s9, s10, 8
	s_add_i32 s9, s9, s7
	s_lshl_b32 s7, s10, 10
	s_lshl_b32 s6, s6, 7
	v_mov_b32_e32 v6, v188
	s_sub_i32 s10, s6, s7
	s_mov_b32 s11, 0x30000
	v_ashrrev_i32_e32 v7, 3, v6
	v_lshlrev_b32_e32 v4, 4, v6
	v_and_b32_e32 v176, 0x70, v4
	v_add_u32_e32 v4, s10, v7
	v_ashrrev_i32_e32 v5, 31, v4
	v_add_u32_e32 v0, s9, v7
	v_lshlrev_b64 v[4:5], 11, v[4:5]
	v_ashrrev_i32_e32 v1, 31, v0
	v_lshl_add_u64 v[4:5], s[2:3], 0, v[4:5]
	v_xor_b32_e32 v8, v7, v6
	v_lshlrev_b64 v[0:1], 11, v[0:1]
	v_lshl_add_u64 v[178:179], v[4:5], 0, v[176:177]
	v_lshlrev_b32_e32 v4, 4, v8
	v_lshl_add_u64 v[2:3], s[0:1], 0, v[0:1]
	v_and_b32_e32 v4, 0x70, v4
	v_lshl_add_u64 v[2:3], v[2:3], 0, v[176:177]
	v_lshl_or_b32 v176, v7, 7, v4
	v_lshrrev_b32_e32 v4, 4, v6
	v_and_b32_e32 v15, 7, v6
	v_bitop3_b32 v20, v4, v15, 3 bitop3:0x6c
	v_add_co_u32_e32 v4, vcc, s11, v178
	v_lshlrev_b32_e32 v12, 7, v6
	s_nop 0
	v_addc_co_u32_e32 v5, vcc, 0, v179, vcc
	v_bfe_u32 v14, v6, 4, 2
	v_add_co_u32_e32 v6, vcc, s12, v178
	s_mov_b32 s6, 0x70000
	s_nop 0
	v_addc_co_u32_e32 v7, vcc, 0, v179, vcc
	global_load_dwordx4 v[8:11], v[4:5], off
	global_load_dwordx4 v[16:19], v[6:7], off
	v_add_co_u32_e32 v4, vcc, s13, v178
	v_and_b32_e32 v13, 0xffffc780, v12
	s_nop 0
	v_addc_co_u32_e32 v5, vcc, 0, v179, vcc
	v_add_co_u32_e32 v6, vcc, s6, v2
	s_mov_b32 s6, 0x60000
	s_nop 0
	v_addc_co_u32_e32 v7, vcc, 0, v3, vcc
	global_load_dwordx4 v[32:35], v[4:5], off
	global_load_dwordx4 v[40:43], v[6:7], off
	v_add_co_u32_e32 v4, vcc, s6, v2
	s_mov_b32 s6, 0x50000
	s_nop 0
	v_addc_co_u32_e32 v5, vcc, 0, v3, vcc
	v_add_co_u32_e32 v6, vcc, s6, v2
	v_and_b32_e32 v12, 0x2780, v12
	s_nop 0
	v_addc_co_u32_e32 v7, vcc, 0, v3, vcc
	global_load_dwordx4 v[60:63], v[4:5], off
	global_load_dwordx4 v[68:71], v[6:7], off
	v_add_co_u32_e32 v4, vcc, 0x40000, v2
	v_bitop3_b32 v14, v14, v15, 4 bitop3:0x36
	s_nop 0
	v_addc_co_u32_e32 v5, vcc, 0, v3, vcc
	v_add_co_u32_e32 v6, vcc, s11, v2
	v_lshl_or_b32 v0, v15, 4, v0
	s_nop 0
	v_addc_co_u32_e32 v7, vcc, 0, v3, vcc
	global_load_dwordx4 v[80:83], v[4:5], off
	global_load_dwordx4 v[88:91], v[6:7], off
	v_add_co_u32_e32 v4, vcc, s12, v2
	v_mov_b32_e32 v140, 0
	s_nop 0
	v_addc_co_u32_e32 v5, vcc, 0, v3, vcc
	v_add_co_u32_e32 v6, vcc, 0x10000, v2
	v_lshl_add_u64 v[180:181], s[34:35], 0, v[0:1]
	s_nop 0
	v_addc_co_u32_e32 v7, vcc, 0, v3, vcc
	global_load_dwordx4 v[104:107], v[4:5], off
	global_load_dwordx4 v[112:115], v[6:7], off
	global_load_dwordx4 v[56:59], v[178:179], off
	global_load_dwordx4 v[116:119], v[2:3], off
	v_lshlrev_b32_e32 v2, 4, v20
	v_or_b32_e32 v185, v13, v2
	v_or_b32_e32 v184, v12, v2
	v_lshlrev_b32_e32 v2, 4, v14
	v_or_b32_e32 v183, v13, v2
	v_or_b32_e32 v182, v12, v2
	s_mov_b64 s[6:7], 0
	v_mov_b32_e32 v141, v140
	v_mov_b32_e32 v142, v140
	v_mov_b32_e32 v143, v140
	v_mov_b32_e32 v0, v140
	v_mov_b32_e32 v1, v140
	v_mov_b32_e32 v2, v140
	v_mov_b32_e32 v3, v140
	v_mov_b32_e32 v4, v140
	v_mov_b32_e32 v5, v140
	v_mov_b32_e32 v6, v140
	v_mov_b32_e32 v7, v140
	v_mov_b32_e32 v12, v140
	v_mov_b32_e32 v13, v140
	v_mov_b32_e32 v14, v140
	v_mov_b32_e32 v15, v140
	v_mov_b32_e32 v20, v140
	v_mov_b32_e32 v21, v140
	v_mov_b32_e32 v22, v140
	v_mov_b32_e32 v23, v140
	v_mov_b32_e32 v24, v140
	v_mov_b32_e32 v25, v140
	v_mov_b32_e32 v26, v140
	v_mov_b32_e32 v27, v140
	v_mov_b32_e32 v28, v140
	v_mov_b32_e32 v29, v140
	v_mov_b32_e32 v30, v140
	v_mov_b32_e32 v31, v140
	v_mov_b32_e32 v36, v140
	v_mov_b32_e32 v37, v140
	v_mov_b32_e32 v38, v140
	v_mov_b32_e32 v39, v140
	v_mov_b32_e32 v44, v140
	v_mov_b32_e32 v45, v140
	v_mov_b32_e32 v46, v140
	v_mov_b32_e32 v47, v140
	v_mov_b32_e32 v48, v140
	v_mov_b32_e32 v49, v140
	v_mov_b32_e32 v50, v140
	v_mov_b32_e32 v51, v140
	v_mov_b32_e32 v52, v140
	v_mov_b32_e32 v53, v140
	v_mov_b32_e32 v54, v140
	v_mov_b32_e32 v55, v140
	v_mov_b32_e32 v64, v140
	v_mov_b32_e32 v65, v140
	v_mov_b32_e32 v66, v140
	v_mov_b32_e32 v67, v140
	v_mov_b32_e32 v72, v140
	v_mov_b32_e32 v73, v140
	v_mov_b32_e32 v74, v140
	v_mov_b32_e32 v75, v140
	v_mov_b32_e32 v76, v140
	v_mov_b32_e32 v77, v140
	v_mov_b32_e32 v78, v140
	v_mov_b32_e32 v79, v140
	v_mov_b32_e32 v84, v140
	v_mov_b32_e32 v85, v140
	v_mov_b32_e32 v86, v140
	v_mov_b32_e32 v87, v140
	v_mov_b32_e32 v92, v140
	v_mov_b32_e32 v93, v140
	v_mov_b32_e32 v94, v140
	v_mov_b32_e32 v95, v140
	v_mov_b32_e32 v96, v140
	v_mov_b32_e32 v97, v140
	v_mov_b32_e32 v98, v140
	v_mov_b32_e32 v99, v140
	v_mov_b32_e32 v100, v140
	v_mov_b32_e32 v101, v140
	v_mov_b32_e32 v102, v140
	v_mov_b32_e32 v103, v140
	v_mov_b32_e32 v108, v140
	v_mov_b32_e32 v109, v140
	v_mov_b32_e32 v110, v140
	v_mov_b32_e32 v111, v140
	v_mov_b32_e32 v120, v140
	v_mov_b32_e32 v121, v140
	v_mov_b32_e32 v122, v140
	v_mov_b32_e32 v123, v140
	v_mov_b32_e32 v124, v140
	v_mov_b32_e32 v125, v140
	v_mov_b32_e32 v126, v140
	v_mov_b32_e32 v127, v140
	v_mov_b32_e32 v128, v140
	v_mov_b32_e32 v129, v140
	v_mov_b32_e32 v130, v140
	v_mov_b32_e32 v131, v140
	v_mov_b32_e32 v132, v140
	v_mov_b32_e32 v133, v140
	v_mov_b32_e32 v134, v140
	v_mov_b32_e32 v135, v140
	v_mov_b32_e32 v136, v140
	v_mov_b32_e32 v137, v140
	v_mov_b32_e32 v138, v140
	v_mov_b32_e32 v139, v140
	v_mov_b32_e32 v144, v140
	v_mov_b32_e32 v145, v140
	v_mov_b32_e32 v146, v140
	v_mov_b32_e32 v147, v140
	v_mov_b32_e32 v148, v140
	v_mov_b32_e32 v149, v140
	v_mov_b32_e32 v150, v140
	v_mov_b32_e32 v151, v140
	v_mov_b32_e32 v152, v140
	v_mov_b32_e32 v153, v140
	v_mov_b32_e32 v154, v140
	v_mov_b32_e32 v155, v140
	v_mov_b32_e32 v156, v140
	v_mov_b32_e32 v157, v140
	v_mov_b32_e32 v158, v140
	v_mov_b32_e32 v159, v140
	v_mov_b32_e32 v160, v140
	v_mov_b32_e32 v161, v140
	v_mov_b32_e32 v162, v140
	v_mov_b32_e32 v163, v140
	v_mov_b32_e32 v164, v140
	v_mov_b32_e32 v165, v140
	v_mov_b32_e32 v166, v140
	v_mov_b32_e32 v167, v140
	v_mov_b32_e32 v168, v140
	v_mov_b32_e32 v169, v140
	v_mov_b32_e32 v170, v140
	v_mov_b32_e32 v171, v140
	v_mov_b32_e32 v172, v140
	v_mov_b32_e32 v173, v140
	v_mov_b32_e32 v174, v140
	v_mov_b32_e32 v175, v140
	v_readlane_b32 s98, v253, 3
	v_readlane_b32 s99, v253, 4
	v_and_b32_e32 v224, 15, v188
	v_bfe_u32 v225, v188, 4, 2
	v_lshrrev_b32_e32 v226, 2, v224
	v_sub_u32_e32 v226, 0, v226
	v_and_b32_e32 v226, 3, v226
	v_xor_b32_e32 v225, v225, v226
	v_lshlrev_b32_e32 v225, 4, v225
	v_lshl_or_b32 v225, v224, 6, v225
	v_bfe_u32 v226, v188, 7, 1
	v_lshl_or_b32 v185, v226, 13, v225
	v_bfe_u32 v226, v188, 6, 1
	v_lshl_or_b32 v184, v226, 12, v225
	v_add_u32_e32 v184, 0x4000, v184
	v_lshrrev_b32_e32 v224, 3, v188
	v_bfe_u32 v225, v188, 2, 1
	v_lshrrev_b32_e32 v226, 2, v224
	v_sub_u32_e32 v226, 0, v226
	v_and_b32_e32 v226, 3, v226
	v_and_b32_e32 v227, 3, v188
	v_xor_b32_e32 v226, v227, v226
	v_lshlrev_b32_e32 v226, 4, v226
	v_xor_b32_e32 v224, v224, v225
	v_lshl_or_b32 v226, v224, 6, v226
	v_mul_u32_u24_e32 v225, 0x6000, v225
	v_add_u32_e32 v183, v225, v226
	s_mov_b32 m0, 0
	s_sub_u32 vcc_lo, s6, s98
	v_add_u32_e32 v186, vcc_lo, v178
	v_add_u32_e32 v187, vcc_lo, v180
	s_barrier
	s_waitcnt vmcnt(0)
	ds_write_b128 v183, v[116:119]
	ds_write_b128 v183, v[112:115] offset:2048
	ds_write_b128 v183, v[104:107] offset:4096
	ds_write_b128 v183, v[88:91] offset:6144
	ds_write_b128 v183, v[80:83] offset:8192
	ds_write_b128 v183, v[68:71] offset:10240
	ds_write_b128 v183, v[60:63] offset:12288
	ds_write_b128 v183, v[40:43] offset:14336
	ds_write_b128 v183, v[56:59] offset:16384
	ds_write_b128 v183, v[32:35] offset:18432
	ds_write_b128 v183, v[16:19] offset:20480
	ds_write_b128 v183, v[8:11] offset:22528
	v_cmp_gt_u32_e32 vcc, 0x6000, v183
	v_add_u32_e32 v182, 0xc000, v183
	v_add_u32_e32 v183, 0xffffa000, v183
	s_nop 0
	v_cndmask_b32_e32 v183, v183, v182, vcc
	v_add_u32_e32 v116, s26, v187
	global_load_dwordx4 v[116:119], v116, s[98:99] offset:128
	v_add_u32_e32 v112, s27, v187
	global_load_dwordx4 v[112:115], v112, s[98:99] offset:128
	v_add_u32_e32 v104, s20, v187
	global_load_dwordx4 v[104:107], v104, s[98:99] offset:128
	v_add_u32_e32 v88, s21, v187
	global_load_dwordx4 v[88:91], v88, s[98:99] offset:128
	v_add_u32_e32 v80, s56, v187
	global_load_dwordx4 v[80:83], v80, s[98:99] offset:128
	v_add_u32_e32 v68, s57, v187
	global_load_dwordx4 v[68:71], v68, s[98:99] offset:128
	v_add_u32_e32 v60, s24, v187
	global_load_dwordx4 v[60:63], v60, s[98:99] offset:128
	v_add_u32_e32 v40, s96, v187
	global_load_dwordx4 v[40:43], v40, s[98:99] offset:128
	v_mov_b32_e32 v56, v186
	global_load_dwordx4 v[56:59], v56, s[98:99] offset:128
	v_add_u32_e32 v32, s13, v186
	global_load_dwordx4 v[32:35], v32, s[98:99] offset:128
	v_add_u32_e32 v16, s12, v186
	global_load_dwordx4 v[16:19], v16, s[98:99] offset:128
	v_add_u32_e32 v8, s11, v186
	global_load_dwordx4 v[8:11], v8, s[98:99] offset:128
	s_add_u32 s6, s6, 0x80
	s_addc_u32 s7, s7, 0
.LBB0_802:
	s_waitcnt lgkmcnt(0)
	s_barrier
	ds_read_b128 v[224:227], v184
	ds_read_b128 v[228:231], v184 offset:1024
	ds_read_b128 v[232:235], v184 offset:2048
	ds_read_b128 v[236:239], v184 offset:3072
	ds_read_b128 v[190:193], v185
	ds_read_b128 v[194:197], v185 offset:1024
	ds_read_b128 v[198:201], v185 offset:2048
	ds_read_b128 v[204:207], v185 offset:3072
	ds_read_b128 v[208:211], v185 offset:4096
	ds_read_b128 v[212:215], v185 offset:5120
	ds_read_b128 v[216:219], v185 offset:6144
	ds_read_b128 v[220:223], v185 offset:7168
	s_movk_i32 vcc_lo, 0x6000
	s_cmp_eq_u32 m0, 2
	s_cselect_b32 vcc_lo, 0xffff4000, vcc_lo
	s_add_u32 m0, m0, 1
	s_cmp_eq_u32 m0, 3
	s_cselect_b32 m0, 0, m0
	v_add_u32_e32 v185, vcc_lo, v185
	v_add_u32_e32 v184, vcc_lo, v184
	v_xor_b32_e32 v185, 64, v185
	v_xor_b32_e32 v184, 64, v184
	s_waitcnt lgkmcnt(7)
	v_mfma_f32_16x16x32_bf16 v[172:175], v[224:227], v[190:193], v[172:175]
	v_mfma_f32_16x16x32_bf16 v[168:171], v[228:231], v[190:193], v[168:171]
	v_mfma_f32_16x16x32_bf16 v[164:167], v[232:235], v[190:193], v[164:167]
	v_mfma_f32_16x16x32_bf16 v[160:163], v[236:239], v[190:193], v[160:163]
	ds_read_b128 v[190:193], v185
	s_waitcnt lgkmcnt(7)
	v_mfma_f32_16x16x32_bf16 v[156:159], v[224:227], v[194:197], v[156:159]
	v_mfma_f32_16x16x32_bf16 v[152:155], v[228:231], v[194:197], v[152:155]
	v_mfma_f32_16x16x32_bf16 v[148:151], v[232:235], v[194:197], v[148:151]
	v_mfma_f32_16x16x32_bf16 v[144:147], v[236:239], v[194:197], v[144:147]
	ds_read_b128 v[194:197], v185 offset:1024
	s_waitcnt lgkmcnt(7)
	v_mfma_f32_16x16x32_bf16 v[136:139], v[224:227], v[198:201], v[136:139]
	v_mfma_f32_16x16x32_bf16 v[132:135], v[228:231], v[198:201], v[132:135]
	v_mfma_f32_16x16x32_bf16 v[128:131], v[232:235], v[198:201], v[128:131]
	v_mfma_f32_16x16x32_bf16 v[124:127], v[236:239], v[198:201], v[124:127]
	ds_read_b128 v[198:201], v185 offset:2048
	s_waitcnt lgkmcnt(7)
	v_mfma_f32_16x16x32_bf16 v[120:123], v[224:227], v[204:207], v[120:123]
	v_mfma_f32_16x16x32_bf16 v[108:111], v[228:231], v[204:207], v[108:111]
	v_mfma_f32_16x16x32_bf16 v[100:103], v[232:235], v[204:207], v[100:103]
	v_mfma_f32_16x16x32_bf16 v[96:99], v[236:239], v[204:207], v[96:99]
	ds_read_b128 v[204:207], v185 offset:3072
	s_waitcnt lgkmcnt(7)
	v_mfma_f32_16x16x32_bf16 v[92:95], v[224:227], v[208:211], v[92:95]
	v_mfma_f32_16x16x32_bf16 v[84:87], v[228:231], v[208:211], v[84:87]
	v_mfma_f32_16x16x32_bf16 v[76:79], v[232:235], v[208:211], v[76:79]
	v_mfma_f32_16x16x32_bf16 v[72:75], v[236:239], v[208:211], v[72:75]
	ds_read_b128 v[208:211], v185 offset:4096
	s_waitcnt lgkmcnt(7)
	v_mfma_f32_16x16x32_bf16 v[64:67], v[224:227], v[212:215], v[64:67]
	v_mfma_f32_16x16x32_bf16 v[52:55], v[228:231], v[212:215], v[52:55]
	v_mfma_f32_16x16x32_bf16 v[48:51], v[232:235], v[212:215], v[48:51]
	v_mfma_f32_16x16x32_bf16 v[44:47], v[236:239], v[212:215], v[44:47]
	ds_read_b128 v[212:215], v185 offset:5120
	s_waitcnt lgkmcnt(7)
	v_mfma_f32_16x16x32_bf16 v[36:39], v[224:227], v[216:219], v[36:39]
	v_mfma_f32_16x16x32_bf16 v[28:31], v[228:231], v[216:219], v[28:31]
	v_mfma_f32_16x16x32_bf16 v[24:27], v[232:235], v[216:219], v[24:27]
	v_mfma_f32_16x16x32_bf16 v[20:23], v[236:239], v[216:219], v[20:23]
	ds_read_b128 v[216:219], v185 offset:6144
	s_waitcnt lgkmcnt(7)
	v_mfma_f32_16x16x32_bf16 v[12:15], v[224:227], v[220:223], v[12:15]
	v_mfma_f32_16x16x32_bf16 v[4:7], v[228:231], v[220:223], v[4:7]
	v_mfma_f32_16x16x32_bf16 v[0:3], v[232:235], v[220:223], v[0:3]
	v_mfma_f32_16x16x32_bf16 v[140:143], v[236:239], v[220:223], v[140:143]
	ds_read_b128 v[220:223], v185 offset:7168
	ds_read_b128 v[224:227], v184
	ds_read_b128 v[228:231], v184 offset:1024
	ds_read_b128 v[232:235], v184 offset:2048
	ds_read_b128 v[236:239], v184 offset:3072
	s_movk_i32 vcc_lo, 0x6000
	s_cmp_eq_u32 m0, 2
	s_cselect_b32 vcc_lo, 0xffff4000, vcc_lo
	s_add_u32 m0, m0, 1
	s_cmp_eq_u32 m0, 3
	s_cselect_b32 m0, 0, m0
	v_add_u32_e32 v185, vcc_lo, v185
	v_add_u32_e32 v184, vcc_lo, v184
	v_xor_b32_e32 v185, 64, v185
	v_xor_b32_e32 v184, 64, v184
	s_sub_u32 vcc_lo, s6, s98
	v_add_u32_e32 v186, vcc_lo, v178
	v_add_u32_e32 v187, vcc_lo, v180
	s_barrier
	s_waitcnt lgkmcnt(0)
	v_mfma_f32_16x16x32_bf16 v[172:175], v[224:227], v[190:193], v[172:175]
	v_mfma_f32_16x16x32_bf16 v[168:171], v[228:231], v[190:193], v[168:171]
	v_mfma_f32_16x16x32_bf16 v[164:167], v[232:235], v[190:193], v[164:167]
	v_mfma_f32_16x16x32_bf16 v[160:163], v[236:239], v[190:193], v[160:163]
	s_waitcnt vmcnt(11)
	ds_write_b128 v183, v[116:119]
	v_add_u32_e32 v116, s26, v187
	global_load_dwordx4 v[116:119], v116, s[98:99] offset:128
	s_waitcnt vmcnt(11)
	ds_write_b128 v183, v[112:115] offset:2048
	v_add_u32_e32 v112, s27, v187
	global_load_dwordx4 v[112:115], v112, s[98:99] offset:128
	v_mfma_f32_16x16x32_bf16 v[156:159], v[224:227], v[194:197], v[156:159]
	v_mfma_f32_16x16x32_bf16 v[152:155], v[228:231], v[194:197], v[152:155]
	v_mfma_f32_16x16x32_bf16 v[148:151], v[232:235], v[194:197], v[148:151]
	v_mfma_f32_16x16x32_bf16 v[144:147], v[236:239], v[194:197], v[144:147]
	s_waitcnt vmcnt(11)
	ds_write_b128 v183, v[104:107] offset:4096
	v_add_u32_e32 v104, s20, v187
	global_load_dwordx4 v[104:107], v104, s[98:99] offset:128
	v_mfma_f32_16x16x32_bf16 v[136:139], v[224:227], v[198:201], v[136:139]
	v_mfma_f32_16x16x32_bf16 v[132:135], v[228:231], v[198:201], v[132:135]
	v_mfma_f32_16x16x32_bf16 v[128:131], v[232:235], v[198:201], v[128:131]
	v_mfma_f32_16x16x32_bf16 v[124:127], v[236:239], v[198:201], v[124:127]
	s_waitcnt vmcnt(11)
	ds_write_b128 v183, v[88:91] offset:6144
	v_add_u32_e32 v88, s21, v187
	global_load_dwordx4 v[88:91], v88, s[98:99] offset:128
	s_waitcnt vmcnt(11)
	ds_write_b128 v183, v[80:83] offset:8192
	v_add_u32_e32 v80, s56, v187
	global_load_dwordx4 v[80:83], v80, s[98:99] offset:128
	v_mfma_f32_16x16x32_bf16 v[120:123], v[224:227], v[204:207], v[120:123]
	v_mfma_f32_16x16x32_bf16 v[108:111], v[228:231], v[204:207], v[108:111]
	v_mfma_f32_16x16x32_bf16 v[100:103], v[232:235], v[204:207], v[100:103]
	v_mfma_f32_16x16x32_bf16 v[96:99], v[236:239], v[204:207], v[96:99]
	s_waitcnt vmcnt(11)
	ds_write_b128 v183, v[68:71] offset:10240
	v_add_u32_e32 v68, s57, v187
	global_load_dwordx4 v[68:71], v68, s[98:99] offset:128
	v_mfma_f32_16x16x32_bf16 v[92:95], v[224:227], v[208:211], v[92:95]
	v_mfma_f32_16x16x32_bf16 v[84:87], v[228:231], v[208:211], v[84:87]
	v_mfma_f32_16x16x32_bf16 v[76:79], v[232:235], v[208:211], v[76:79]
	v_mfma_f32_16x16x32_bf16 v[72:75], v[236:239], v[208:211], v[72:75]
	s_waitcnt vmcnt(11)
	ds_write_b128 v183, v[60:63] offset:12288
	v_add_u32_e32 v60, s24, v187
	global_load_dwordx4 v[60:63], v60, s[98:99] offset:128
	s_waitcnt vmcnt(11)
	ds_write_b128 v183, v[40:43] offset:14336
	v_add_u32_e32 v40, s96, v187
	global_load_dwordx4 v[40:43], v40, s[98:99] offset:128
	v_mfma_f32_16x16x32_bf16 v[64:67], v[224:227], v[212:215], v[64:67]
	v_mfma_f32_16x16x32_bf16 v[52:55], v[228:231], v[212:215], v[52:55]
	v_mfma_f32_16x16x32_bf16 v[48:51], v[232:235], v[212:215], v[48:51]
	v_mfma_f32_16x16x32_bf16 v[44:47], v[236:239], v[212:215], v[44:47]
	s_waitcnt vmcnt(11)
	ds_write_b128 v183, v[56:59] offset:16384
	v_mov_b32_e32 v56, v186
	global_load_dwordx4 v[56:59], v56, s[98:99] offset:128
	v_mfma_f32_16x16x32_bf16 v[36:39], v[224:227], v[216:219], v[36:39]
	v_mfma_f32_16x16x32_bf16 v[28:31], v[228:231], v[216:219], v[28:31]
	v_mfma_f32_16x16x32_bf16 v[24:27], v[232:235], v[216:219], v[24:27]
	v_mfma_f32_16x16x32_bf16 v[20:23], v[236:239], v[216:219], v[20:23]
	s_waitcnt vmcnt(11)
	ds_write_b128 v183, v[32:35] offset:18432
	v_add_u32_e32 v32, s13, v186
	global_load_dwordx4 v[32:35], v32, s[98:99] offset:128
	s_waitcnt vmcnt(11)
	ds_write_b128 v183, v[16:19] offset:20480
	v_add_u32_e32 v16, s12, v186
	global_load_dwordx4 v[16:19], v16, s[98:99] offset:128
	v_mfma_f32_16x16x32_bf16 v[12:15], v[224:227], v[220:223], v[12:15]
	v_mfma_f32_16x16x32_bf16 v[4:7], v[228:231], v[220:223], v[4:7]
	v_mfma_f32_16x16x32_bf16 v[0:3], v[232:235], v[220:223], v[0:3]
	v_mfma_f32_16x16x32_bf16 v[140:143], v[236:239], v[220:223], v[140:143]
	s_waitcnt vmcnt(11)
	ds_write_b128 v183, v[8:11] offset:22528
	v_add_u32_e32 v8, s11, v186
	global_load_dwordx4 v[8:11], v8, s[98:99] offset:128
	v_cmp_gt_u32_e32 vcc, 0x6000, v183
	v_add_u32_e32 v182, 0xc000, v183
	v_add_u32_e32 v183, 0xffffa000, v183
	s_nop 0
	v_cndmask_b32_e32 v183, v183, v182, vcc
	s_add_u32 s6, s6, 0x80
	s_addc_u32 s7, s7, 0
	s_cmpk_lg_i32 s6, 0x780
	s_cbranch_scc1 .LBB0_802
	s_waitcnt lgkmcnt(0)
	s_barrier
	ds_read_b128 v[224:227], v184
	ds_read_b128 v[228:231], v184 offset:1024
	ds_read_b128 v[232:235], v184 offset:2048
	ds_read_b128 v[236:239], v184 offset:3072
	ds_read_b128 v[190:193], v185
	ds_read_b128 v[194:197], v185 offset:1024
	ds_read_b128 v[198:201], v185 offset:2048
	ds_read_b128 v[204:207], v185 offset:3072
	ds_read_b128 v[208:211], v185 offset:4096
	ds_read_b128 v[212:215], v185 offset:5120
	ds_read_b128 v[216:219], v185 offset:6144
	ds_read_b128 v[220:223], v185 offset:7168
	s_movk_i32 vcc_lo, 0x6000
	s_cmp_eq_u32 m0, 2
	s_cselect_b32 vcc_lo, 0xffff4000, vcc_lo
	s_add_u32 m0, m0, 1
	s_cmp_eq_u32 m0, 3
	s_cselect_b32 m0, 0, m0
	v_add_u32_e32 v185, vcc_lo, v185
	v_add_u32_e32 v184, vcc_lo, v184
	v_xor_b32_e32 v185, 64, v185
	v_xor_b32_e32 v184, 64, v184
	s_waitcnt lgkmcnt(7)
	v_mfma_f32_16x16x32_bf16 v[172:175], v[224:227], v[190:193], v[172:175]
	v_mfma_f32_16x16x32_bf16 v[168:171], v[228:231], v[190:193], v[168:171]
	v_mfma_f32_16x16x32_bf16 v[164:167], v[232:235], v[190:193], v[164:167]
	v_mfma_f32_16x16x32_bf16 v[160:163], v[236:239], v[190:193], v[160:163]
	ds_read_b128 v[190:193], v185
	s_waitcnt lgkmcnt(7)
	v_mfma_f32_16x16x32_bf16 v[156:159], v[224:227], v[194:197], v[156:159]
	v_mfma_f32_16x16x32_bf16 v[152:155], v[228:231], v[194:197], v[152:155]
	v_mfma_f32_16x16x32_bf16 v[148:151], v[232:235], v[194:197], v[148:151]
	v_mfma_f32_16x16x32_bf16 v[144:147], v[236:239], v[194:197], v[144:147]
	ds_read_b128 v[194:197], v185 offset:1024
	s_waitcnt lgkmcnt(7)
	v_mfma_f32_16x16x32_bf16 v[136:139], v[224:227], v[198:201], v[136:139]
	v_mfma_f32_16x16x32_bf16 v[132:135], v[228:231], v[198:201], v[132:135]
	v_mfma_f32_16x16x32_bf16 v[128:131], v[232:235], v[198:201], v[128:131]
	v_mfma_f32_16x16x32_bf16 v[124:127], v[236:239], v[198:201], v[124:127]
	ds_read_b128 v[198:201], v185 offset:2048
	s_waitcnt lgkmcnt(7)
	v_mfma_f32_16x16x32_bf16 v[120:123], v[224:227], v[204:207], v[120:123]
	v_mfma_f32_16x16x32_bf16 v[108:111], v[228:231], v[204:207], v[108:111]
	v_mfma_f32_16x16x32_bf16 v[100:103], v[232:235], v[204:207], v[100:103]
	v_mfma_f32_16x16x32_bf16 v[96:99], v[236:239], v[204:207], v[96:99]
	ds_read_b128 v[204:207], v185 offset:3072
	s_waitcnt lgkmcnt(7)
	v_mfma_f32_16x16x32_bf16 v[92:95], v[224:227], v[208:211], v[92:95]
	v_mfma_f32_16x16x32_bf16 v[84:87], v[228:231], v[208:211], v[84:87]
	v_mfma_f32_16x16x32_bf16 v[76:79], v[232:235], v[208:211], v[76:79]
	v_mfma_f32_16x16x32_bf16 v[72:75], v[236:239], v[208:211], v[72:75]
	ds_read_b128 v[208:211], v185 offset:4096
	s_waitcnt lgkmcnt(7)
	v_mfma_f32_16x16x32_bf16 v[64:67], v[224:227], v[212:215], v[64:67]
	v_mfma_f32_16x16x32_bf16 v[52:55], v[228:231], v[212:215], v[52:55]
	v_mfma_f32_16x16x32_bf16 v[48:51], v[232:235], v[212:215], v[48:51]
	v_mfma_f32_16x16x32_bf16 v[44:47], v[236:239], v[212:215], v[44:47]
	ds_read_b128 v[212:215], v185 offset:5120
	s_waitcnt lgkmcnt(7)
	v_mfma_f32_16x16x32_bf16 v[36:39], v[224:227], v[216:219], v[36:39]
	v_mfma_f32_16x16x32_bf16 v[28:31], v[228:231], v[216:219], v[28:31]
	v_mfma_f32_16x16x32_bf16 v[24:27], v[232:235], v[216:219], v[24:27]
	v_mfma_f32_16x16x32_bf16 v[20:23], v[236:239], v[216:219], v[20:23]
	ds_read_b128 v[216:219], v185 offset:6144
	s_waitcnt lgkmcnt(7)
	v_mfma_f32_16x16x32_bf16 v[12:15], v[224:227], v[220:223], v[12:15]
	v_mfma_f32_16x16x32_bf16 v[4:7], v[228:231], v[220:223], v[4:7]
	v_mfma_f32_16x16x32_bf16 v[0:3], v[232:235], v[220:223], v[0:3]
	v_mfma_f32_16x16x32_bf16 v[140:143], v[236:239], v[220:223], v[140:143]
	ds_read_b128 v[220:223], v185 offset:7168
	ds_read_b128 v[224:227], v184
	ds_read_b128 v[228:231], v184 offset:1024
	ds_read_b128 v[232:235], v184 offset:2048
	ds_read_b128 v[236:239], v184 offset:3072
	s_movk_i32 vcc_lo, 0x6000
	s_cmp_eq_u32 m0, 2
	s_cselect_b32 vcc_lo, 0xffff4000, vcc_lo
	s_add_u32 m0, m0, 1
	s_cmp_eq_u32 m0, 3
	s_cselect_b32 m0, 0, m0
	v_add_u32_e32 v185, vcc_lo, v185
	v_add_u32_e32 v184, vcc_lo, v184
	v_xor_b32_e32 v185, 64, v185
	v_xor_b32_e32 v184, 64, v184
	s_waitcnt lgkmcnt(0)
	v_mfma_f32_16x16x32_bf16 v[172:175], v[224:227], v[190:193], v[172:175]
	v_mfma_f32_16x16x32_bf16 v[168:171], v[228:231], v[190:193], v[168:171]
	v_mfma_f32_16x16x32_bf16 v[164:167], v[232:235], v[190:193], v[164:167]
	v_mfma_f32_16x16x32_bf16 v[160:163], v[236:239], v[190:193], v[160:163]
	v_mfma_f32_16x16x32_bf16 v[156:159], v[224:227], v[194:197], v[156:159]
	v_mfma_f32_16x16x32_bf16 v[152:155], v[228:231], v[194:197], v[152:155]
	v_mfma_f32_16x16x32_bf16 v[148:151], v[232:235], v[194:197], v[148:151]
	v_mfma_f32_16x16x32_bf16 v[144:147], v[236:239], v[194:197], v[144:147]
	v_mfma_f32_16x16x32_bf16 v[136:139], v[224:227], v[198:201], v[136:139]
	v_mfma_f32_16x16x32_bf16 v[132:135], v[228:231], v[198:201], v[132:135]
	v_mfma_f32_16x16x32_bf16 v[128:131], v[232:235], v[198:201], v[128:131]
	v_mfma_f32_16x16x32_bf16 v[124:127], v[236:239], v[198:201], v[124:127]
	v_mfma_f32_16x16x32_bf16 v[120:123], v[224:227], v[204:207], v[120:123]
	v_mfma_f32_16x16x32_bf16 v[108:111], v[228:231], v[204:207], v[108:111]
	v_mfma_f32_16x16x32_bf16 v[100:103], v[232:235], v[204:207], v[100:103]
	v_mfma_f32_16x16x32_bf16 v[96:99], v[236:239], v[204:207], v[96:99]
	v_mfma_f32_16x16x32_bf16 v[92:95], v[224:227], v[208:211], v[92:95]
	v_mfma_f32_16x16x32_bf16 v[84:87], v[228:231], v[208:211], v[84:87]
	v_mfma_f32_16x16x32_bf16 v[76:79], v[232:235], v[208:211], v[76:79]
	v_mfma_f32_16x16x32_bf16 v[72:75], v[236:239], v[208:211], v[72:75]
	v_mfma_f32_16x16x32_bf16 v[64:67], v[224:227], v[212:215], v[64:67]
	v_mfma_f32_16x16x32_bf16 v[52:55], v[228:231], v[212:215], v[52:55]
	v_mfma_f32_16x16x32_bf16 v[48:51], v[232:235], v[212:215], v[48:51]
	v_mfma_f32_16x16x32_bf16 v[44:47], v[236:239], v[212:215], v[44:47]
	v_mfma_f32_16x16x32_bf16 v[36:39], v[224:227], v[216:219], v[36:39]
	v_mfma_f32_16x16x32_bf16 v[28:31], v[228:231], v[216:219], v[28:31]
	v_mfma_f32_16x16x32_bf16 v[24:27], v[232:235], v[216:219], v[24:27]
	v_mfma_f32_16x16x32_bf16 v[20:23], v[236:239], v[216:219], v[20:23]
	v_mfma_f32_16x16x32_bf16 v[12:15], v[224:227], v[220:223], v[12:15]
	v_mfma_f32_16x16x32_bf16 v[4:7], v[228:231], v[220:223], v[4:7]
	v_mfma_f32_16x16x32_bf16 v[0:3], v[232:235], v[220:223], v[0:3]
	v_mfma_f32_16x16x32_bf16 v[140:143], v[236:239], v[220:223], v[140:143]
	v_lshrrev_b32_e32 v224, 4, v188
	v_and_b32_e32 v225, 7, v188
	v_bitop3_b32 v226, v224, v225, 3 bitop3:0x6c
	v_lshlrev_b32_e32 v227, 7, v188
	v_bfe_u32 v228, v188, 4, 2
	v_and_b32_e32 v229, 0xffffc780, v227
	v_and_b32_e32 v227, 0x2780, v227
	v_bitop3_b32 v228, v228, v225, 4 bitop3:0x36
	v_lshlrev_b32_e32 v226, 4, v226
	v_lshlrev_b32_e32 v228, 4, v228
	v_or_b32_e32 v185, v229, v226
	v_or_b32_e32 v184, v227, v226
	v_or_b32_e32 v183, v229, v228
	v_or_b32_e32 v182, v227, v228
	s_waitcnt vmcnt(0)
	s_barrier
	s_waitcnt vmcnt(10)
	ds_write_b128 v176, v[116:119]
	s_waitcnt vmcnt(9)
	ds_write_b128 v176, v[112:115] offset:4096
	s_waitcnt vmcnt(8)
	ds_write_b128 v176, v[104:107] offset:8192
	s_waitcnt vmcnt(7)
	ds_write_b128 v176, v[88:91] offset:12288
	s_waitcnt vmcnt(6)
	ds_write_b128 v176, v[80:83] offset:16384
	s_waitcnt vmcnt(5)
	ds_write_b128 v176, v[68:71] offset:20480
	s_waitcnt vmcnt(4)
	ds_write_b128 v176, v[60:63] offset:24576
	s_waitcnt vmcnt(3)
	ds_write_b128 v176, v[40:43] offset:28672
	ds_write_b128 v176, v[56:59] offset:32768
	s_waitcnt vmcnt(2)
	ds_write_b128 v176, v[32:35] offset:36864
	s_waitcnt vmcnt(1)
	ds_write_b128 v176, v[16:19] offset:40960
	s_waitcnt vmcnt(0)
	ds_write_b128 v176, v[8:11] offset:45056
	s_waitcnt lgkmcnt(0)
	s_barrier
	ds_read_b128 v[8:11], v185
	ds_read_b128 v[16:19], v185 offset:2048
	ds_read_b128 v[32:35], v185 offset:4096
	ds_read_b128 v[40:43], v185 offset:6144
	ds_read_b128 v[56:59], v185 offset:8192
	ds_read_b128 v[60:63], v185 offset:10240
	ds_read_b128 v[68:71], v185 offset:12288
	ds_read_b128 v[80:83], v185 offset:14336
	ds_read_b128 v[88:91], v184 offset:32768
	ds_read_b128 v[104:107], v184 offset:34816
	ds_read_b128 v[112:115], v184 offset:36864
	ds_read_b128 v[116:119], v184 offset:38912
	s_waitcnt lgkmcnt(3)
	v_mfma_f32_16x16x32_bf16 v[172:175], v[88:91], v[8:11], v[172:175]
	s_waitcnt lgkmcnt(2)
	v_mfma_f32_16x16x32_bf16 v[168:171], v[104:107], v[8:11], v[168:171]
	s_waitcnt lgkmcnt(1)
	v_mfma_f32_16x16x32_bf16 v[164:167], v[112:115], v[8:11], v[164:167]
	s_waitcnt lgkmcnt(0)
	v_mfma_f32_16x16x32_bf16 v[8:11], v[116:119], v[8:11], v[160:163]
	v_mfma_f32_16x16x32_bf16 v[156:159], v[88:91], v[16:19], v[156:159]
	v_mfma_f32_16x16x32_bf16 v[152:155], v[104:107], v[16:19], v[152:155]
	v_mfma_f32_16x16x32_bf16 v[148:151], v[112:115], v[16:19], v[148:151]
	v_mfma_f32_16x16x32_bf16 v[16:19], v[116:119], v[16:19], v[144:147]
	v_mfma_f32_16x16x32_bf16 v[136:139], v[88:91], v[32:35], v[136:139]
	v_mfma_f32_16x16x32_bf16 v[132:135], v[104:107], v[32:35], v[132:135]
	v_mfma_f32_16x16x32_bf16 v[128:131], v[112:115], v[32:35], v[128:131]
	v_mfma_f32_16x16x32_bf16 v[32:35], v[116:119], v[32:35], v[124:127]
	v_mfma_f32_16x16x32_bf16 v[120:123], v[88:91], v[40:43], v[120:123]
	v_mfma_f32_16x16x32_bf16 v[108:111], v[104:107], v[40:43], v[108:111]
	v_mfma_f32_16x16x32_bf16 v[100:103], v[112:115], v[40:43], v[100:103]
	v_mfma_f32_16x16x32_bf16 v[40:43], v[116:119], v[40:43], v[96:99]
	v_mfma_f32_16x16x32_bf16 v[92:95], v[88:91], v[56:59], v[92:95]
	v_mfma_f32_16x16x32_bf16 v[84:87], v[104:107], v[56:59], v[84:87]
	v_mfma_f32_16x16x32_bf16 v[76:79], v[112:115], v[56:59], v[76:79]
	v_mfma_f32_16x16x32_bf16 v[56:59], v[116:119], v[56:59], v[72:75]
	v_mfma_f32_16x16x32_bf16 v[64:67], v[88:91], v[60:63], v[64:67]
	v_mfma_f32_16x16x32_bf16 v[52:55], v[104:107], v[60:63], v[52:55]
	v_mfma_f32_16x16x32_bf16 v[72:75], v[112:115], v[60:63], v[48:51]
	v_mfma_f32_16x16x32_bf16 v[60:63], v[116:119], v[60:63], v[44:47]
	v_mfma_f32_16x16x32_bf16 v[96:99], v[88:91], v[68:71], v[36:39]
	v_mfma_f32_16x16x32_bf16 v[28:31], v[104:107], v[68:71], v[28:31]
	v_mfma_f32_16x16x32_bf16 v[124:127], v[112:115], v[68:71], v[24:27]
	v_mfma_f32_16x16x32_bf16 v[20:23], v[116:119], v[68:71], v[20:23]
	v_mfma_f32_16x16x32_bf16 v[12:15], v[88:91], v[80:83], v[12:15]
	v_mfma_f32_16x16x32_bf16 v[4:7], v[104:107], v[80:83], v[4:7]
	v_mfma_f32_16x16x32_bf16 v[0:3], v[112:115], v[80:83], v[0:3]
	v_mfma_f32_16x16x32_bf16 v[68:71], v[116:119], v[80:83], v[140:143]
	ds_read_b128 v[24:27], v183
	ds_read_b128 v[36:39], v183 offset:2048
	ds_read_b128 v[44:47], v183 offset:4096
	ds_read_b128 v[80:83], v183 offset:6144
	ds_read_b128 v[88:91], v183 offset:8192
	ds_read_b128 v[104:107], v183 offset:10240
	ds_read_b128 v[112:115], v183 offset:12288
	ds_read_b128 v[116:119], v183 offset:14336
	ds_read_b128 v[140:143], v182 offset:32768
	ds_read_b128 v[144:147], v182 offset:34816
	ds_read_b128 v[160:163], v182 offset:36864
	ds_read_b128 v[178:181], v182 offset:38912
	s_waitcnt lgkmcnt(3)
	v_mfma_f32_16x16x32_bf16 v[172:175], v[140:143], v[24:27], v[172:175]
	v_mov_b32_e32 v49, v188
	v_cmp_lt_i32_e32 vcc, v189, v202
	s_waitcnt lgkmcnt(2)
	v_mfma_f32_16x16x32_bf16 v[168:171], v[144:147], v[24:27], v[168:171]
	v_mov_b32_e32 v48, v188
	v_readlane_b32 s6, v253, 24
	s_waitcnt lgkmcnt(1)
	v_mfma_f32_16x16x32_bf16 v[164:167], v[160:163], v[24:27], v[164:167]
	v_and_b32_e32 v50, 0xffffff80, v48
	v_add_u32_e32 v51, s9, v50
	v_and_or_b32 v50, v48, 64, s10
	s_waitcnt lgkmcnt(0)
	v_mfma_f32_16x16x32_bf16 v[8:11], v[178:181], v[24:27], v[8:11]
	v_bfe_u32 v26, v49, 4, 1
	v_cndmask_b32_e32 v24, v203, v189, vcc
	v_cmp_eq_u32_e32 vcc, 0, v26
	v_lshlrev_b32_e32 v186, 2, v24
	v_mfma_f32_16x16x32_bf16 v[182:185], v[178:181], v[36:39], v[16:19]
	v_and_or_b32 v48, v49, 15, v51
	v_ashrrev_i32_e32 v51, 31, v50
	v_lshl_add_u64 v[50:51], v[50:51], 1, s[4:5]
	v_cndmask_b32_e32 v16, v172, v168, vcc
	v_cndmask_b32_e32 v17, v173, v169, vcc
	v_cndmask_b32_e32 v18, v174, v170, vcc
	v_cndmask_b32_e32 v19, v175, v171, vcc
	ds_bpermute_b32 v16, v186, v16
	ds_bpermute_b32 v17, v186, v17
	ds_bpermute_b32 v18, v186, v18
	ds_bpermute_b32 v19, v186, v19
	v_lshlrev_b32_e32 v176, 5, v26
	v_lshrrev_b32_e32 v27, 1, v49
	v_lshl_add_u64 v[24:25], v[50:51], 0, v[176:177]
	v_and_b32_e32 v176, 16, v27
	v_ashrrev_i32_e32 v49, 31, v48
	v_mfma_f32_16x16x32_bf16 v[156:159], v[140:143], v[36:39], v[156:159]
	v_lshl_add_u64 v[50:51], v[24:25], 0, v[176:177]
	v_lshlrev_b64 v[24:25], 11, v[48:49]
	s_waitcnt lgkmcnt(3)
	v_cndmask_b32_e32 v26, v16, v172, vcc
	v_mfma_f32_16x16x32_bf16 v[152:155], v[144:147], v[36:39], v[152:155]
	v_cndmask_b32_e32 v27, v168, v16, vcc
	s_waitcnt lgkmcnt(2)
	v_cndmask_b32_e32 v16, v17, v173, vcc
	v_lshl_add_u64 v[24:25], v[50:51], 0, v[24:25]
	v_mfma_f32_16x16x32_bf16 v[148:151], v[160:163], v[36:39], v[148:151]
	v_cndmask_b32_e32 v36, v169, v17, vcc
	s_waitcnt lgkmcnt(1)
	v_cndmask_b32_e32 v17, v18, v174, vcc
	v_cvt_pk_bf16_f32 v16, v26, v16
	v_mfma_f32_16x16x32_bf16 v[190:193], v[178:181], v[44:47], v[32:35]
	v_readlane_b32 s7, v253, 25
	s_nop 1
	v_cndmask_b32_e32 v32, v170, v18, vcc
	s_waitcnt lgkmcnt(0)
	v_cndmask_b32_e32 v18, v19, v175, vcc
	v_cndmask_b32_e32 v19, v171, v19, vcc
	v_cvt_pk_bf16_f32 v17, v17, v18
	v_cvt_pk_bf16_f32 v18, v27, v36
	v_cvt_pk_bf16_f32 v19, v32, v19
	global_store_dwordx4 v[24:25], v[16:19], off
	v_mfma_f32_16x16x32_bf16 v[120:123], v[140:143], v[80:83], v[120:123]
	s_nop 0
	v_cndmask_b32_e32 v16, v164, v8, vcc
	v_cndmask_b32_e32 v17, v165, v9, vcc
	v_cndmask_b32_e32 v18, v166, v10, vcc
	v_cndmask_b32_e32 v19, v167, v11, vcc
	ds_bpermute_b32 v16, v186, v16
	ds_bpermute_b32 v17, v186, v17
	ds_bpermute_b32 v18, v186, v18
	ds_bpermute_b32 v19, v186, v19
	v_mfma_f32_16x16x32_bf16 v[108:111], v[144:147], v[80:83], v[108:111]
	s_waitcnt lgkmcnt(3)
	v_cndmask_b32_e32 v26, v16, v164, vcc
	v_cndmask_b32_e32 v16, v8, v16, vcc
	s_waitcnt lgkmcnt(2)
	v_cndmask_b32_e32 v8, v17, v165, vcc
	v_cndmask_b32_e32 v17, v9, v17, vcc
	s_waitcnt lgkmcnt(1)
	v_cndmask_b32_e32 v9, v18, v166, vcc
	v_cndmask_b32_e32 v18, v10, v18, vcc
	s_waitcnt lgkmcnt(0)
	v_cndmask_b32_e32 v10, v19, v167, vcc
	v_cndmask_b32_e32 v11, v11, v19, vcc
	v_cvt_pk_bf16_f32 v8, v26, v8
	v_cvt_pk_bf16_f32 v9, v9, v10
	v_cvt_pk_bf16_f32 v10, v16, v17
	v_cvt_pk_bf16_f32 v11, v18, v11
	global_store_dwordx4 v[24:25], v[8:11], off offset:64
	v_mfma_f32_16x16x32_bf16 v[100:103], v[160:163], v[80:83], v[100:103]
	s_nop 0
	v_or_b32_e32 v8, 16, v48
	v_ashrrev_i32_e32 v9, 31, v8
	v_lshlrev_b64 v[8:9], 11, v[8:9]
	v_mfma_f32_16x16x32_bf16 v[80:83], v[178:181], v[80:83], v[40:43]
	v_cndmask_b32_e32 v10, v158, v154, vcc
	v_cndmask_b32_e32 v11, v159, v155, vcc
	ds_bpermute_b32 v10, v186, v10
	v_mfma_f32_16x16x32_bf16 v[40:43], v[140:143], v[104:107], v[64:67]
	ds_bpermute_b32 v11, v186, v11
	s_nop 1
	v_lshl_add_u64 v[64:65], v[50:51], 0, v[8:9]
	v_cndmask_b32_e32 v8, v156, v152, vcc
	v_cndmask_b32_e32 v9, v157, v153, vcc
	ds_bpermute_b32 v8, v186, v8
	ds_bpermute_b32 v9, v186, v9
	v_mfma_f32_16x16x32_bf16 v[136:139], v[140:143], v[44:47], v[136:139]
	s_waitcnt lgkmcnt(1)
	v_cndmask_b32_e32 v49, v8, v156, vcc
	v_mfma_f32_16x16x32_bf16 v[132:135], v[144:147], v[44:47], v[132:135]
	v_mfma_f32_16x16x32_bf16 v[128:131], v[160:163], v[44:47], v[128:131]
	v_mfma_f32_16x16x32_bf16 v[44:47], v[144:147], v[104:107], v[52:55]
	v_mfma_f32_16x16x32_bf16 v[36:39], v[178:181], v[104:107], v[60:63]
	s_nop 1
	v_cndmask_b32_e32 v54, v152, v8, vcc
	s_waitcnt lgkmcnt(0)
	v_cndmask_b32_e32 v8, v9, v157, vcc
	v_cndmask_b32_e32 v55, v153, v9, vcc
	v_cndmask_b32_e32 v53, v10, v158, vcc
	v_cndmask_b32_e32 v60, v154, v10, vcc
	v_cndmask_b32_e32 v61, v11, v159, vcc
	v_cndmask_b32_e32 v62, v155, v11, vcc
	v_cvt_pk_bf16_f32 v52, v49, v8
	v_cvt_pk_bf16_f32 v53, v53, v61
	v_cvt_pk_bf16_f32 v54, v54, v55
	v_cvt_pk_bf16_f32 v55, v60, v62
	v_mfma_f32_16x16x32_bf16 v[8:11], v[140:143], v[116:119], v[12:15]
	global_store_dwordx4 v[64:65], v[52:55], off
	v_cndmask_b32_e32 v49, v149, v183, vcc
	ds_bpermute_b32 v49, v186, v49
	v_mfma_f32_16x16x32_bf16 v[12:15], v[144:147], v[116:119], v[4:7]
	v_cndmask_b32_e32 v52, v150, v184, vcc
	v_cndmask_b32_e32 v53, v151, v185, vcc
	ds_bpermute_b32 v52, v186, v52
	v_cndmask_b32_e32 v4, v148, v182, vcc
	ds_bpermute_b32 v54, v186, v4
	ds_bpermute_b32 v53, v186, v53
	s_waitcnt lgkmcnt(3)
	v_cndmask_b32_e32 v60, v49, v149, vcc
	v_cndmask_b32_e32 v49, v183, v49, vcc
	s_waitcnt lgkmcnt(2)
	v_cndmask_b32_e32 v61, v52, v150, vcc
	s_waitcnt lgkmcnt(1)
	v_cndmask_b32_e32 v55, v54, v148, vcc
	v_cndmask_b32_e32 v54, v182, v54, vcc
	v_cndmask_b32_e32 v62, v184, v52, vcc
	s_waitcnt lgkmcnt(0)
	v_cndmask_b32_e32 v63, v53, v151, vcc
	v_cndmask_b32_e32 v66, v185, v53, vcc
	v_cvt_pk_bf16_f32 v52, v55, v60
	v_cvt_pk_bf16_f32 v53, v61, v63
	v_cvt_pk_bf16_f32 v54, v54, v49
	v_cvt_pk_bf16_f32 v55, v62, v66
	global_store_dwordx4 v[64:65], v[52:55], off offset:64
	v_cndmask_b32_e32 v49, v136, v132, vcc
	ds_bpermute_b32 v49, v186, v49
	v_or_b32_e32 v52, 32, v48
	v_ashrrev_i32_e32 v53, 31, v52
	v_lshlrev_b64 v[52:53], 11, v[52:53]
	v_lshl_add_u64 v[60:61], v[50:51], 0, v[52:53]
	v_cndmask_b32_e32 v52, v137, v133, vcc
	v_cndmask_b32_e32 v53, v138, v134, vcc
	v_cndmask_b32_e32 v54, v139, v135, vcc
	ds_bpermute_b32 v52, v186, v52
	ds_bpermute_b32 v53, v186, v53
	ds_bpermute_b32 v54, v186, v54
	s_waitcnt lgkmcnt(3)
	v_cndmask_b32_e32 v55, v49, v136, vcc
	v_cndmask_b32_e32 v49, v132, v49, vcc
	s_waitcnt lgkmcnt(2)
	v_cndmask_b32_e32 v62, v52, v137, vcc
	v_cndmask_b32_e32 v63, v133, v52, vcc
	s_waitcnt lgkmcnt(1)
	v_cndmask_b32_e32 v64, v53, v138, vcc
	v_cndmask_b32_e32 v65, v134, v53, vcc
	s_waitcnt lgkmcnt(0)
	v_cndmask_b32_e32 v53, v54, v139, vcc
	v_cndmask_b32_e32 v66, v135, v54, vcc
	v_cvt_pk_bf16_f32 v52, v55, v62
	v_cvt_pk_bf16_f32 v53, v64, v53
	v_cvt_pk_bf16_f32 v54, v49, v63
	v_cvt_pk_bf16_f32 v55, v65, v66
	global_store_dwordx4 v[60:61], v[52:55], off
	v_cndmask_b32_e32 v49, v128, v190, vcc
	ds_bpermute_b32 v49, v186, v49
	v_cndmask_b32_e32 v52, v129, v191, vcc
	v_cndmask_b32_e32 v53, v130, v192, vcc
	v_cndmask_b32_e32 v54, v131, v193, vcc
	ds_bpermute_b32 v52, v186, v52
	ds_bpermute_b32 v53, v186, v53
	ds_bpermute_b32 v54, v186, v54
	s_waitcnt lgkmcnt(3)
	v_cndmask_b32_e32 v55, v49, v128, vcc
	v_cndmask_b32_e32 v49, v190, v49, vcc
	s_waitcnt lgkmcnt(2)
	v_cndmask_b32_e32 v62, v52, v129, vcc
	v_cndmask_b32_e32 v63, v191, v52, vcc
	s_waitcnt lgkmcnt(1)
	v_cndmask_b32_e32 v64, v53, v130, vcc
	v_cndmask_b32_e32 v65, v192, v53, vcc
	s_waitcnt lgkmcnt(0)
	v_cndmask_b32_e32 v53, v54, v131, vcc
	v_cndmask_b32_e32 v66, v193, v54, vcc
	v_cvt_pk_bf16_f32 v52, v55, v62
	v_cvt_pk_bf16_f32 v53, v64, v53
	v_cvt_pk_bf16_f32 v54, v49, v63
	v_cvt_pk_bf16_f32 v55, v65, v66
	global_store_dwordx4 v[60:61], v[52:55], off offset:64
	v_cndmask_b32_e32 v49, v120, v108, vcc
	ds_bpermute_b32 v49, v186, v49
	v_or_b32_e32 v52, 48, v48
	v_ashrrev_i32_e32 v53, 31, v52
	v_lshlrev_b64 v[52:53], 11, v[52:53]
	v_lshl_add_u64 v[60:61], v[50:51], 0, v[52:53]
	v_cndmask_b32_e32 v52, v121, v109, vcc
	v_cndmask_b32_e32 v53, v122, v110, vcc
	v_cndmask_b32_e32 v54, v123, v111, vcc
	ds_bpermute_b32 v52, v186, v52
	ds_bpermute_b32 v53, v186, v53
	ds_bpermute_b32 v54, v186, v54
	s_waitcnt lgkmcnt(3)
	v_cndmask_b32_e32 v55, v49, v120, vcc
	v_cndmask_b32_e32 v49, v108, v49, vcc
	s_waitcnt lgkmcnt(2)
	v_cndmask_b32_e32 v62, v52, v121, vcc
	v_cndmask_b32_e32 v63, v109, v52, vcc
	s_waitcnt lgkmcnt(1)
	v_cndmask_b32_e32 v64, v53, v122, vcc
	v_cndmask_b32_e32 v65, v110, v53, vcc
	s_waitcnt lgkmcnt(0)
	v_cndmask_b32_e32 v53, v54, v123, vcc
	v_cndmask_b32_e32 v66, v111, v54, vcc
	v_cvt_pk_bf16_f32 v52, v55, v62
	v_cvt_pk_bf16_f32 v53, v64, v53
	v_cvt_pk_bf16_f32 v54, v49, v63
	v_cvt_pk_bf16_f32 v55, v65, v66
	global_store_dwordx4 v[60:61], v[52:55], off
	v_cndmask_b32_e32 v49, v100, v80, vcc
	ds_bpermute_b32 v49, v186, v49
	v_cndmask_b32_e32 v52, v101, v81, vcc
	v_cndmask_b32_e32 v53, v102, v82, vcc
	v_cndmask_b32_e32 v54, v103, v83, vcc
	ds_bpermute_b32 v52, v186, v52
	ds_bpermute_b32 v53, v186, v53
	ds_bpermute_b32 v54, v186, v54
	s_waitcnt lgkmcnt(3)
	v_cndmask_b32_e32 v55, v49, v100, vcc
	v_cndmask_b32_e32 v49, v80, v49, vcc
	s_waitcnt lgkmcnt(2)
	v_cndmask_b32_e32 v62, v52, v101, vcc
	v_cndmask_b32_e32 v63, v81, v52, vcc
	s_waitcnt lgkmcnt(1)
	v_cndmask_b32_e32 v64, v53, v102, vcc
	v_cndmask_b32_e32 v65, v82, v53, vcc
	s_waitcnt lgkmcnt(0)
	v_cndmask_b32_e32 v53, v54, v103, vcc
	v_cndmask_b32_e32 v66, v83, v54, vcc
	v_mfma_f32_16x16x32_bf16 v[92:95], v[140:143], v[88:91], v[92:95]
	v_cvt_pk_bf16_f32 v52, v55, v62
	v_cvt_pk_bf16_f32 v53, v64, v53
	v_cvt_pk_bf16_f32 v54, v49, v63
	v_mfma_f32_16x16x32_bf16 v[84:87], v[144:147], v[88:91], v[84:87]
	v_cvt_pk_bf16_f32 v55, v65, v66
	global_store_dwordx4 v[60:61], v[52:55], off offset:64
	v_mfma_f32_16x16x32_bf16 v[76:79], v[160:163], v[88:91], v[76:79]
	s_nop 0
	v_or_b32_e32 v52, 64, v48
	v_ashrrev_i32_e32 v53, 31, v52
	v_lshlrev_b64 v[52:53], 11, v[52:53]
	v_lshl_add_u64 v[60:61], v[50:51], 0, v[52:53]
	v_cndmask_b32_e32 v49, v92, v84, vcc
	v_cndmask_b32_e32 v52, v93, v85, vcc
	v_cndmask_b32_e32 v53, v94, v86, vcc
	v_cndmask_b32_e32 v54, v95, v87, vcc
	ds_bpermute_b32 v49, v186, v49
	ds_bpermute_b32 v52, v186, v52
	ds_bpermute_b32 v53, v186, v53
	ds_bpermute_b32 v54, v186, v54
	v_mfma_f32_16x16x32_bf16 v[56:59], v[178:181], v[88:91], v[56:59]
	s_waitcnt lgkmcnt(3)
	v_cndmask_b32_e32 v55, v49, v92, vcc
	v_cndmask_b32_e32 v49, v84, v49, vcc
	s_waitcnt lgkmcnt(2)
	v_cndmask_b32_e32 v62, v52, v93, vcc
	v_cndmask_b32_e32 v63, v85, v52, vcc
	s_waitcnt lgkmcnt(1)
	v_cndmask_b32_e32 v64, v53, v94, vcc
	v_cndmask_b32_e32 v65, v86, v53, vcc
	s_waitcnt lgkmcnt(0)
	v_cndmask_b32_e32 v53, v54, v95, vcc
	v_cndmask_b32_e32 v66, v87, v54, vcc
	v_cvt_pk_bf16_f32 v52, v55, v62
	v_cvt_pk_bf16_f32 v53, v64, v53
	v_cvt_pk_bf16_f32 v54, v49, v63
	v_cvt_pk_bf16_f32 v55, v65, v66
	global_store_dwordx4 v[60:61], v[52:55], off
	v_cndmask_b32_e32 v49, v76, v56, vcc
	ds_bpermute_b32 v49, v186, v49
	v_cndmask_b32_e32 v52, v77, v57, vcc
	v_cndmask_b32_e32 v53, v78, v58, vcc
	v_cndmask_b32_e32 v54, v79, v59, vcc
	ds_bpermute_b32 v52, v186, v52
	ds_bpermute_b32 v53, v186, v53
	ds_bpermute_b32 v54, v186, v54
	s_waitcnt lgkmcnt(3)
	v_cndmask_b32_e32 v55, v49, v76, vcc
	v_cndmask_b32_e32 v49, v56, v49, vcc
	s_waitcnt lgkmcnt(2)
	v_cndmask_b32_e32 v56, v52, v77, vcc
	v_cndmask_b32_e32 v57, v57, v52, vcc
	s_waitcnt lgkmcnt(1)
	v_cndmask_b32_e32 v62, v53, v78, vcc
	v_cndmask_b32_e32 v58, v58, v53, vcc
	s_waitcnt lgkmcnt(0)
	v_cndmask_b32_e32 v53, v54, v79, vcc
	v_cndmask_b32_e32 v59, v59, v54, vcc
	v_cvt_pk_bf16_f32 v52, v55, v56
	v_cvt_pk_bf16_f32 v53, v62, v53
	v_cvt_pk_bf16_f32 v54, v49, v57
	v_cvt_pk_bf16_f32 v55, v58, v59
	global_store_dwordx4 v[60:61], v[52:55], off offset:64
	v_cndmask_b32_e32 v49, v40, v44, vcc
	v_cndmask_b32_e32 v56, v43, v47, vcc
	v_cndmask_b32_e32 v54, v41, v45, vcc
	v_cndmask_b32_e32 v55, v42, v46, vcc
	ds_bpermute_b32 v49, v186, v49
	ds_bpermute_b32 v54, v186, v54
	ds_bpermute_b32 v55, v186, v55
	ds_bpermute_b32 v56, v186, v56
	v_mfma_f32_16x16x32_bf16 v[32:35], v[160:163], v[104:107], v[72:75]
	v_or_b32_e32 v52, 0x50, v48
	v_ashrrev_i32_e32 v53, 31, v52
	v_lshlrev_b64 v[52:53], 11, v[52:53]
	s_waitcnt lgkmcnt(3)
	v_cndmask_b32_e32 v40, v49, v40, vcc
	v_cndmask_b32_e32 v44, v44, v49, vcc
	s_waitcnt lgkmcnt(2)
	v_cndmask_b32_e32 v41, v54, v41, vcc
	v_cndmask_b32_e32 v45, v45, v54, vcc
	s_waitcnt lgkmcnt(1)
	v_cndmask_b32_e32 v42, v55, v42, vcc
	v_cndmask_b32_e32 v46, v46, v55, vcc
	s_waitcnt lgkmcnt(0)
	v_cndmask_b32_e32 v43, v56, v43, vcc
	v_cndmask_b32_e32 v47, v47, v56, vcc
	v_lshl_add_u64 v[52:53], v[50:51], 0, v[52:53]
	v_cvt_pk_bf16_f32 v40, v40, v41
	v_cvt_pk_bf16_f32 v41, v42, v43
	v_cvt_pk_bf16_f32 v42, v44, v45
	v_cvt_pk_bf16_f32 v43, v46, v47
	global_store_dwordx4 v[52:53], v[40:43], off
	v_mfma_f32_16x16x32_bf16 v[24:27], v[140:143], v[112:115], v[96:99]
	s_nop 0
	v_cndmask_b32_e32 v40, v32, v36, vcc
	v_cndmask_b32_e32 v41, v33, v37, vcc
	v_cndmask_b32_e32 v42, v34, v38, vcc
	v_cndmask_b32_e32 v43, v35, v39, vcc
	ds_bpermute_b32 v40, v186, v40
	ds_bpermute_b32 v41, v186, v41
	ds_bpermute_b32 v42, v186, v42
	ds_bpermute_b32 v43, v186, v43
	v_mfma_f32_16x16x32_bf16 v[28:31], v[144:147], v[112:115], v[28:31]
	s_waitcnt lgkmcnt(3)
	v_cndmask_b32_e32 v32, v40, v32, vcc
	v_cndmask_b32_e32 v36, v36, v40, vcc
	s_waitcnt lgkmcnt(2)
	v_cndmask_b32_e32 v33, v41, v33, vcc
	v_cndmask_b32_e32 v37, v37, v41, vcc
	s_waitcnt lgkmcnt(1)
	v_cndmask_b32_e32 v34, v42, v34, vcc
	v_cndmask_b32_e32 v38, v38, v42, vcc
	s_waitcnt lgkmcnt(0)
	v_cndmask_b32_e32 v35, v43, v35, vcc
	v_cndmask_b32_e32 v39, v39, v43, vcc
	v_cvt_pk_bf16_f32 v32, v32, v33
	v_cvt_pk_bf16_f32 v33, v34, v35
	v_cvt_pk_bf16_f32 v34, v36, v37
	v_cvt_pk_bf16_f32 v35, v38, v39
	global_store_dwordx4 v[52:53], v[32:35], off offset:64
	v_cndmask_b32_e32 v36, v26, v30, vcc
	v_cndmask_b32_e32 v37, v27, v31, vcc
	v_cndmask_b32_e32 v34, v24, v28, vcc
	v_cndmask_b32_e32 v35, v25, v29, vcc
	ds_bpermute_b32 v34, v186, v34
	ds_bpermute_b32 v35, v186, v35
	ds_bpermute_b32 v36, v186, v36
	ds_bpermute_b32 v37, v186, v37
	v_mfma_f32_16x16x32_bf16 v[16:19], v[160:163], v[112:115], v[124:127]
	v_or_b32_e32 v32, 0x60, v48
	v_ashrrev_i32_e32 v33, 31, v32
	v_lshlrev_b64 v[32:33], 11, v[32:33]
	v_mfma_f32_16x16x32_bf16 v[20:23], v[178:181], v[112:115], v[20:23]
	s_waitcnt lgkmcnt(3)
	v_cndmask_b32_e32 v24, v34, v24, vcc
	v_cndmask_b32_e32 v28, v28, v34, vcc
	s_waitcnt lgkmcnt(2)
	v_cndmask_b32_e32 v25, v35, v25, vcc
	v_cndmask_b32_e32 v29, v29, v35, vcc
	s_waitcnt lgkmcnt(1)
	v_cndmask_b32_e32 v26, v36, v26, vcc
	v_cndmask_b32_e32 v30, v30, v36, vcc
	s_waitcnt lgkmcnt(0)
	v_cndmask_b32_e32 v27, v37, v27, vcc
	v_cndmask_b32_e32 v31, v31, v37, vcc
	v_lshl_add_u64 v[32:33], v[50:51], 0, v[32:33]
	v_cvt_pk_bf16_f32 v24, v24, v25
	v_cvt_pk_bf16_f32 v25, v26, v27
	v_cvt_pk_bf16_f32 v26, v28, v29
	v_cvt_pk_bf16_f32 v27, v30, v31
	global_store_dwordx4 v[32:33], v[24:27], off
	v_mfma_f32_16x16x32_bf16 v[0:3], v[160:163], v[116:119], v[0:3]
	s_nop 0
	v_cndmask_b32_e32 v24, v16, v20, vcc
	v_cndmask_b32_e32 v25, v17, v21, vcc
	v_cndmask_b32_e32 v26, v18, v22, vcc
	v_cndmask_b32_e32 v27, v19, v23, vcc
	ds_bpermute_b32 v24, v186, v24
	ds_bpermute_b32 v25, v186, v25
	ds_bpermute_b32 v26, v186, v26
	ds_bpermute_b32 v27, v186, v27
	v_mfma_f32_16x16x32_bf16 v[4:7], v[178:181], v[116:119], v[68:71]
	s_waitcnt lgkmcnt(3)
	v_cndmask_b32_e32 v16, v24, v16, vcc
	v_cndmask_b32_e32 v20, v20, v24, vcc
	s_waitcnt lgkmcnt(2)
	v_cndmask_b32_e32 v17, v25, v17, vcc
	v_cndmask_b32_e32 v21, v21, v25, vcc
	s_waitcnt lgkmcnt(1)
	v_cndmask_b32_e32 v18, v26, v18, vcc
	v_cndmask_b32_e32 v22, v22, v26, vcc
	s_waitcnt lgkmcnt(0)
	v_cndmask_b32_e32 v19, v27, v19, vcc
	v_cndmask_b32_e32 v23, v23, v27, vcc
	v_cvt_pk_bf16_f32 v16, v16, v17
	v_cvt_pk_bf16_f32 v17, v18, v19
	v_cvt_pk_bf16_f32 v18, v20, v21
	v_cvt_pk_bf16_f32 v19, v22, v23
	global_store_dwordx4 v[32:33], v[16:19], off offset:64
	v_cndmask_b32_e32 v20, v10, v14, vcc
	v_cndmask_b32_e32 v21, v11, v15, vcc
	v_cndmask_b32_e32 v18, v8, v12, vcc
	v_cndmask_b32_e32 v19, v9, v13, vcc
	ds_bpermute_b32 v18, v186, v18
	ds_bpermute_b32 v19, v186, v19
	ds_bpermute_b32 v20, v186, v20
	ds_bpermute_b32 v21, v186, v21
	v_or_b32_e32 v16, 0x70, v48
	v_ashrrev_i32_e32 v17, 31, v16
	v_lshlrev_b64 v[16:17], 11, v[16:17]
	s_waitcnt lgkmcnt(3)
	v_cndmask_b32_e32 v8, v18, v8, vcc
	v_cndmask_b32_e32 v12, v12, v18, vcc
	s_waitcnt lgkmcnt(2)
	v_cndmask_b32_e32 v9, v19, v9, vcc
	v_cndmask_b32_e32 v13, v13, v19, vcc
	s_waitcnt lgkmcnt(1)
	v_cndmask_b32_e32 v10, v20, v10, vcc
	v_cndmask_b32_e32 v14, v14, v20, vcc
	s_waitcnt lgkmcnt(0)
	v_cndmask_b32_e32 v11, v21, v11, vcc
	v_cndmask_b32_e32 v15, v15, v21, vcc
	v_lshl_add_u64 v[16:17], v[50:51], 0, v[16:17]
	v_cvt_pk_bf16_f32 v8, v8, v9
	v_cvt_pk_bf16_f32 v9, v10, v11
	v_cvt_pk_bf16_f32 v10, v12, v13
	v_cvt_pk_bf16_f32 v11, v14, v15
	global_store_dwordx4 v[16:17], v[8:11], off
	s_nop 1
	v_cndmask_b32_e32 v8, v0, v4, vcc
	v_cndmask_b32_e32 v9, v1, v5, vcc
	v_cndmask_b32_e32 v10, v2, v6, vcc
	v_cndmask_b32_e32 v11, v3, v7, vcc
	ds_bpermute_b32 v8, v186, v8
	ds_bpermute_b32 v9, v186, v9
	ds_bpermute_b32 v10, v186, v10
	ds_bpermute_b32 v11, v186, v11
	s_waitcnt lgkmcnt(3)
	v_cndmask_b32_e32 v0, v8, v0, vcc
	v_cndmask_b32_e32 v4, v4, v8, vcc
	s_waitcnt lgkmcnt(2)
	v_cndmask_b32_e32 v1, v9, v1, vcc
	v_cndmask_b32_e32 v5, v5, v9, vcc
	s_waitcnt lgkmcnt(1)
	v_cndmask_b32_e32 v2, v10, v2, vcc
	v_cndmask_b32_e32 v6, v6, v10, vcc
	s_waitcnt lgkmcnt(0)
	v_cndmask_b32_e32 v3, v11, v3, vcc
	v_cndmask_b32_e32 v7, v7, v11, vcc
	v_cvt_pk_bf16_f32 v0, v0, v1
	v_cvt_pk_bf16_f32 v1, v2, v3
	v_cvt_pk_bf16_f32 v2, v4, v5
	v_cvt_pk_bf16_f32 v3, v6, v7
	global_store_dwordx4 v[16:17], v[0:3], off offset:64
	s_load_dword s6, s[6:7], 0x0
	s_waitcnt lgkmcnt(0)
	s_add_i32 s8, s6, s8
	s_cmpk_gt_i32 s8, 0xff
	s_cbranch_scc0 .LBB0_801

.LBB0_1040:
	s_add_i32 s14, s12, -1
	s_bitcmp1_b32 s14, 0
	s_cselect_b32 s13, 0x9000, 0
	s_bitcmp1_b32 s12, 0
	s_cselect_b32 s15, 0x9000, 0
	v_lshlrev_b32_e32 v112, 1, v151
	v_lshlrev_b32_e32 v113, 1, v146
	v_add3_u32 v112, s15, v112, v113
	s_waitcnt vmcnt(7)
	ds_write_b128 v112, v[16:19]
	v_lshlrev_b32_e32 v16, 1, v153
	v_lshlrev_b32_e32 v17, 1, v152
	v_add3_u32 v16, s15, v16, v17
	s_waitcnt vmcnt(5)
	ds_write_b128 v16, v[20:23]
	v_lshlrev_b32_e32 v16, 1, v155
	v_lshlrev_b32_e32 v17, 1, v156
	v_add3_u32 v16, s15, v16, v17
	ds_write_b128 v16, v[32:35]
	v_lshlrev_b32_e32 v16, 1, v157
	v_lshlrev_b32_e32 v17, 1, v160
	v_add3_u32 v16, s15, v16, v17
	s_waitcnt vmcnt(4)
	ds_write_b128 v16, v[44:47]
	v_lshlrev_b32_e32 v16, 1, v159
	v_lshlrev_b32_e32 v17, 1, v162
	v_add3_u32 v16, s15, v16, v17
	s_waitcnt vmcnt(3)
	ds_write_b128 v16, v[60:63] offset:18432
	v_lshlrev_b32_e32 v16, 1, v161
	v_lshlrev_b32_e32 v17, 1, v166
	v_add3_u32 v16, s15, v16, v17
	s_waitcnt vmcnt(2)
	ds_write_b128 v16, v[52:55] offset:18432
	v_lshlrev_b32_e32 v16, 1, v163
	v_lshlrev_b32_e32 v17, 1, v170
	v_add3_u32 v16, s15, v16, v17
	s_waitcnt vmcnt(1)
	ds_write_b128 v16, v[56:59] offset:18432
	v_lshlrev_b32_e32 v16, 1, v167
	v_lshlrev_b32_e32 v17, 1, v174
	s_min_u32 s14, s14, 17
	v_add3_u32 v16, s15, v16, v17
	s_lshl_b32 s15, s14, 6
	s_addk_i32 s15, 0x80
	s_waitcnt vmcnt(0)
	ds_write_b128 v16, v[48:51] offset:18432
	v_add_u32_e32 v16, s15, v144
	v_add_u32_e32 v18, s15, v150
	v_add_u32_e32 v32, s15, v154
	v_add_u32_e32 v34, s15, v158
	v_ashrrev_i32_e32 v17, 31, v16
	v_ashrrev_i32_e32 v19, 31, v18
	v_ashrrev_i32_e32 v33, 31, v32
	v_ashrrev_i32_e32 v35, 31, v34
	v_lshlrev_b64 v[16:17], 11, v[16:17]
	v_lshlrev_b64 v[18:19], 11, v[18:19]
	v_lshlrev_b64 v[32:33], 11, v[32:33]
	v_lshlrev_b64 v[34:35], 11, v[34:35]
	s_lshl_b32 s36, s14, 7
	v_lshl_add_u64 v[16:17], v[180:181], 0, v[16:17]
	v_lshl_add_u64 v[20:21], v[182:183], 0, v[18:19]
	v_lshl_add_u64 v[32:33], v[184:185], 0, v[32:33]
	v_lshl_add_u64 v[44:45], v[186:187], 0, v[34:35]
	v_lshl_add_u64 v[48:49], v[164:165], 0, s[36:37]
	v_lshl_add_u64 v[50:51], v[168:169], 0, s[36:37]
	global_load_dwordx4 v[16:19], v[16:17], off
	s_nop 0
	global_load_dwordx4 v[20:23], v[20:21], off
	s_nop 0
	global_load_dwordx4 v[32:35], v[32:33], off
	s_nop 0
	global_load_dwordx4 v[44:47], v[44:45], off
	s_nop 0
	global_load_dwordx4 v[60:63], v[48:49], off offset:256
	global_load_dwordx4 v[52:55], v[50:51], off offset:256
	v_lshl_add_u64 v[48:49], v[172:173], 0, s[36:37]
	v_lshl_add_u64 v[50:51], v[178:179], 0, s[36:37]
	global_load_dwordx4 v[56:59], v[48:49], off offset:256
	s_nop 0
	global_load_dwordx4 v[48:51], v[50:51], off offset:256
	v_lshlrev_b32_e32 v116, 1, v214
	v_add3_u32 v217, s13, v211, v116
	ds_read_b128 v[116:119], v217
	ds_read_b128 v[120:123], v217 offset:128
	ds_read_b128 v[124:127], v217 offset:4608
	v_xor_b32_e32 v112, 0x80000000, v213
	v_xor_b32_e32 v128, 0x80000000, v212
	v_mov_b32_e32 v113, v112
	v_mov_b32_e32 v114, v112
	v_mov_b32_e32 v115, v112
	v_mov_b32_e32 v129, v128
	v_mov_b32_e32 v130, v128
	v_mov_b32_e32 v131, v128
	s_waitcnt lgkmcnt(2)
	v_mfma_f32_16x16x32_bf16 v[116:119], v[116:119], v[12:15], v[112:115]
	ds_read_b128 v[132:135], v217 offset:4736
	s_waitcnt lgkmcnt(2)
	v_mfma_f32_16x16x32_bf16 v[120:123], v[120:123], v[8:11], v[128:131]
	ds_read_b128 v[136:139], v217 offset:9216
	s_waitcnt lgkmcnt(2)
	v_mfma_f32_16x16x32_bf16 v[190:193], v[124:127], v[12:15], v[112:115]
	ds_read_b128 v[124:127], v217 offset:9344
	s_waitcnt lgkmcnt(2)
	v_mfma_f32_16x16x32_bf16 v[132:135], v[132:135], v[8:11], v[128:131]
	ds_read_b128 v[140:143], v217 offset:13824
	s_waitcnt lgkmcnt(2)
	v_mfma_f32_16x16x32_bf16 v[194:197], v[136:139], v[12:15], v[112:115]
	ds_read_b128 v[136:139], v217 offset:13952
	s_waitcnt lgkmcnt(2)
	v_mfma_f32_16x16x32_bf16 v[198:201], v[124:127], v[8:11], v[128:131]
	ds_read_b128 v[124:127], v217 offset:64
	s_waitcnt lgkmcnt(2)
	v_mfma_f32_16x16x32_bf16 v[112:115], v[140:143], v[12:15], v[112:115]
	ds_read_b128 v[204:207], v217 offset:192
	s_waitcnt lgkmcnt(2)
	v_mfma_f32_16x16x32_bf16 v[218:221], v[136:139], v[8:11], v[128:131]
	s_nop 2
	ds_read_b128 v[128:131], v217 offset:4672
	s_waitcnt lgkmcnt(2)
	v_mfma_f32_16x16x32_bf16 v[140:143], v[124:127], v[4:7], v[116:119]
	s_nop 2
	ds_read_b128 v[116:119], v217 offset:4800
	s_waitcnt lgkmcnt(2)
	v_mfma_f32_16x16x32_bf16 v[124:127], v[204:207], v[0:3], v[120:123]
	ds_read_b128 v[204:207], v217 offset:9280
	s_waitcnt lgkmcnt(2)
	v_mfma_f32_16x16x32_bf16 v[136:139], v[128:131], v[4:7], v[190:193]
	ds_read_b128 v[128:131], v217 offset:9408
	s_waitcnt lgkmcnt(2)
	v_mfma_f32_16x16x32_bf16 v[120:123], v[116:119], v[0:3], v[132:135]
	ds_read_b128 v[190:193], v217 offset:13888
	s_waitcnt lgkmcnt(2)
	v_mfma_f32_16x16x32_bf16 v[132:135], v[204:207], v[4:7], v[194:197]
	s_nop 2
	ds_read_b128 v[194:197], v217 offset:14016
	s_waitcnt lgkmcnt(2)
	v_mfma_f32_16x16x32_bf16 v[116:119], v[128:131], v[0:3], v[198:201]
	s_waitcnt lgkmcnt(1)
	v_mfma_f32_16x16x32_bf16 v[128:131], v[190:193], v[4:7], v[112:115]
	s_waitcnt lgkmcnt(0)
	v_mfma_f32_16x16x32_bf16 v[112:115], v[194:197], v[0:3], v[218:221]
	v_max_f32_e32 v190, v141, v141
	v_max_f32_e32 v191, v140, v140
	v_max_f32_e32 v204, v125, v125
	v_max_f32_e32 v205, v124, v124
	v_max_f32_e32 v190, v191, v190
	v_max_f32_e32 v204, v205, v204
	v_max3_f32 v190, v190, v142, v143
	v_max3_f32 v204, v204, v126, v127
	v_max3_f32 v190, v190, v136, v137
	v_max3_f32 v204, v204, v120, v121
	v_max3_f32 v190, v190, v138, v139
	v_max3_f32 v204, v204, v122, v123
	v_max3_f32 v190, v190, v132, v133
	v_max3_f32 v204, v204, v116, v117
	v_max3_f32 v190, v190, v134, v135
	v_max3_f32 v204, v204, v118, v119
	v_max3_f32 v190, v190, v128, v129
	v_max3_f32 v204, v204, v112, v113
	v_max3_f32 v190, v190, v130, v131
	v_max3_f32 v204, v204, v114, v115
	ds_bpermute_b32 v191, v145, v190
	ds_bpermute_b32 v205, v145, v204
	s_waitcnt lgkmcnt(0)
	v_max_f32_e32 v191, v191, v191
	v_max_f32_e32 v205, v205, v205
	v_max_f32_e32 v190, v190, v191
	v_max_f32_e32 v204, v204, v205
	ds_bpermute_b32 v191, v147, v190
	ds_bpermute_b32 v205, v147, v204
	s_waitcnt lgkmcnt(0)
	v_max_f32_e32 v191, v191, v191
	v_max_f32_e32 v205, v205, v205
	v_max_f32_e32 v217, v190, v191
	v_max_f32_e32 v206, v204, v205
	v_cmp_lt_f32_e32 vcc, s79, v217
	s_cbranch_vccz .LBB0_1042
	s_nop 0
	v_cndmask_b32_e32 v191, 0, v217, vcc
	v_exp_f32_e64 v190, -v191
	v_add_f32_e32 v213, v213, v191
	v_sub_f32_e32 v140, v140, v191
	v_sub_f32_e32 v141, v141, v191
	v_pk_mul_f32 v[30:31], v[30:31], v[190:191] op_sel_hi:[1,0]
	v_pk_mul_f32 v[28:29], v[28:29], v[190:191] op_sel_hi:[1,0]
	v_pk_mul_f32 v[42:43], v[42:43], v[190:191] op_sel_hi:[1,0]
	v_pk_mul_f32 v[40:41], v[40:41], v[190:191] op_sel_hi:[1,0]
	v_pk_mul_f32 v[70:71], v[70:71], v[190:191] op_sel_hi:[1,0]
	v_pk_mul_f32 v[68:69], v[68:69], v[190:191] op_sel_hi:[1,0]
	v_pk_mul_f32 v[78:79], v[78:79], v[190:191] op_sel_hi:[1,0]
	v_pk_mul_f32 v[76:77], v[76:77], v[190:191] op_sel_hi:[1,0]
	v_pk_mul_f32 v[86:87], v[86:87], v[190:191] op_sel_hi:[1,0]
	v_pk_mul_f32 v[84:85], v[84:85], v[190:191] op_sel_hi:[1,0]
	v_pk_mul_f32 v[94:95], v[94:95], v[190:191] op_sel_hi:[1,0]
	v_pk_mul_f32 v[92:93], v[92:93], v[190:191] op_sel_hi:[1,0]
	v_pk_mul_f32 v[102:103], v[102:103], v[190:191] op_sel_hi:[1,0]
	v_pk_mul_f32 v[100:101], v[100:101], v[190:191] op_sel_hi:[1,0]
	v_pk_mul_f32 v[110:111], v[110:111], v[190:191] op_sel_hi:[1,0]
	v_pk_mul_f32 v[108:109], v[108:109], v[190:191] op_sel_hi:[1,0]
	v_mul_f32_e32 v171, v171, v190
	v_sub_f32_e32 v142, v142, v191
	v_sub_f32_e32 v143, v143, v191
	v_sub_f32_e32 v136, v136, v191
	v_sub_f32_e32 v137, v137, v191
	v_sub_f32_e32 v138, v138, v191
	v_sub_f32_e32 v139, v139, v191
	v_sub_f32_e32 v132, v132, v191
	v_sub_f32_e32 v133, v133, v191
	v_sub_f32_e32 v134, v134, v191
	v_sub_f32_e32 v135, v135, v191
	v_sub_f32_e32 v128, v128, v191
	v_sub_f32_e32 v129, v129, v191
	v_sub_f32_e32 v130, v130, v191
	v_sub_f32_e32 v131, v131, v191
.LBB0_1042:
	v_mov_b32_e32 v217, v206
	v_cmp_lt_f32_e32 vcc, s79, v206
	s_cbranch_vccz .LBB0_1039
	s_nop 0
	v_cndmask_b32_e32 v191, 0, v217, vcc
	v_exp_f32_e64 v190, -v191
	v_add_f32_e32 v212, v212, v191
	v_sub_f32_e32 v124, v124, v191
	v_sub_f32_e32 v125, v125, v191
	v_pk_mul_f32 v[26:27], v[26:27], v[190:191] op_sel_hi:[1,0]
	v_pk_mul_f32 v[24:25], v[24:25], v[190:191] op_sel_hi:[1,0]
	v_pk_mul_f32 v[38:39], v[38:39], v[190:191] op_sel_hi:[1,0]
	v_pk_mul_f32 v[36:37], v[36:37], v[190:191] op_sel_hi:[1,0]
	v_pk_mul_f32 v[66:67], v[66:67], v[190:191] op_sel_hi:[1,0]
	v_pk_mul_f32 v[64:65], v[64:65], v[190:191] op_sel_hi:[1,0]
	v_pk_mul_f32 v[74:75], v[74:75], v[190:191] op_sel_hi:[1,0]
	v_pk_mul_f32 v[72:73], v[72:73], v[190:191] op_sel_hi:[1,0]
	v_pk_mul_f32 v[82:83], v[82:83], v[190:191] op_sel_hi:[1,0]
	v_pk_mul_f32 v[80:81], v[80:81], v[190:191] op_sel_hi:[1,0]
	v_pk_mul_f32 v[90:91], v[90:91], v[190:191] op_sel_hi:[1,0]
	v_pk_mul_f32 v[88:89], v[88:89], v[190:191] op_sel_hi:[1,0]
	v_pk_mul_f32 v[98:99], v[98:99], v[190:191] op_sel_hi:[1,0]
	v_pk_mul_f32 v[96:97], v[96:97], v[190:191] op_sel_hi:[1,0]
	v_pk_mul_f32 v[106:107], v[106:107], v[190:191] op_sel_hi:[1,0]
	v_pk_mul_f32 v[104:105], v[104:105], v[190:191] op_sel_hi:[1,0]
	v_mul_f32_e32 v175, v175, v190
	v_sub_f32_e32 v126, v126, v191
	v_sub_f32_e32 v127, v127, v191
	v_sub_f32_e32 v120, v120, v191
	v_sub_f32_e32 v121, v121, v191
	v_sub_f32_e32 v122, v122, v191
	v_sub_f32_e32 v123, v123, v191
	v_sub_f32_e32 v116, v116, v191
	v_sub_f32_e32 v117, v117, v191
	v_sub_f32_e32 v118, v118, v191
	v_sub_f32_e32 v119, v119, v191
	v_sub_f32_e32 v112, v112, v191
	v_sub_f32_e32 v113, v113, v191
	v_sub_f32_e32 v114, v114, v191
	v_sub_f32_e32 v115, v115, v191
	s_branch .LBB0_1039

.LBB0_1064:
	s_ashr_i32 s22, s52, 3
	s_lshl_b32 s31, s22, 1
	s_and_b32 s30, s22, -16
	s_and_b32 s31, s31, 14
	s_or_b32 s30, s31, s30
	s_bfe_u32 s31, s22, 0x10003
	s_or_b32 s23, s22, 63
	s_or_b32 s30, s30, s31
	s_cmpk_lt_i32 s23, 0x80
	s_cselect_b32 s22, s30, s22
	s_lshl_b32 s23, s52, 7
	s_and_b32 s23, s23, 0x380
	s_add_i32 s22, s22, s23
	s_ashr_i32 s23, s22, 31
	s_lshr_b32 s30, s23, 27
	s_add_i32 s30, s22, s30
	s_ashr_i32 s31, s30, 5
	s_andn2_b32 s30, s30, 31
	s_sub_i32 s30, s22, s30
	s_lshr_b32 s23, s23, 25
	s_add_i32 s22, s22, s23
	s_ashr_i32 s23, s30, 31
	s_lshr_b32 s23, s23, 29
	s_ashr_i32 s22, s22, 7
	s_add_i32 s23, s30, s23
	s_ashr_i32 s23, s23, 3
	s_lshl_b32 s38, s22, 2
	s_add_i32 s38, s38, s23
	s_sub_i32 s31, s31, s38
	s_lshl_b32 s42, s31, 3
	s_add_i32 s42, s42, s30
	s_lshl_b32 s22, s22, 10
	s_lshl_b32 s38, s23, 8
	s_add_i32 s38, s38, s22
	s_lshl_b32 s53, s42, 7
	s_ashr_i32 s44, s42, 3
	s_cmp_lg_u32 s44, 2
	s_cselect_b64 s[22:23], -1, 0
	s_mov_b64 s[30:31], -1
	s_and_b64 vcc, exec, s[22:23]
	s_mov_b32 s39, 0x30000
	s_cbranch_vccz .LBB0_1068
	v_mov_b32_e32 v8, v188
	s_mov_b32 s30, 0x20000
	v_ashrrev_i32_e32 v9, 3, v8
	v_lshlrev_b32_e32 v4, 4, v8
	v_and_b32_e32 v176, 0x70, v4
	v_add_u32_e32 v4, s53, v9
	v_add_u32_e32 v0, s38, v9
	v_ashrrev_i32_e32 v5, 31, v4
	v_ashrrev_i32_e32 v1, 31, v0
	v_lshlrev_b64 v[4:5], 11, v[4:5]
	v_xor_b32_e32 v10, v9, v8
	v_lshlrev_b64 v[0:1], 11, v[0:1]
	v_lshl_add_u64 v[6:7], s[2:3], 0, v[4:5]
	v_lshlrev_b32_e32 v10, 4, v10
	v_lshl_add_u64 v[2:3], s[0:1], 0, v[0:1]
	v_lshl_add_u64 v[6:7], v[6:7], 0, v[176:177]
	v_and_b32_e32 v10, 0x70, v10
	v_lshl_add_u64 v[2:3], v[2:3], 0, v[176:177]
	v_lshl_or_b32 v176, v9, 7, v10
	v_lshlrev_b32_e32 v12, 7, v8
	v_lshrrev_b32_e32 v9, 4, v8
	v_bfe_u32 v14, v8, 4, 2
	v_and_b32_e32 v15, 7, v8
	v_add_co_u32_e32 v8, vcc, s39, v6
	v_bitop3_b32 v16, v9, v15, 3 bitop3:0x6c
	s_nop 0
	v_addc_co_u32_e32 v9, vcc, 0, v7, vcc
	v_add_co_u32_e32 v10, vcc, s30, v6
	s_mov_b32 s31, 0x10000
	s_nop 0
	v_addc_co_u32_e32 v11, vcc, 0, v7, vcc
	global_load_dwordx4 v[20:23], v[8:9], off
	global_load_dwordx4 v[24:27], v[10:11], off
	v_add_co_u32_e32 v8, vcc, s31, v6
	s_mov_b32 s40, 0x70000
	s_nop 0
	v_addc_co_u32_e32 v9, vcc, 0, v7, vcc
	v_add_co_u32_e32 v10, vcc, s40, v2
	s_mov_b32 s40, 0x60000
	s_nop 0
	v_addc_co_u32_e32 v11, vcc, 0, v3, vcc
	global_load_dwordx4 v[40:43], v[8:9], off
	global_load_dwordx4 v[48:51], v[10:11], off
	v_add_co_u32_e32 v8, vcc, s40, v2
	s_mov_b32 s40, 0x50000
	s_nop 0
	v_addc_co_u32_e32 v9, vcc, 0, v3, vcc
	v_add_co_u32_e32 v10, vcc, s40, v2
	s_mov_b32 s40, 0x40000
	s_nop 0
	v_addc_co_u32_e32 v11, vcc, 0, v3, vcc
	global_load_dwordx4 v[60:63], v[8:9], off
	global_load_dwordx4 v[68:71], v[10:11], off
	v_add_co_u32_e32 v8, vcc, s40, v2
	v_and_b32_e32 v13, 0xffffc780, v12
	s_nop 0
	v_addc_co_u32_e32 v9, vcc, 0, v3, vcc
	v_add_co_u32_e32 v10, vcc, s39, v2
	v_and_b32_e32 v12, 0x2780, v12
	s_nop 0
	v_addc_co_u32_e32 v11, vcc, 0, v3, vcc
	global_load_dwordx4 v[80:83], v[8:9], off
	global_load_dwordx4 v[88:91], v[10:11], off
	v_add_co_u32_e32 v8, vcc, s30, v2
	v_bitop3_b32 v14, v14, v15, 4 bitop3:0x36
	s_nop 0
	v_addc_co_u32_e32 v9, vcc, 0, v3, vcc
	v_add_co_u32_e32 v10, vcc, s31, v2
	v_mov_b32_e32 v140, 0
	s_nop 0
	v_addc_co_u32_e32 v11, vcc, 0, v3, vcc
	global_load_dwordx4 v[104:107], v[8:9], off
	global_load_dwordx4 v[112:115], v[10:11], off
	global_load_dwordx4 v[100:103], v[6:7], off
	global_load_dwordx4 v[116:119], v[2:3], off
	v_lshlrev_b32_e32 v2, 4, v16
	v_or_b32_e32 v185, v13, v2
	v_or_b32_e32 v184, v12, v2
	v_lshlrev_b32_e32 v2, 4, v14
	v_or_b32_e32 v183, v13, v2
	v_or_b32_e32 v182, v12, v2
	v_lshlrev_b32_e32 v2, 4, v15
	v_or_b32_e32 v0, v0, v2
	v_or_b32_e32 v4, v4, v2
	v_lshl_add_u64 v[178:179], s[34:35], 0, v[0:1]
	v_lshl_add_u64 v[180:181], s[50:51], 0, v[4:5]
	s_mov_b64 s[30:31], 0
	v_mov_b32_e32 v141, v140
	v_mov_b32_e32 v142, v140
	v_mov_b32_e32 v143, v140
	v_mov_b32_e32 v0, v140
	v_mov_b32_e32 v1, v140
	v_mov_b32_e32 v2, v140
	v_mov_b32_e32 v3, v140
	v_mov_b32_e32 v4, v140
	v_mov_b32_e32 v5, v140
	v_mov_b32_e32 v6, v140
	v_mov_b32_e32 v7, v140
	v_mov_b32_e32 v8, v140
	v_mov_b32_e32 v9, v140
	v_mov_b32_e32 v10, v140
	v_mov_b32_e32 v11, v140
	v_mov_b32_e32 v12, v140
	v_mov_b32_e32 v13, v140
	v_mov_b32_e32 v14, v140
	v_mov_b32_e32 v15, v140
	v_mov_b32_e32 v16, v140
	v_mov_b32_e32 v17, v140
	v_mov_b32_e32 v18, v140
	v_mov_b32_e32 v19, v140
	v_mov_b32_e32 v28, v140
	v_mov_b32_e32 v29, v140
	v_mov_b32_e32 v30, v140
	v_mov_b32_e32 v31, v140
	v_mov_b32_e32 v32, v140
	v_mov_b32_e32 v33, v140
	v_mov_b32_e32 v34, v140
	v_mov_b32_e32 v35, v140
	v_mov_b32_e32 v36, v140
	v_mov_b32_e32 v37, v140
	v_mov_b32_e32 v38, v140
	v_mov_b32_e32 v39, v140
	v_mov_b32_e32 v44, v140
	v_mov_b32_e32 v45, v140
	v_mov_b32_e32 v46, v140
	v_mov_b32_e32 v47, v140
	v_mov_b32_e32 v52, v140
	v_mov_b32_e32 v53, v140
	v_mov_b32_e32 v54, v140
	v_mov_b32_e32 v55, v140
	v_mov_b32_e32 v56, v140
	v_mov_b32_e32 v57, v140
	v_mov_b32_e32 v58, v140
	v_mov_b32_e32 v59, v140
	v_mov_b32_e32 v64, v140
	v_mov_b32_e32 v65, v140
	v_mov_b32_e32 v66, v140
	v_mov_b32_e32 v67, v140
	v_mov_b32_e32 v72, v140
	v_mov_b32_e32 v73, v140
	v_mov_b32_e32 v74, v140
	v_mov_b32_e32 v75, v140
	v_mov_b32_e32 v76, v140
	v_mov_b32_e32 v77, v140
	v_mov_b32_e32 v78, v140
	v_mov_b32_e32 v79, v140
	v_mov_b32_e32 v84, v140
	v_mov_b32_e32 v85, v140
	v_mov_b32_e32 v86, v140
	v_mov_b32_e32 v87, v140
	v_mov_b32_e32 v92, v140
	v_mov_b32_e32 v93, v140
	v_mov_b32_e32 v94, v140
	v_mov_b32_e32 v95, v140
	v_mov_b32_e32 v96, v140
	v_mov_b32_e32 v97, v140
	v_mov_b32_e32 v98, v140
	v_mov_b32_e32 v99, v140
	v_mov_b32_e32 v108, v140
	v_mov_b32_e32 v109, v140
	v_mov_b32_e32 v110, v140
	v_mov_b32_e32 v111, v140
	v_mov_b32_e32 v120, v140
	v_mov_b32_e32 v121, v140
	v_mov_b32_e32 v122, v140
	v_mov_b32_e32 v123, v140
	v_mov_b32_e32 v124, v140
	v_mov_b32_e32 v125, v140
	v_mov_b32_e32 v126, v140
	v_mov_b32_e32 v127, v140
	v_mov_b32_e32 v128, v140
	v_mov_b32_e32 v129, v140
	v_mov_b32_e32 v130, v140
	v_mov_b32_e32 v131, v140
	v_mov_b32_e32 v132, v140
	v_mov_b32_e32 v133, v140
	v_mov_b32_e32 v134, v140
	v_mov_b32_e32 v135, v140
	v_mov_b32_e32 v136, v140
	v_mov_b32_e32 v137, v140
	v_mov_b32_e32 v138, v140
	v_mov_b32_e32 v139, v140
	v_mov_b32_e32 v144, v140
	v_mov_b32_e32 v145, v140
	v_mov_b32_e32 v146, v140
	v_mov_b32_e32 v147, v140
	v_mov_b32_e32 v148, v140
	v_mov_b32_e32 v149, v140
	v_mov_b32_e32 v150, v140
	v_mov_b32_e32 v151, v140
	v_mov_b32_e32 v152, v140
	v_mov_b32_e32 v153, v140
	v_mov_b32_e32 v154, v140
	v_mov_b32_e32 v155, v140
	v_mov_b32_e32 v156, v140
	v_mov_b32_e32 v157, v140
	v_mov_b32_e32 v158, v140
	v_mov_b32_e32 v159, v140
	v_mov_b32_e32 v160, v140
	v_mov_b32_e32 v161, v140
	v_mov_b32_e32 v162, v140
	v_mov_b32_e32 v163, v140
	v_mov_b32_e32 v164, v140
	v_mov_b32_e32 v165, v140
	v_mov_b32_e32 v166, v140
	v_mov_b32_e32 v167, v140
	v_mov_b32_e32 v168, v140
	v_mov_b32_e32 v169, v140
	v_mov_b32_e32 v170, v140
	v_mov_b32_e32 v171, v140
	v_mov_b32_e32 v172, v140
	v_mov_b32_e32 v173, v140
	v_mov_b32_e32 v174, v140
	v_mov_b32_e32 v175, v140
	s_mov_b32 s40, 0x820000
	s_mov_b32 s41, 0x830000
	v_readlane_b32 s98, v253, 3
	v_readlane_b32 s99, v253, 4
	v_and_b32_e32 v236, 15, v188
	v_bfe_u32 v237, v188, 4, 2
	v_lshrrev_b32_e32 v238, 2, v236
	v_sub_u32_e32 v238, 0, v238
	v_and_b32_e32 v238, 3, v238
	v_xor_b32_e32 v237, v237, v238
	v_lshlrev_b32_e32 v237, 4, v237
	v_lshl_or_b32 v237, v236, 6, v237
	v_bfe_u32 v238, v188, 7, 1
	v_lshl_or_b32 v185, v238, 13, v237
	v_bfe_u32 v238, v188, 6, 1
	v_lshl_or_b32 v184, v238, 12, v237
	v_add_u32_e32 v184, 0x4000, v184
	v_lshrrev_b32_e32 v236, 3, v188
	v_bfe_u32 v237, v188, 2, 1
	v_lshrrev_b32_e32 v238, 2, v236
	v_sub_u32_e32 v238, 0, v238
	v_and_b32_e32 v238, 3, v238
	v_and_b32_e32 v239, 3, v188
	v_xor_b32_e32 v238, v239, v238
	v_lshlrev_b32_e32 v238, 4, v238
	v_xor_b32_e32 v236, v236, v237
	v_lshl_or_b32 v238, v236, 6, v238
	v_mul_u32_u24_e32 v237, 0x6000, v237
	v_add_u32_e32 v183, v237, v238
	s_mov_b32 m0, 0
	s_sub_u32 vcc_lo, s30, s98
	v_add_u32_e32 v186, vcc_lo, v178
	v_add_u32_e32 v187, vcc_lo, v180
	s_barrier
	s_waitcnt vmcnt(0)
	ds_write_b128 v183, v[116:119]
	ds_write_b128 v183, v[112:115] offset:2048
	ds_write_b128 v183, v[104:107] offset:4096
	ds_write_b128 v183, v[88:91] offset:6144
	ds_write_b128 v183, v[80:83] offset:8192
	ds_write_b128 v183, v[68:71] offset:10240
	ds_write_b128 v183, v[60:63] offset:12288
	ds_write_b128 v183, v[48:51] offset:14336
	ds_write_b128 v183, v[100:103] offset:16384
	ds_write_b128 v183, v[40:43] offset:18432
	ds_write_b128 v183, v[24:27] offset:20480
	ds_write_b128 v183, v[20:23] offset:22528
	v_cmp_gt_u32_e32 vcc, 0x6000, v183
	v_add_u32_e32 v182, 0xc000, v183
	v_add_u32_e32 v183, 0xffffa000, v183
	s_nop 0
	v_cndmask_b32_e32 v183, v183, v182, vcc
	v_add_u32_e32 v116, s26, v186
	global_load_dwordx4 v[116:119], v116, s[98:99] offset:128
	v_add_u32_e32 v112, s27, v186
	global_load_dwordx4 v[112:115], v112, s[98:99] offset:128
	v_add_u32_e32 v104, s20, v186
	global_load_dwordx4 v[104:107], v104, s[98:99] offset:128
	v_add_u32_e32 v88, s21, v186
	global_load_dwordx4 v[88:91], v88, s[98:99] offset:128
	v_add_u32_e32 v80, s56, v186
	global_load_dwordx4 v[80:83], v80, s[98:99] offset:128
	v_add_u32_e32 v68, s57, v186
	global_load_dwordx4 v[68:71], v68, s[98:99] offset:128
	v_add_u32_e32 v60, s24, v186
	global_load_dwordx4 v[60:63], v60, s[98:99] offset:128
	v_add_u32_e32 v48, s96, v186
	global_load_dwordx4 v[48:51], v48, s[98:99] offset:128
	v_add_u32_e32 v100, s25, v187
	global_load_dwordx4 v[100:103], v100, s[98:99] offset:128
	v_add_u32_e32 v40, s33, v187
	global_load_dwordx4 v[40:43], v40, s[98:99] offset:128
	v_add_u32_e32 v24, s40, v187
	global_load_dwordx4 v[24:27], v24, s[98:99] offset:128
	v_add_u32_e32 v20, s41, v187
	global_load_dwordx4 v[20:23], v20, s[98:99] offset:128
	s_add_u32 s30, s30, 0x80
	s_addc_u32 s31, s31, 0
.LBB0_1066:
	s_waitcnt lgkmcnt(0)
	s_barrier
	ds_read_b128 v[236:239], v184
	ds_read_b128 v[240:243], v184 offset:1024
	ds_read_b128 v[244:247], v184 offset:2048
	ds_read_b128 v[248:251], v184 offset:3072
	ds_read_b128 v[204:207], v185
	ds_read_b128 v[208:211], v185 offset:1024
	ds_read_b128 v[212:215], v185 offset:2048
	ds_read_b128 v[216:219], v185 offset:3072
	ds_read_b128 v[220:223], v185 offset:4096
	ds_read_b128 v[224:227], v185 offset:5120
	ds_read_b128 v[228:231], v185 offset:6144
	ds_read_b128 v[232:235], v185 offset:7168
	s_movk_i32 vcc_lo, 0x6000
	s_cmp_eq_u32 m0, 2
	s_cselect_b32 vcc_lo, 0xffff4000, vcc_lo
	s_add_u32 m0, m0, 1
	s_cmp_eq_u32 m0, 3
	s_cselect_b32 m0, 0, m0
	v_add_u32_e32 v185, vcc_lo, v185
	v_add_u32_e32 v184, vcc_lo, v184
	v_xor_b32_e32 v185, 64, v185
	v_xor_b32_e32 v184, 64, v184
	s_waitcnt lgkmcnt(7)
	v_mfma_f32_16x16x32_bf16 v[172:175], v[236:239], v[204:207], v[172:175]
	v_mfma_f32_16x16x32_bf16 v[168:171], v[240:243], v[204:207], v[168:171]
	v_mfma_f32_16x16x32_bf16 v[164:167], v[244:247], v[204:207], v[164:167]
	v_mfma_f32_16x16x32_bf16 v[160:163], v[248:251], v[204:207], v[160:163]
	ds_read_b128 v[204:207], v185
	s_waitcnt lgkmcnt(7)
	v_mfma_f32_16x16x32_bf16 v[156:159], v[236:239], v[208:211], v[156:159]
	v_mfma_f32_16x16x32_bf16 v[152:155], v[240:243], v[208:211], v[152:155]
	v_mfma_f32_16x16x32_bf16 v[148:151], v[244:247], v[208:211], v[148:151]
	v_mfma_f32_16x16x32_bf16 v[144:147], v[248:251], v[208:211], v[144:147]
	ds_read_b128 v[208:211], v185 offset:1024
	s_waitcnt lgkmcnt(7)
	v_mfma_f32_16x16x32_bf16 v[136:139], v[236:239], v[212:215], v[136:139]
	v_mfma_f32_16x16x32_bf16 v[132:135], v[240:243], v[212:215], v[132:135]
	v_mfma_f32_16x16x32_bf16 v[128:131], v[244:247], v[212:215], v[128:131]
	v_mfma_f32_16x16x32_bf16 v[124:127], v[248:251], v[212:215], v[124:127]
	ds_read_b128 v[212:215], v185 offset:2048
	s_waitcnt lgkmcnt(7)
	v_mfma_f32_16x16x32_bf16 v[120:123], v[236:239], v[216:219], v[120:123]
	v_mfma_f32_16x16x32_bf16 v[108:111], v[240:243], v[216:219], v[108:111]
	v_mfma_f32_16x16x32_bf16 v[96:99], v[244:247], v[216:219], v[96:99]
	v_mfma_f32_16x16x32_bf16 v[92:95], v[248:251], v[216:219], v[92:95]
	ds_read_b128 v[216:219], v185 offset:3072
	s_waitcnt lgkmcnt(7)
	v_mfma_f32_16x16x32_bf16 v[84:87], v[236:239], v[220:223], v[84:87]
	v_mfma_f32_16x16x32_bf16 v[76:79], v[240:243], v[220:223], v[76:79]
	v_mfma_f32_16x16x32_bf16 v[72:75], v[244:247], v[220:223], v[72:75]
	v_mfma_f32_16x16x32_bf16 v[64:67], v[248:251], v[220:223], v[64:67]
	ds_read_b128 v[220:223], v185 offset:4096
	s_waitcnt lgkmcnt(7)
	v_mfma_f32_16x16x32_bf16 v[56:59], v[236:239], v[224:227], v[56:59]
	v_mfma_f32_16x16x32_bf16 v[52:55], v[240:243], v[224:227], v[52:55]
	v_mfma_f32_16x16x32_bf16 v[44:47], v[244:247], v[224:227], v[44:47]
	v_mfma_f32_16x16x32_bf16 v[36:39], v[248:251], v[224:227], v[36:39]
	ds_read_b128 v[224:227], v185 offset:5120
	s_waitcnt lgkmcnt(7)
	v_mfma_f32_16x16x32_bf16 v[32:35], v[236:239], v[228:231], v[32:35]
	v_mfma_f32_16x16x32_bf16 v[28:31], v[240:243], v[228:231], v[28:31]
	v_mfma_f32_16x16x32_bf16 v[16:19], v[244:247], v[228:231], v[16:19]
	v_mfma_f32_16x16x32_bf16 v[12:15], v[248:251], v[228:231], v[12:15]
	ds_read_b128 v[228:231], v185 offset:6144
	s_waitcnt lgkmcnt(7)
	v_mfma_f32_16x16x32_bf16 v[8:11], v[236:239], v[232:235], v[8:11]
	v_mfma_f32_16x16x32_bf16 v[4:7], v[240:243], v[232:235], v[4:7]
	v_mfma_f32_16x16x32_bf16 v[0:3], v[244:247], v[232:235], v[0:3]
	v_mfma_f32_16x16x32_bf16 v[140:143], v[248:251], v[232:235], v[140:143]
	ds_read_b128 v[232:235], v185 offset:7168
	ds_read_b128 v[236:239], v184
	ds_read_b128 v[240:243], v184 offset:1024
	ds_read_b128 v[244:247], v184 offset:2048
	ds_read_b128 v[248:251], v184 offset:3072
	s_movk_i32 vcc_lo, 0x6000
	s_cmp_eq_u32 m0, 2
	s_cselect_b32 vcc_lo, 0xffff4000, vcc_lo
	s_add_u32 m0, m0, 1
	s_cmp_eq_u32 m0, 3
	s_cselect_b32 m0, 0, m0
	v_add_u32_e32 v185, vcc_lo, v185
	v_add_u32_e32 v184, vcc_lo, v184
	v_xor_b32_e32 v185, 64, v185
	v_xor_b32_e32 v184, 64, v184
	s_sub_u32 vcc_lo, s30, s98
	v_add_u32_e32 v186, vcc_lo, v178
	v_add_u32_e32 v187, vcc_lo, v180
	s_barrier
	s_waitcnt lgkmcnt(0)
	v_mfma_f32_16x16x32_bf16 v[172:175], v[236:239], v[204:207], v[172:175]
	v_mfma_f32_16x16x32_bf16 v[168:171], v[240:243], v[204:207], v[168:171]
	v_mfma_f32_16x16x32_bf16 v[164:167], v[244:247], v[204:207], v[164:167]
	v_mfma_f32_16x16x32_bf16 v[160:163], v[248:251], v[204:207], v[160:163]
	s_waitcnt vmcnt(11)
	ds_write_b128 v183, v[116:119]
	v_add_u32_e32 v116, s26, v186
	global_load_dwordx4 v[116:119], v116, s[98:99] offset:128
	s_waitcnt vmcnt(11)
	ds_write_b128 v183, v[112:115] offset:2048
	v_add_u32_e32 v112, s27, v186
	global_load_dwordx4 v[112:115], v112, s[98:99] offset:128
	v_mfma_f32_16x16x32_bf16 v[156:159], v[236:239], v[208:211], v[156:159]
	v_mfma_f32_16x16x32_bf16 v[152:155], v[240:243], v[208:211], v[152:155]
	v_mfma_f32_16x16x32_bf16 v[148:151], v[244:247], v[208:211], v[148:151]
	v_mfma_f32_16x16x32_bf16 v[144:147], v[248:251], v[208:211], v[144:147]
	s_waitcnt vmcnt(11)
	ds_write_b128 v183, v[104:107] offset:4096
	v_add_u32_e32 v104, s20, v186
	global_load_dwordx4 v[104:107], v104, s[98:99] offset:128
	v_mfma_f32_16x16x32_bf16 v[136:139], v[236:239], v[212:215], v[136:139]
	v_mfma_f32_16x16x32_bf16 v[132:135], v[240:243], v[212:215], v[132:135]
	v_mfma_f32_16x16x32_bf16 v[128:131], v[244:247], v[212:215], v[128:131]
	v_mfma_f32_16x16x32_bf16 v[124:127], v[248:251], v[212:215], v[124:127]
	s_waitcnt vmcnt(11)
	ds_write_b128 v183, v[88:91] offset:6144
	v_add_u32_e32 v88, s21, v186
	global_load_dwordx4 v[88:91], v88, s[98:99] offset:128
	s_waitcnt vmcnt(11)
	ds_write_b128 v183, v[80:83] offset:8192
	v_add_u32_e32 v80, s56, v186
	global_load_dwordx4 v[80:83], v80, s[98:99] offset:128
	v_mfma_f32_16x16x32_bf16 v[120:123], v[236:239], v[216:219], v[120:123]
	v_mfma_f32_16x16x32_bf16 v[108:111], v[240:243], v[216:219], v[108:111]
	v_mfma_f32_16x16x32_bf16 v[96:99], v[244:247], v[216:219], v[96:99]
	v_mfma_f32_16x16x32_bf16 v[92:95], v[248:251], v[216:219], v[92:95]
	s_waitcnt vmcnt(11)
	ds_write_b128 v183, v[68:71] offset:10240
	v_add_u32_e32 v68, s57, v186
	global_load_dwordx4 v[68:71], v68, s[98:99] offset:128
	v_mfma_f32_16x16x32_bf16 v[84:87], v[236:239], v[220:223], v[84:87]
	v_mfma_f32_16x16x32_bf16 v[76:79], v[240:243], v[220:223], v[76:79]
	v_mfma_f32_16x16x32_bf16 v[72:75], v[244:247], v[220:223], v[72:75]
	v_mfma_f32_16x16x32_bf16 v[64:67], v[248:251], v[220:223], v[64:67]
	s_waitcnt vmcnt(11)
	ds_write_b128 v183, v[60:63] offset:12288
	v_add_u32_e32 v60, s24, v186
	global_load_dwordx4 v[60:63], v60, s[98:99] offset:128
	s_waitcnt vmcnt(11)
	ds_write_b128 v183, v[48:51] offset:14336
	v_add_u32_e32 v48, s96, v186
	global_load_dwordx4 v[48:51], v48, s[98:99] offset:128
	v_mfma_f32_16x16x32_bf16 v[56:59], v[236:239], v[224:227], v[56:59]
	v_mfma_f32_16x16x32_bf16 v[52:55], v[240:243], v[224:227], v[52:55]
	v_mfma_f32_16x16x32_bf16 v[44:47], v[244:247], v[224:227], v[44:47]
	v_mfma_f32_16x16x32_bf16 v[36:39], v[248:251], v[224:227], v[36:39]
	s_waitcnt vmcnt(11)
	ds_write_b128 v183, v[100:103] offset:16384
	v_add_u32_e32 v100, s25, v187
	global_load_dwordx4 v[100:103], v100, s[98:99] offset:128
	v_mfma_f32_16x16x32_bf16 v[32:35], v[236:239], v[228:231], v[32:35]
	v_mfma_f32_16x16x32_bf16 v[28:31], v[240:243], v[228:231], v[28:31]
	v_mfma_f32_16x16x32_bf16 v[16:19], v[244:247], v[228:231], v[16:19]
	v_mfma_f32_16x16x32_bf16 v[12:15], v[248:251], v[228:231], v[12:15]
	s_waitcnt vmcnt(11)
	ds_write_b128 v183, v[40:43] offset:18432
	v_add_u32_e32 v40, s33, v187
	global_load_dwordx4 v[40:43], v40, s[98:99] offset:128
	s_waitcnt vmcnt(11)
	ds_write_b128 v183, v[24:27] offset:20480
	v_add_u32_e32 v24, s40, v187
	global_load_dwordx4 v[24:27], v24, s[98:99] offset:128
	v_mfma_f32_16x16x32_bf16 v[8:11], v[236:239], v[232:235], v[8:11]
	v_mfma_f32_16x16x32_bf16 v[4:7], v[240:243], v[232:235], v[4:7]
	v_mfma_f32_16x16x32_bf16 v[0:3], v[244:247], v[232:235], v[0:3]
	v_mfma_f32_16x16x32_bf16 v[140:143], v[248:251], v[232:235], v[140:143]
	s_waitcnt vmcnt(11)
	ds_write_b128 v183, v[20:23] offset:22528
	v_add_u32_e32 v20, s41, v187
	global_load_dwordx4 v[20:23], v20, s[98:99] offset:128
	v_cmp_gt_u32_e32 vcc, 0x6000, v183
	v_add_u32_e32 v182, 0xc000, v183
	v_add_u32_e32 v183, 0xffffa000, v183
	s_nop 0
	v_cndmask_b32_e32 v183, v183, v182, vcc
	s_add_u32 s30, s30, 0x80
	s_addc_u32 s31, s31, 0
	s_cmpk_eq_i32 s30, 0x780
	s_cbranch_scc0 .LBB0_1066
	s_waitcnt lgkmcnt(0)
	s_barrier
	ds_read_b128 v[236:239], v184
	ds_read_b128 v[240:243], v184 offset:1024
	ds_read_b128 v[244:247], v184 offset:2048
	ds_read_b128 v[248:251], v184 offset:3072
	ds_read_b128 v[204:207], v185
	ds_read_b128 v[208:211], v185 offset:1024
	ds_read_b128 v[212:215], v185 offset:2048
	ds_read_b128 v[216:219], v185 offset:3072
	ds_read_b128 v[220:223], v185 offset:4096
	ds_read_b128 v[224:227], v185 offset:5120
	ds_read_b128 v[228:231], v185 offset:6144
	ds_read_b128 v[232:235], v185 offset:7168
	s_movk_i32 vcc_lo, 0x6000
	s_cmp_eq_u32 m0, 2
	s_cselect_b32 vcc_lo, 0xffff4000, vcc_lo
	s_add_u32 m0, m0, 1
	s_cmp_eq_u32 m0, 3
	s_cselect_b32 m0, 0, m0
	v_add_u32_e32 v185, vcc_lo, v185
	v_add_u32_e32 v184, vcc_lo, v184
	v_xor_b32_e32 v185, 64, v185
	v_xor_b32_e32 v184, 64, v184
	s_waitcnt lgkmcnt(7)
	v_mfma_f32_16x16x32_bf16 v[172:175], v[236:239], v[204:207], v[172:175]
	v_mfma_f32_16x16x32_bf16 v[168:171], v[240:243], v[204:207], v[168:171]
	v_mfma_f32_16x16x32_bf16 v[164:167], v[244:247], v[204:207], v[164:167]
	v_mfma_f32_16x16x32_bf16 v[160:163], v[248:251], v[204:207], v[160:163]
	ds_read_b128 v[204:207], v185
	s_waitcnt lgkmcnt(7)
	v_mfma_f32_16x16x32_bf16 v[156:159], v[236:239], v[208:211], v[156:159]
	v_mfma_f32_16x16x32_bf16 v[152:155], v[240:243], v[208:211], v[152:155]
	v_mfma_f32_16x16x32_bf16 v[148:151], v[244:247], v[208:211], v[148:151]
	v_mfma_f32_16x16x32_bf16 v[144:147], v[248:251], v[208:211], v[144:147]
	ds_read_b128 v[208:211], v185 offset:1024
	s_waitcnt lgkmcnt(7)
	v_mfma_f32_16x16x32_bf16 v[136:139], v[236:239], v[212:215], v[136:139]
	v_mfma_f32_16x16x32_bf16 v[132:135], v[240:243], v[212:215], v[132:135]
	v_mfma_f32_16x16x32_bf16 v[128:131], v[244:247], v[212:215], v[128:131]
	v_mfma_f32_16x16x32_bf16 v[124:127], v[248:251], v[212:215], v[124:127]
	ds_read_b128 v[212:215], v185 offset:2048
	s_waitcnt lgkmcnt(7)
	v_mfma_f32_16x16x32_bf16 v[120:123], v[236:239], v[216:219], v[120:123]
	v_mfma_f32_16x16x32_bf16 v[108:111], v[240:243], v[216:219], v[108:111]
	v_mfma_f32_16x16x32_bf16 v[96:99], v[244:247], v[216:219], v[96:99]
	v_mfma_f32_16x16x32_bf16 v[92:95], v[248:251], v[216:219], v[92:95]
	ds_read_b128 v[216:219], v185 offset:3072
	s_waitcnt lgkmcnt(7)
	v_mfma_f32_16x16x32_bf16 v[84:87], v[236:239], v[220:223], v[84:87]
	v_mfma_f32_16x16x32_bf16 v[76:79], v[240:243], v[220:223], v[76:79]
	v_mfma_f32_16x16x32_bf16 v[72:75], v[244:247], v[220:223], v[72:75]
	v_mfma_f32_16x16x32_bf16 v[64:67], v[248:251], v[220:223], v[64:67]
	ds_read_b128 v[220:223], v185 offset:4096
	s_waitcnt lgkmcnt(7)
	v_mfma_f32_16x16x32_bf16 v[56:59], v[236:239], v[224:227], v[56:59]
	v_mfma_f32_16x16x32_bf16 v[52:55], v[240:243], v[224:227], v[52:55]
	v_mfma_f32_16x16x32_bf16 v[44:47], v[244:247], v[224:227], v[44:47]
	v_mfma_f32_16x16x32_bf16 v[36:39], v[248:251], v[224:227], v[36:39]
	ds_read_b128 v[224:227], v185 offset:5120
	s_waitcnt lgkmcnt(7)
	v_mfma_f32_16x16x32_bf16 v[32:35], v[236:239], v[228:231], v[32:35]
	v_mfma_f32_16x16x32_bf16 v[28:31], v[240:243], v[228:231], v[28:31]
	v_mfma_f32_16x16x32_bf16 v[16:19], v[244:247], v[228:231], v[16:19]
	v_mfma_f32_16x16x32_bf16 v[12:15], v[248:251], v[228:231], v[12:15]
	ds_read_b128 v[228:231], v185 offset:6144
	s_waitcnt lgkmcnt(7)
	v_mfma_f32_16x16x32_bf16 v[8:11], v[236:239], v[232:235], v[8:11]
	v_mfma_f32_16x16x32_bf16 v[4:7], v[240:243], v[232:235], v[4:7]
	v_mfma_f32_16x16x32_bf16 v[0:3], v[244:247], v[232:235], v[0:3]
	v_mfma_f32_16x16x32_bf16 v[140:143], v[248:251], v[232:235], v[140:143]
	ds_read_b128 v[232:235], v185 offset:7168
	ds_read_b128 v[236:239], v184
	ds_read_b128 v[240:243], v184 offset:1024
	ds_read_b128 v[244:247], v184 offset:2048
	ds_read_b128 v[248:251], v184 offset:3072
	s_movk_i32 vcc_lo, 0x6000
	s_cmp_eq_u32 m0, 2
	s_cselect_b32 vcc_lo, 0xffff4000, vcc_lo
	s_add_u32 m0, m0, 1
	s_cmp_eq_u32 m0, 3
	s_cselect_b32 m0, 0, m0
	v_add_u32_e32 v185, vcc_lo, v185
	v_add_u32_e32 v184, vcc_lo, v184
	v_xor_b32_e32 v185, 64, v185
	v_xor_b32_e32 v184, 64, v184
	s_waitcnt lgkmcnt(0)
	v_mfma_f32_16x16x32_bf16 v[172:175], v[236:239], v[204:207], v[172:175]
	v_mfma_f32_16x16x32_bf16 v[168:171], v[240:243], v[204:207], v[168:171]
	v_mfma_f32_16x16x32_bf16 v[164:167], v[244:247], v[204:207], v[164:167]
	v_mfma_f32_16x16x32_bf16 v[160:163], v[248:251], v[204:207], v[160:163]
	v_mfma_f32_16x16x32_bf16 v[156:159], v[236:239], v[208:211], v[156:159]
	v_mfma_f32_16x16x32_bf16 v[152:155], v[240:243], v[208:211], v[152:155]
	v_mfma_f32_16x16x32_bf16 v[148:151], v[244:247], v[208:211], v[148:151]
	v_mfma_f32_16x16x32_bf16 v[144:147], v[248:251], v[208:211], v[144:147]
	v_mfma_f32_16x16x32_bf16 v[136:139], v[236:239], v[212:215], v[136:139]
	v_mfma_f32_16x16x32_bf16 v[132:135], v[240:243], v[212:215], v[132:135]
	v_mfma_f32_16x16x32_bf16 v[128:131], v[244:247], v[212:215], v[128:131]
	v_mfma_f32_16x16x32_bf16 v[124:127], v[248:251], v[212:215], v[124:127]
	v_mfma_f32_16x16x32_bf16 v[120:123], v[236:239], v[216:219], v[120:123]
	v_mfma_f32_16x16x32_bf16 v[108:111], v[240:243], v[216:219], v[108:111]
	v_mfma_f32_16x16x32_bf16 v[96:99], v[244:247], v[216:219], v[96:99]
	v_mfma_f32_16x16x32_bf16 v[92:95], v[248:251], v[216:219], v[92:95]
	v_mfma_f32_16x16x32_bf16 v[84:87], v[236:239], v[220:223], v[84:87]
	v_mfma_f32_16x16x32_bf16 v[76:79], v[240:243], v[220:223], v[76:79]
	v_mfma_f32_16x16x32_bf16 v[72:75], v[244:247], v[220:223], v[72:75]
	v_mfma_f32_16x16x32_bf16 v[64:67], v[248:251], v[220:223], v[64:67]
	v_mfma_f32_16x16x32_bf16 v[56:59], v[236:239], v[224:227], v[56:59]
	v_mfma_f32_16x16x32_bf16 v[52:55], v[240:243], v[224:227], v[52:55]
	v_mfma_f32_16x16x32_bf16 v[44:47], v[244:247], v[224:227], v[44:47]
	v_mfma_f32_16x16x32_bf16 v[36:39], v[248:251], v[224:227], v[36:39]
	v_mfma_f32_16x16x32_bf16 v[32:35], v[236:239], v[228:231], v[32:35]
	v_mfma_f32_16x16x32_bf16 v[28:31], v[240:243], v[228:231], v[28:31]
	v_mfma_f32_16x16x32_bf16 v[16:19], v[244:247], v[228:231], v[16:19]
	v_mfma_f32_16x16x32_bf16 v[12:15], v[248:251], v[228:231], v[12:15]
	v_mfma_f32_16x16x32_bf16 v[8:11], v[236:239], v[232:235], v[8:11]
	v_mfma_f32_16x16x32_bf16 v[4:7], v[240:243], v[232:235], v[4:7]
	v_mfma_f32_16x16x32_bf16 v[0:3], v[244:247], v[232:235], v[0:3]
	v_mfma_f32_16x16x32_bf16 v[140:143], v[248:251], v[232:235], v[140:143]
	v_lshrrev_b32_e32 v236, 4, v188
	v_and_b32_e32 v237, 7, v188
	v_bitop3_b32 v238, v236, v237, 3 bitop3:0x6c
	v_lshlrev_b32_e32 v239, 7, v188
	v_bfe_u32 v240, v188, 4, 2
	v_and_b32_e32 v241, 0xffffc780, v239
	v_and_b32_e32 v239, 0x2780, v239
	v_bitop3_b32 v240, v240, v237, 4 bitop3:0x36
	v_lshlrev_b32_e32 v238, 4, v238
	v_lshlrev_b32_e32 v240, 4, v240
	v_or_b32_e32 v185, v241, v238
	v_or_b32_e32 v184, v239, v238
	v_or_b32_e32 v183, v241, v240
	v_or_b32_e32 v182, v239, v240
	s_waitcnt vmcnt(0)
	s_barrier
	s_waitcnt vmcnt(11)
	ds_write_b128 v176, v[116:119]
	s_waitcnt vmcnt(10)
	ds_write_b128 v176, v[112:115] offset:4096
	s_waitcnt vmcnt(9)
	ds_write_b128 v176, v[104:107] offset:8192
	s_waitcnt vmcnt(8)
	ds_write_b128 v176, v[88:91] offset:12288
	s_waitcnt vmcnt(7)
	ds_write_b128 v176, v[80:83] offset:16384
	s_waitcnt vmcnt(6)
	ds_write_b128 v176, v[68:71] offset:20480
	s_waitcnt vmcnt(5)
	ds_write_b128 v176, v[60:63] offset:24576
	s_waitcnt vmcnt(4)
	ds_write_b128 v176, v[48:51] offset:28672
	s_waitcnt vmcnt(3)
	ds_write_b128 v176, v[100:103] offset:32768
	s_waitcnt vmcnt(2)
	ds_write_b128 v176, v[40:43] offset:36864
	s_waitcnt vmcnt(1)
	ds_write_b128 v176, v[24:27] offset:40960
	s_waitcnt vmcnt(0)
	ds_write_b128 v176, v[20:23] offset:45056
	s_waitcnt lgkmcnt(0)
	s_barrier
	ds_read_b128 v[20:23], v185
	ds_read_b128 v[24:27], v185 offset:2048
	ds_read_b128 v[40:43], v185 offset:4096
	ds_read_b128 v[48:51], v185 offset:6144
	ds_read_b128 v[60:63], v185 offset:8192
	ds_read_b128 v[68:71], v185 offset:10240
	ds_read_b128 v[80:83], v185 offset:12288
	ds_read_b128 v[88:91], v185 offset:14336
	ds_read_b128 v[100:103], v184 offset:32768
	ds_read_b128 v[104:107], v184 offset:34816
	ds_read_b128 v[112:115], v184 offset:36864
	ds_read_b128 v[116:119], v184 offset:38912
	s_waitcnt lgkmcnt(3)
	v_mfma_f32_16x16x32_bf16 v[172:175], v[100:103], v[20:23], v[172:175]
	s_waitcnt lgkmcnt(2)
	v_mfma_f32_16x16x32_bf16 v[168:171], v[104:107], v[20:23], v[168:171]
	s_waitcnt lgkmcnt(1)
	v_mfma_f32_16x16x32_bf16 v[164:167], v[112:115], v[20:23], v[164:167]
	s_waitcnt lgkmcnt(0)
	v_mfma_f32_16x16x32_bf16 v[20:23], v[116:119], v[20:23], v[160:163]
	v_mfma_f32_16x16x32_bf16 v[156:159], v[100:103], v[24:27], v[156:159]
	v_mfma_f32_16x16x32_bf16 v[152:155], v[104:107], v[24:27], v[152:155]
	v_mfma_f32_16x16x32_bf16 v[148:151], v[112:115], v[24:27], v[148:151]
	v_mfma_f32_16x16x32_bf16 v[24:27], v[116:119], v[24:27], v[144:147]
	v_mfma_f32_16x16x32_bf16 v[136:139], v[100:103], v[40:43], v[136:139]
	v_mfma_f32_16x16x32_bf16 v[132:135], v[104:107], v[40:43], v[132:135]
	v_mfma_f32_16x16x32_bf16 v[128:131], v[112:115], v[40:43], v[128:131]
	v_mfma_f32_16x16x32_bf16 v[40:43], v[116:119], v[40:43], v[124:127]
	v_mfma_f32_16x16x32_bf16 v[144:147], v[100:103], v[48:51], v[120:123]
	v_mfma_f32_16x16x32_bf16 v[160:163], v[104:107], v[48:51], v[108:111]
	v_mfma_f32_16x16x32_bf16 v[178:181], v[112:115], v[48:51], v[96:99]
	v_mfma_f32_16x16x32_bf16 v[48:51], v[116:119], v[48:51], v[92:95]
	v_mfma_f32_16x16x32_bf16 v[184:187], v[100:103], v[60:63], v[84:87]
	v_mfma_f32_16x16x32_bf16 v[16:19], v[112:115], v[80:83], v[16:19]
	v_mfma_f32_16x16x32_bf16 v[12:15], v[116:119], v[80:83], v[12:15]
	v_mfma_f32_16x16x32_bf16 v[8:11], v[100:103], v[88:91], v[8:11]
	v_mfma_f32_16x16x32_bf16 v[4:7], v[104:107], v[88:91], v[4:7]
	v_mfma_f32_16x16x32_bf16 v[0:3], v[112:115], v[88:91], v[0:3]
	v_mfma_f32_16x16x32_bf16 v[190:193], v[104:107], v[60:63], v[76:79]
	v_mfma_f32_16x16x32_bf16 v[194:197], v[112:115], v[60:63], v[72:75]
	v_mfma_f32_16x16x32_bf16 v[198:201], v[116:119], v[60:63], v[64:67]
	v_mfma_f32_16x16x32_bf16 v[56:59], v[100:103], v[68:71], v[56:59]
	v_mfma_f32_16x16x32_bf16 v[52:55], v[104:107], v[68:71], v[52:55]
	v_mfma_f32_16x16x32_bf16 v[204:207], v[112:115], v[68:71], v[44:47]
	v_mfma_f32_16x16x32_bf16 v[208:211], v[116:119], v[68:71], v[36:39]
	v_mfma_f32_16x16x32_bf16 v[212:215], v[100:103], v[80:83], v[32:35]
	v_mfma_f32_16x16x32_bf16 v[216:219], v[104:107], v[80:83], v[28:31]
	v_mfma_f32_16x16x32_bf16 v[140:143], v[116:119], v[88:91], v[140:143]
	s_nop 1
	ds_read_b128 v[28:31], v183
	ds_read_b128 v[32:35], v183 offset:2048
	ds_read_b128 v[36:39], v183 offset:4096
	ds_read_b128 v[44:47], v183 offset:6144
	ds_read_b128 v[220:223], v183 offset:8192
	ds_read_b128 v[224:227], v183 offset:10240
	ds_read_b128 v[228:231], v183 offset:12288
	ds_read_b128 v[232:235], v183 offset:14336
	ds_read_b128 v[236:239], v182 offset:32768
	ds_read_b128 v[240:243], v182 offset:34816
	ds_read_b128 v[244:247], v182 offset:36864
	ds_read_b128 v[248:251], v182 offset:38912
	s_waitcnt lgkmcnt(3)
	v_mfma_f32_16x16x32_bf16 v[124:127], v[236:239], v[28:31], v[172:175]
	s_mov_b64 s[30:31], 0
	s_waitcnt lgkmcnt(2)
	v_mfma_f32_16x16x32_bf16 v[120:123], v[240:243], v[28:31], v[168:171]
	s_waitcnt lgkmcnt(1)
	v_mfma_f32_16x16x32_bf16 v[116:119], v[244:247], v[28:31], v[164:167]
	s_waitcnt lgkmcnt(0)
	v_mfma_f32_16x16x32_bf16 v[112:115], v[248:251], v[28:31], v[20:23]
	v_mfma_f32_16x16x32_bf16 v[108:111], v[236:239], v[32:35], v[156:159]
	v_mfma_f32_16x16x32_bf16 v[104:107], v[240:243], v[32:35], v[152:155]
	v_mfma_f32_16x16x32_bf16 v[100:103], v[244:247], v[32:35], v[148:151]
	v_mfma_f32_16x16x32_bf16 v[96:99], v[248:251], v[32:35], v[24:27]
	v_mfma_f32_16x16x32_bf16 v[92:95], v[236:239], v[36:39], v[136:139]
	v_mfma_f32_16x16x32_bf16 v[88:91], v[240:243], v[36:39], v[132:135]
	v_mfma_f32_16x16x32_bf16 v[84:87], v[244:247], v[36:39], v[128:131]
	v_mfma_f32_16x16x32_bf16 v[80:83], v[248:251], v[36:39], v[40:43]
	v_mfma_f32_16x16x32_bf16 v[76:79], v[236:239], v[44:47], v[144:147]
	v_mfma_f32_16x16x32_bf16 v[72:75], v[240:243], v[44:47], v[160:163]
	v_mfma_f32_16x16x32_bf16 v[68:71], v[244:247], v[44:47], v[178:181]
	v_mfma_f32_16x16x32_bf16 v[64:67], v[248:251], v[44:47], v[48:51]
	v_mfma_f32_16x16x32_bf16 v[60:63], v[236:239], v[220:223], v[184:187]
	v_mfma_f32_16x16x32_bf16 v[184:187], v[240:243], v[220:223], v[190:193]
	v_mfma_f32_16x16x32_bf16 v[180:183], v[244:247], v[220:223], v[194:197]
	v_mfma_f32_16x16x32_bf16 v[48:51], v[248:251], v[220:223], v[198:201]
	v_mfma_f32_16x16x32_bf16 v[44:47], v[236:239], v[224:227], v[56:59]
	v_mfma_f32_16x16x32_bf16 v[40:43], v[240:243], v[224:227], v[52:55]
	v_mfma_f32_16x16x32_bf16 v[36:39], v[244:247], v[224:227], v[204:207]
	v_mfma_f32_16x16x32_bf16 v[32:35], v[248:251], v[224:227], v[208:211]
	v_mfma_f32_16x16x32_bf16 v[28:31], v[236:239], v[228:231], v[212:215]
	v_mfma_f32_16x16x32_bf16 v[24:27], v[240:243], v[228:231], v[216:219]
	v_mfma_f32_16x16x32_bf16 v[20:23], v[244:247], v[228:231], v[16:19]
	v_mfma_f32_16x16x32_bf16 v[16:19], v[248:251], v[228:231], v[12:15]
	v_mfma_f32_16x16x32_bf16 v[12:15], v[236:239], v[232:235], v[8:11]
	v_mfma_f32_16x16x32_bf16 v[8:11], v[240:243], v[232:235], v[4:7]
	v_xor_b32_e32 v240, 32, v203
	v_mfma_f32_16x16x32_bf16 v[4:7], v[244:247], v[232:235], v[0:3]
	v_mfma_f32_16x16x32_bf16 v[0:3], v[248:251], v[232:235], v[140:143]
.LBB0_1068:
	s_and_b64 vcc, exec, s[30:31]
	s_cbranch_vccz .LBB0_1072
	s_nop 2
	v_mov_b32_e32 v8, v188
	s_mov_b32 s30, 0x20000
	v_ashrrev_i32_e32 v9, 3, v8
	v_lshlrev_b32_e32 v4, 4, v8
	v_and_b32_e32 v176, 0x70, v4
	v_add_u32_e32 v4, s53, v9
	v_add_u32_e32 v0, s38, v9
	v_ashrrev_i32_e32 v5, 31, v4
	v_ashrrev_i32_e32 v1, 31, v0
	v_lshlrev_b64 v[4:5], 11, v[4:5]
	v_xor_b32_e32 v10, v9, v8
	v_lshlrev_b64 v[0:1], 11, v[0:1]
	v_lshl_add_u64 v[6:7], s[2:3], 0, v[4:5]
	v_lshlrev_b32_e32 v10, 4, v10
	v_lshl_add_u64 v[2:3], s[0:1], 0, v[0:1]
	v_lshl_add_u64 v[6:7], v[6:7], 0, v[176:177]
	v_and_b32_e32 v10, 0x70, v10
	v_lshl_add_u64 v[2:3], v[2:3], 0, v[176:177]
	v_lshl_or_b32 v176, v9, 7, v10
	v_lshlrev_b32_e32 v12, 7, v8
	v_lshrrev_b32_e32 v9, 4, v8
	v_bfe_u32 v14, v8, 4, 2
	v_and_b32_e32 v15, 7, v8
	v_add_co_u32_e32 v8, vcc, s39, v6
	v_bitop3_b32 v16, v9, v15, 3 bitop3:0x6c
	s_nop 0
	v_addc_co_u32_e32 v9, vcc, 0, v7, vcc
	v_add_co_u32_e32 v10, vcc, s30, v6
	s_mov_b32 s31, 0x10000
	s_nop 0
	v_addc_co_u32_e32 v11, vcc, 0, v7, vcc
	global_load_dwordx4 v[20:23], v[8:9], off
	global_load_dwordx4 v[24:27], v[10:11], off
	v_add_co_u32_e32 v8, vcc, s31, v6
	s_mov_b32 s40, 0x70000
	s_nop 0
	v_addc_co_u32_e32 v9, vcc, 0, v7, vcc
	v_add_co_u32_e32 v10, vcc, s40, v2
	s_mov_b32 s40, 0x60000
	s_nop 0
	v_addc_co_u32_e32 v11, vcc, 0, v3, vcc
	global_load_dwordx4 v[40:43], v[8:9], off
	global_load_dwordx4 v[48:51], v[10:11], off
	v_add_co_u32_e32 v8, vcc, s40, v2
	s_mov_b32 s40, 0x50000
	s_nop 0
	v_addc_co_u32_e32 v9, vcc, 0, v3, vcc
	v_add_co_u32_e32 v10, vcc, s40, v2
	s_mov_b32 s40, 0x40000
	s_nop 0
	v_addc_co_u32_e32 v11, vcc, 0, v3, vcc
	global_load_dwordx4 v[60:63], v[8:9], off
	global_load_dwordx4 v[68:71], v[10:11], off
	v_add_co_u32_e32 v8, vcc, s40, v2
	v_and_b32_e32 v13, 0xffffc780, v12
	s_nop 0
	v_addc_co_u32_e32 v9, vcc, 0, v3, vcc
	v_add_co_u32_e32 v10, vcc, s39, v2
	v_and_b32_e32 v12, 0x2780, v12
	s_nop 0
	v_addc_co_u32_e32 v11, vcc, 0, v3, vcc
	global_load_dwordx4 v[80:83], v[8:9], off
	global_load_dwordx4 v[88:91], v[10:11], off
	v_add_co_u32_e32 v8, vcc, s30, v2
	v_bitop3_b32 v14, v14, v15, 4 bitop3:0x36
	s_nop 0
	v_addc_co_u32_e32 v9, vcc, 0, v3, vcc
	v_add_co_u32_e32 v10, vcc, s31, v2
	v_mov_b32_e32 v140, 0
	s_nop 0
	v_addc_co_u32_e32 v11, vcc, 0, v3, vcc
	global_load_dwordx4 v[104:107], v[8:9], off
	global_load_dwordx4 v[112:115], v[10:11], off
	global_load_dwordx4 v[100:103], v[6:7], off
	global_load_dwordx4 v[116:119], v[2:3], off
	v_lshlrev_b32_e32 v2, 4, v16
	v_or_b32_e32 v185, v13, v2
	v_or_b32_e32 v184, v12, v2
	v_lshlrev_b32_e32 v2, 4, v14
	v_or_b32_e32 v183, v13, v2
	v_or_b32_e32 v182, v12, v2
	v_lshlrev_b32_e32 v2, 4, v15
	v_or_b32_e32 v0, v0, v2
	v_or_b32_e32 v4, v4, v2
	v_lshl_add_u64 v[178:179], s[34:35], 0, v[0:1]
	v_lshl_add_u64 v[180:181], s[50:51], 0, v[4:5]
	s_mov_b64 s[30:31], 0
	v_mov_b32_e32 v141, v140
	v_mov_b32_e32 v142, v140
	v_mov_b32_e32 v143, v140
	v_mov_b32_e32 v0, v140
	v_mov_b32_e32 v1, v140
	v_mov_b32_e32 v2, v140
	v_mov_b32_e32 v3, v140
	v_mov_b32_e32 v4, v140
	v_mov_b32_e32 v5, v140
	v_mov_b32_e32 v6, v140
	v_mov_b32_e32 v7, v140
	v_mov_b32_e32 v8, v140
	v_mov_b32_e32 v9, v140
	v_mov_b32_e32 v10, v140
	v_mov_b32_e32 v11, v140
	v_mov_b32_e32 v12, v140
	v_mov_b32_e32 v13, v140
	v_mov_b32_e32 v14, v140
	v_mov_b32_e32 v15, v140
	v_mov_b32_e32 v16, v140
	v_mov_b32_e32 v17, v140
	v_mov_b32_e32 v18, v140
	v_mov_b32_e32 v19, v140
	v_mov_b32_e32 v28, v140
	v_mov_b32_e32 v29, v140
	v_mov_b32_e32 v30, v140
	v_mov_b32_e32 v31, v140
	v_mov_b32_e32 v32, v140
	v_mov_b32_e32 v33, v140
	v_mov_b32_e32 v34, v140
	v_mov_b32_e32 v35, v140
	v_mov_b32_e32 v36, v140
	v_mov_b32_e32 v37, v140
	v_mov_b32_e32 v38, v140
	v_mov_b32_e32 v39, v140
	v_mov_b32_e32 v44, v140
	v_mov_b32_e32 v45, v140
	v_mov_b32_e32 v46, v140
	v_mov_b32_e32 v47, v140
	v_mov_b32_e32 v52, v140
	v_mov_b32_e32 v53, v140
	v_mov_b32_e32 v54, v140
	v_mov_b32_e32 v55, v140
	v_mov_b32_e32 v56, v140
	v_mov_b32_e32 v57, v140
	v_mov_b32_e32 v58, v140
	v_mov_b32_e32 v59, v140
	v_mov_b32_e32 v64, v140
	v_mov_b32_e32 v65, v140
	v_mov_b32_e32 v66, v140
	v_mov_b32_e32 v67, v140
	v_mov_b32_e32 v72, v140
	v_mov_b32_e32 v73, v140
	v_mov_b32_e32 v74, v140
	v_mov_b32_e32 v75, v140
	v_mov_b32_e32 v76, v140
	v_mov_b32_e32 v77, v140
	v_mov_b32_e32 v78, v140
	v_mov_b32_e32 v79, v140
	v_mov_b32_e32 v84, v140
	v_mov_b32_e32 v85, v140
	v_mov_b32_e32 v86, v140
	v_mov_b32_e32 v87, v140
	v_mov_b32_e32 v92, v140
	v_mov_b32_e32 v93, v140
	v_mov_b32_e32 v94, v140
	v_mov_b32_e32 v95, v140
	v_mov_b32_e32 v96, v140
	v_mov_b32_e32 v97, v140
	v_mov_b32_e32 v98, v140
	v_mov_b32_e32 v99, v140
	v_mov_b32_e32 v108, v140
	v_mov_b32_e32 v109, v140
	v_mov_b32_e32 v110, v140
	v_mov_b32_e32 v111, v140
	v_mov_b32_e32 v120, v140
	v_mov_b32_e32 v121, v140
	v_mov_b32_e32 v122, v140
	v_mov_b32_e32 v123, v140
	v_mov_b32_e32 v124, v140
	v_mov_b32_e32 v125, v140
	v_mov_b32_e32 v126, v140
	v_mov_b32_e32 v127, v140
	v_mov_b32_e32 v128, v140
	v_mov_b32_e32 v129, v140
	v_mov_b32_e32 v130, v140
	v_mov_b32_e32 v131, v140
	v_mov_b32_e32 v132, v140
	v_mov_b32_e32 v133, v140
	v_mov_b32_e32 v134, v140
	v_mov_b32_e32 v135, v140
	v_mov_b32_e32 v136, v140
	v_mov_b32_e32 v137, v140
	v_mov_b32_e32 v138, v140
	v_mov_b32_e32 v139, v140
	v_mov_b32_e32 v144, v140
	v_mov_b32_e32 v145, v140
	v_mov_b32_e32 v146, v140
	v_mov_b32_e32 v147, v140
	v_mov_b32_e32 v148, v140
	v_mov_b32_e32 v149, v140
	v_mov_b32_e32 v150, v140
	v_mov_b32_e32 v151, v140
	v_mov_b32_e32 v152, v140
	v_mov_b32_e32 v153, v140
	v_mov_b32_e32 v154, v140
	v_mov_b32_e32 v155, v140
	v_mov_b32_e32 v156, v140
	v_mov_b32_e32 v157, v140
	v_mov_b32_e32 v158, v140
	v_mov_b32_e32 v159, v140
	v_mov_b32_e32 v160, v140
	v_mov_b32_e32 v161, v140
	v_mov_b32_e32 v162, v140
	v_mov_b32_e32 v163, v140
	v_mov_b32_e32 v164, v140
	v_mov_b32_e32 v165, v140
	v_mov_b32_e32 v166, v140
	v_mov_b32_e32 v167, v140
	v_mov_b32_e32 v168, v140
	v_mov_b32_e32 v169, v140
	v_mov_b32_e32 v170, v140
	v_mov_b32_e32 v171, v140
	v_mov_b32_e32 v172, v140
	v_mov_b32_e32 v173, v140
	v_mov_b32_e32 v174, v140
	v_mov_b32_e32 v175, v140
	s_mov_b32 s39, 0x820000
	s_mov_b32 s40, 0x830000
	v_readlane_b32 s98, v253, 3
	v_readlane_b32 s99, v253, 4
	v_and_b32_e32 v240, 15, v188
	v_bfe_u32 v241, v188, 4, 2
	v_lshrrev_b32_e32 v242, 2, v240
	v_sub_u32_e32 v242, 0, v242
	v_and_b32_e32 v242, 3, v242
	v_xor_b32_e32 v241, v241, v242
	v_lshlrev_b32_e32 v241, 4, v241
	v_lshl_or_b32 v241, v240, 6, v241
	v_bfe_u32 v242, v188, 7, 1
	v_lshl_or_b32 v185, v242, 13, v241
	v_bfe_u32 v242, v188, 6, 1
	v_lshl_or_b32 v184, v242, 12, v241
	v_add_u32_e32 v184, 0x4000, v184
	v_lshrrev_b32_e32 v240, 3, v188
	v_bfe_u32 v241, v188, 2, 1
	v_lshrrev_b32_e32 v242, 2, v240
	v_sub_u32_e32 v242, 0, v242
	v_and_b32_e32 v242, 3, v242
	v_and_b32_e32 v243, 3, v188
	v_xor_b32_e32 v242, v243, v242
	v_lshlrev_b32_e32 v242, 4, v242
	v_xor_b32_e32 v240, v240, v241
	v_lshl_or_b32 v242, v240, 6, v242
	v_mul_u32_u24_e32 v241, 0x6000, v241
	v_add_u32_e32 v183, v241, v242
	s_mov_b32 m0, 0
	s_sub_u32 vcc_lo, s30, s98
	v_add_u32_e32 v186, vcc_lo, v178
	v_add_u32_e32 v187, vcc_lo, v180
	s_barrier
	s_waitcnt vmcnt(0)
	ds_write_b128 v183, v[116:119]
	ds_write_b128 v183, v[112:115] offset:2048
	ds_write_b128 v183, v[104:107] offset:4096
	ds_write_b128 v183, v[88:91] offset:6144
	ds_write_b128 v183, v[80:83] offset:8192
	ds_write_b128 v183, v[68:71] offset:10240
	ds_write_b128 v183, v[60:63] offset:12288
	ds_write_b128 v183, v[48:51] offset:14336
	ds_write_b128 v183, v[100:103] offset:16384
	ds_write_b128 v183, v[40:43] offset:18432
	ds_write_b128 v183, v[24:27] offset:20480
	ds_write_b128 v183, v[20:23] offset:22528
	v_cmp_gt_u32_e32 vcc, 0x6000, v183
	v_add_u32_e32 v182, 0xc000, v183
	v_add_u32_e32 v183, 0xffffa000, v183
	s_nop 0
	v_cndmask_b32_e32 v183, v183, v182, vcc
	v_add_u32_e32 v116, s26, v186
	global_load_dwordx4 v[116:119], v116, s[98:99] offset:128
	v_add_u32_e32 v112, s27, v186
	global_load_dwordx4 v[112:115], v112, s[98:99] offset:128
	v_add_u32_e32 v104, s20, v186
	global_load_dwordx4 v[104:107], v104, s[98:99] offset:128
	v_add_u32_e32 v88, s21, v186
	global_load_dwordx4 v[88:91], v88, s[98:99] offset:128
	v_add_u32_e32 v80, s56, v186
	global_load_dwordx4 v[80:83], v80, s[98:99] offset:128
	v_add_u32_e32 v68, s57, v186
	global_load_dwordx4 v[68:71], v68, s[98:99] offset:128
	v_add_u32_e32 v60, s24, v186
	global_load_dwordx4 v[60:63], v60, s[98:99] offset:128
	v_add_u32_e32 v48, s96, v186
	global_load_dwordx4 v[48:51], v48, s[98:99] offset:128
	v_add_u32_e32 v100, s25, v187
	global_load_dwordx4 v[100:103], v100, s[98:99] offset:128
	v_add_u32_e32 v40, s33, v187
	global_load_dwordx4 v[40:43], v40, s[98:99] offset:128
	v_add_u32_e32 v24, s39, v187
	global_load_dwordx4 v[24:27], v24, s[98:99] offset:128
	v_add_u32_e32 v20, s40, v187
	global_load_dwordx4 v[20:23], v20, s[98:99] offset:128
	s_add_u32 s30, s30, 0x80
	s_addc_u32 s31, s31, 0
.LBB0_1070:
	s_waitcnt lgkmcnt(0)
	s_barrier
	ds_read_b128 v[240:243], v184
	ds_read_b128 v[244:247], v184 offset:1024
	ds_read_b128 v[248:251], v184 offset:2048
	ds_read_b128 v[204:207], v184 offset:3072
	ds_read_b128 v[208:211], v185
	ds_read_b128 v[212:215], v185 offset:1024
	ds_read_b128 v[216:219], v185 offset:2048
	ds_read_b128 v[220:223], v185 offset:3072
	ds_read_b128 v[224:227], v185 offset:4096
	ds_read_b128 v[228:231], v185 offset:5120
	ds_read_b128 v[232:235], v185 offset:6144
	ds_read_b128 v[236:239], v185 offset:7168
	s_movk_i32 vcc_lo, 0x6000
	s_cmp_eq_u32 m0, 2
	s_cselect_b32 vcc_lo, 0xffff4000, vcc_lo
	s_add_u32 m0, m0, 1
	s_cmp_eq_u32 m0, 3
	s_cselect_b32 m0, 0, m0
	v_add_u32_e32 v185, vcc_lo, v185
	v_add_u32_e32 v184, vcc_lo, v184
	v_xor_b32_e32 v185, 64, v185
	v_xor_b32_e32 v184, 64, v184
	s_waitcnt lgkmcnt(7)
	v_mfma_f32_16x16x32_bf16 v[172:175], v[208:211], v[240:243], v[172:175]
	v_mfma_f32_16x16x32_bf16 v[168:171], v[208:211], v[244:247], v[168:171]
	v_mfma_f32_16x16x32_bf16 v[164:167], v[208:211], v[248:251], v[164:167]
	v_mfma_f32_16x16x32_bf16 v[160:163], v[208:211], v[204:207], v[160:163]
	ds_read_b128 v[208:211], v185
	s_waitcnt lgkmcnt(7)
	v_mfma_f32_16x16x32_bf16 v[156:159], v[212:215], v[240:243], v[156:159]
	v_mfma_f32_16x16x32_bf16 v[152:155], v[212:215], v[244:247], v[152:155]
	v_mfma_f32_16x16x32_bf16 v[148:151], v[212:215], v[248:251], v[148:151]
	v_mfma_f32_16x16x32_bf16 v[144:147], v[212:215], v[204:207], v[144:147]
	ds_read_b128 v[212:215], v185 offset:1024
	s_waitcnt lgkmcnt(7)
	v_mfma_f32_16x16x32_bf16 v[136:139], v[216:219], v[240:243], v[136:139]
	v_mfma_f32_16x16x32_bf16 v[132:135], v[216:219], v[244:247], v[132:135]
	v_mfma_f32_16x16x32_bf16 v[128:131], v[216:219], v[248:251], v[128:131]
	v_mfma_f32_16x16x32_bf16 v[124:127], v[216:219], v[204:207], v[124:127]
	ds_read_b128 v[216:219], v185 offset:2048
	s_waitcnt lgkmcnt(7)
	v_mfma_f32_16x16x32_bf16 v[120:123], v[220:223], v[240:243], v[120:123]
	v_mfma_f32_16x16x32_bf16 v[108:111], v[220:223], v[244:247], v[108:111]
	v_mfma_f32_16x16x32_bf16 v[96:99], v[220:223], v[248:251], v[96:99]
	v_mfma_f32_16x16x32_bf16 v[92:95], v[220:223], v[204:207], v[92:95]
	ds_read_b128 v[220:223], v185 offset:3072
	s_waitcnt lgkmcnt(7)
	v_mfma_f32_16x16x32_bf16 v[84:87], v[224:227], v[240:243], v[84:87]
	v_mfma_f32_16x16x32_bf16 v[76:79], v[224:227], v[244:247], v[76:79]
	v_mfma_f32_16x16x32_bf16 v[72:75], v[224:227], v[248:251], v[72:75]
	v_mfma_f32_16x16x32_bf16 v[64:67], v[224:227], v[204:207], v[64:67]
	ds_read_b128 v[224:227], v185 offset:4096
	s_waitcnt lgkmcnt(7)
	v_mfma_f32_16x16x32_bf16 v[56:59], v[228:231], v[240:243], v[56:59]
	v_mfma_f32_16x16x32_bf16 v[52:55], v[228:231], v[244:247], v[52:55]
	v_mfma_f32_16x16x32_bf16 v[44:47], v[228:231], v[248:251], v[44:47]
	v_mfma_f32_16x16x32_bf16 v[36:39], v[228:231], v[204:207], v[36:39]
	ds_read_b128 v[228:231], v185 offset:5120
	s_waitcnt lgkmcnt(7)
	v_mfma_f32_16x16x32_bf16 v[32:35], v[232:235], v[240:243], v[32:35]
	v_mfma_f32_16x16x32_bf16 v[28:31], v[232:235], v[244:247], v[28:31]
	v_mfma_f32_16x16x32_bf16 v[16:19], v[232:235], v[248:251], v[16:19]
	v_mfma_f32_16x16x32_bf16 v[12:15], v[232:235], v[204:207], v[12:15]
	ds_read_b128 v[232:235], v185 offset:6144
	s_waitcnt lgkmcnt(7)
	v_mfma_f32_16x16x32_bf16 v[8:11], v[236:239], v[240:243], v[8:11]
	v_mfma_f32_16x16x32_bf16 v[4:7], v[236:239], v[244:247], v[4:7]
	v_mfma_f32_16x16x32_bf16 v[0:3], v[236:239], v[248:251], v[0:3]
	v_mfma_f32_16x16x32_bf16 v[140:143], v[236:239], v[204:207], v[140:143]
	ds_read_b128 v[236:239], v185 offset:7168
	ds_read_b128 v[240:243], v184
	ds_read_b128 v[244:247], v184 offset:1024
	ds_read_b128 v[248:251], v184 offset:2048
	ds_read_b128 v[204:207], v184 offset:3072
	s_movk_i32 vcc_lo, 0x6000
	s_cmp_eq_u32 m0, 2
	s_cselect_b32 vcc_lo, 0xffff4000, vcc_lo
	s_add_u32 m0, m0, 1
	s_cmp_eq_u32 m0, 3
	s_cselect_b32 m0, 0, m0
	v_add_u32_e32 v185, vcc_lo, v185
	v_add_u32_e32 v184, vcc_lo, v184
	v_xor_b32_e32 v185, 64, v185
	v_xor_b32_e32 v184, 64, v184
	s_sub_u32 vcc_lo, s30, s98
	v_add_u32_e32 v186, vcc_lo, v178
	v_add_u32_e32 v187, vcc_lo, v180
	s_barrier
	s_waitcnt lgkmcnt(0)
	v_mfma_f32_16x16x32_bf16 v[172:175], v[208:211], v[240:243], v[172:175]
	v_mfma_f32_16x16x32_bf16 v[168:171], v[208:211], v[244:247], v[168:171]
	v_mfma_f32_16x16x32_bf16 v[164:167], v[208:211], v[248:251], v[164:167]
	v_mfma_f32_16x16x32_bf16 v[160:163], v[208:211], v[204:207], v[160:163]
	s_waitcnt vmcnt(11)
	ds_write_b128 v183, v[116:119]
	v_add_u32_e32 v116, s26, v186
	global_load_dwordx4 v[116:119], v116, s[98:99] offset:128
	s_waitcnt vmcnt(11)
	ds_write_b128 v183, v[112:115] offset:2048
	v_add_u32_e32 v112, s27, v186
	global_load_dwordx4 v[112:115], v112, s[98:99] offset:128
	v_mfma_f32_16x16x32_bf16 v[156:159], v[212:215], v[240:243], v[156:159]
	v_mfma_f32_16x16x32_bf16 v[152:155], v[212:215], v[244:247], v[152:155]
	v_mfma_f32_16x16x32_bf16 v[148:151], v[212:215], v[248:251], v[148:151]
	v_mfma_f32_16x16x32_bf16 v[144:147], v[212:215], v[204:207], v[144:147]
	s_waitcnt vmcnt(11)
	ds_write_b128 v183, v[104:107] offset:4096
	v_add_u32_e32 v104, s20, v186
	global_load_dwordx4 v[104:107], v104, s[98:99] offset:128
	v_mfma_f32_16x16x32_bf16 v[136:139], v[216:219], v[240:243], v[136:139]
	v_mfma_f32_16x16x32_bf16 v[132:135], v[216:219], v[244:247], v[132:135]
	v_mfma_f32_16x16x32_bf16 v[128:131], v[216:219], v[248:251], v[128:131]
	v_mfma_f32_16x16x32_bf16 v[124:127], v[216:219], v[204:207], v[124:127]
	s_waitcnt vmcnt(11)
	ds_write_b128 v183, v[88:91] offset:6144
	v_add_u32_e32 v88, s21, v186
	global_load_dwordx4 v[88:91], v88, s[98:99] offset:128
	s_waitcnt vmcnt(11)
	ds_write_b128 v183, v[80:83] offset:8192
	v_add_u32_e32 v80, s56, v186
	global_load_dwordx4 v[80:83], v80, s[98:99] offset:128
	v_mfma_f32_16x16x32_bf16 v[120:123], v[220:223], v[240:243], v[120:123]
	v_mfma_f32_16x16x32_bf16 v[108:111], v[220:223], v[244:247], v[108:111]
	v_mfma_f32_16x16x32_bf16 v[96:99], v[220:223], v[248:251], v[96:99]
	v_mfma_f32_16x16x32_bf16 v[92:95], v[220:223], v[204:207], v[92:95]
	s_waitcnt vmcnt(11)
	ds_write_b128 v183, v[68:71] offset:10240
	v_add_u32_e32 v68, s57, v186
	global_load_dwordx4 v[68:71], v68, s[98:99] offset:128
	v_mfma_f32_16x16x32_bf16 v[84:87], v[224:227], v[240:243], v[84:87]
	v_mfma_f32_16x16x32_bf16 v[76:79], v[224:227], v[244:247], v[76:79]
	v_mfma_f32_16x16x32_bf16 v[72:75], v[224:227], v[248:251], v[72:75]
	v_mfma_f32_16x16x32_bf16 v[64:67], v[224:227], v[204:207], v[64:67]
	s_waitcnt vmcnt(11)
	ds_write_b128 v183, v[60:63] offset:12288
	v_add_u32_e32 v60, s24, v186
	global_load_dwordx4 v[60:63], v60, s[98:99] offset:128
	s_waitcnt vmcnt(11)
	ds_write_b128 v183, v[48:51] offset:14336
	v_add_u32_e32 v48, s96, v186
	global_load_dwordx4 v[48:51], v48, s[98:99] offset:128
	v_mfma_f32_16x16x32_bf16 v[56:59], v[228:231], v[240:243], v[56:59]
	v_mfma_f32_16x16x32_bf16 v[52:55], v[228:231], v[244:247], v[52:55]
	v_mfma_f32_16x16x32_bf16 v[44:47], v[228:231], v[248:251], v[44:47]
	v_mfma_f32_16x16x32_bf16 v[36:39], v[228:231], v[204:207], v[36:39]
	s_waitcnt vmcnt(11)
	ds_write_b128 v183, v[100:103] offset:16384
	v_add_u32_e32 v100, s25, v187
	global_load_dwordx4 v[100:103], v100, s[98:99] offset:128
	v_mfma_f32_16x16x32_bf16 v[32:35], v[232:235], v[240:243], v[32:35]
	v_mfma_f32_16x16x32_bf16 v[28:31], v[232:235], v[244:247], v[28:31]
	v_mfma_f32_16x16x32_bf16 v[16:19], v[232:235], v[248:251], v[16:19]
	v_mfma_f32_16x16x32_bf16 v[12:15], v[232:235], v[204:207], v[12:15]
	s_waitcnt vmcnt(11)
	ds_write_b128 v183, v[40:43] offset:18432
	v_add_u32_e32 v40, s33, v187
	global_load_dwordx4 v[40:43], v40, s[98:99] offset:128
	s_waitcnt vmcnt(11)
	ds_write_b128 v183, v[24:27] offset:20480
	v_add_u32_e32 v24, s39, v187
	global_load_dwordx4 v[24:27], v24, s[98:99] offset:128
	v_mfma_f32_16x16x32_bf16 v[8:11], v[236:239], v[240:243], v[8:11]
	v_mfma_f32_16x16x32_bf16 v[4:7], v[236:239], v[244:247], v[4:7]
	v_mfma_f32_16x16x32_bf16 v[0:3], v[236:239], v[248:251], v[0:3]
	v_mfma_f32_16x16x32_bf16 v[140:143], v[236:239], v[204:207], v[140:143]
	s_waitcnt vmcnt(11)
	ds_write_b128 v183, v[20:23] offset:22528
	v_add_u32_e32 v20, s40, v187
	global_load_dwordx4 v[20:23], v20, s[98:99] offset:128
	v_cmp_gt_u32_e32 vcc, 0x6000, v183
	v_add_u32_e32 v182, 0xc000, v183
	v_add_u32_e32 v183, 0xffffa000, v183
	s_nop 0
	v_cndmask_b32_e32 v183, v183, v182, vcc
	s_add_u32 s30, s30, 0x80
	s_addc_u32 s31, s31, 0
	s_cmpk_eq_i32 s30, 0x780
	s_cbranch_scc0 .LBB0_1070
	s_waitcnt lgkmcnt(0)
	s_barrier
	ds_read_b128 v[240:243], v184
	ds_read_b128 v[244:247], v184 offset:1024
	ds_read_b128 v[248:251], v184 offset:2048
	ds_read_b128 v[204:207], v184 offset:3072
	ds_read_b128 v[208:211], v185
	ds_read_b128 v[212:215], v185 offset:1024
	ds_read_b128 v[216:219], v185 offset:2048
	ds_read_b128 v[220:223], v185 offset:3072
	ds_read_b128 v[224:227], v185 offset:4096
	ds_read_b128 v[228:231], v185 offset:5120
	ds_read_b128 v[232:235], v185 offset:6144
	ds_read_b128 v[236:239], v185 offset:7168
	s_movk_i32 vcc_lo, 0x6000
	s_cmp_eq_u32 m0, 2
	s_cselect_b32 vcc_lo, 0xffff4000, vcc_lo
	s_add_u32 m0, m0, 1
	s_cmp_eq_u32 m0, 3
	s_cselect_b32 m0, 0, m0
	v_add_u32_e32 v185, vcc_lo, v185
	v_add_u32_e32 v184, vcc_lo, v184
	v_xor_b32_e32 v185, 64, v185
	v_xor_b32_e32 v184, 64, v184
	s_waitcnt lgkmcnt(7)
	v_mfma_f32_16x16x32_bf16 v[172:175], v[208:211], v[240:243], v[172:175]
	v_mfma_f32_16x16x32_bf16 v[168:171], v[208:211], v[244:247], v[168:171]
	v_mfma_f32_16x16x32_bf16 v[164:167], v[208:211], v[248:251], v[164:167]
	v_mfma_f32_16x16x32_bf16 v[160:163], v[208:211], v[204:207], v[160:163]
	ds_read_b128 v[208:211], v185
	s_waitcnt lgkmcnt(7)
	v_mfma_f32_16x16x32_bf16 v[156:159], v[212:215], v[240:243], v[156:159]
	v_mfma_f32_16x16x32_bf16 v[152:155], v[212:215], v[244:247], v[152:155]
	v_mfma_f32_16x16x32_bf16 v[148:151], v[212:215], v[248:251], v[148:151]
	v_mfma_f32_16x16x32_bf16 v[144:147], v[212:215], v[204:207], v[144:147]
	ds_read_b128 v[212:215], v185 offset:1024
	s_waitcnt lgkmcnt(7)
	v_mfma_f32_16x16x32_bf16 v[136:139], v[216:219], v[240:243], v[136:139]
	v_mfma_f32_16x16x32_bf16 v[132:135], v[216:219], v[244:247], v[132:135]
	v_mfma_f32_16x16x32_bf16 v[128:131], v[216:219], v[248:251], v[128:131]
	v_mfma_f32_16x16x32_bf16 v[124:127], v[216:219], v[204:207], v[124:127]
	ds_read_b128 v[216:219], v185 offset:2048
	s_waitcnt lgkmcnt(7)
	v_mfma_f32_16x16x32_bf16 v[120:123], v[220:223], v[240:243], v[120:123]
	v_mfma_f32_16x16x32_bf16 v[108:111], v[220:223], v[244:247], v[108:111]
	v_mfma_f32_16x16x32_bf16 v[96:99], v[220:223], v[248:251], v[96:99]
	v_mfma_f32_16x16x32_bf16 v[92:95], v[220:223], v[204:207], v[92:95]
	ds_read_b128 v[220:223], v185 offset:3072
	s_waitcnt lgkmcnt(7)
	v_mfma_f32_16x16x32_bf16 v[84:87], v[224:227], v[240:243], v[84:87]
	v_mfma_f32_16x16x32_bf16 v[76:79], v[224:227], v[244:247], v[76:79]
	v_mfma_f32_16x16x32_bf16 v[72:75], v[224:227], v[248:251], v[72:75]
	v_mfma_f32_16x16x32_bf16 v[64:67], v[224:227], v[204:207], v[64:67]
	ds_read_b128 v[224:227], v185 offset:4096
	s_waitcnt lgkmcnt(7)
	v_mfma_f32_16x16x32_bf16 v[56:59], v[228:231], v[240:243], v[56:59]
	v_mfma_f32_16x16x32_bf16 v[52:55], v[228:231], v[244:247], v[52:55]
	v_mfma_f32_16x16x32_bf16 v[44:47], v[228:231], v[248:251], v[44:47]
	v_mfma_f32_16x16x32_bf16 v[36:39], v[228:231], v[204:207], v[36:39]
	ds_read_b128 v[228:231], v185 offset:5120
	s_waitcnt lgkmcnt(7)
	v_mfma_f32_16x16x32_bf16 v[32:35], v[232:235], v[240:243], v[32:35]
	v_mfma_f32_16x16x32_bf16 v[28:31], v[232:235], v[244:247], v[28:31]
	v_mfma_f32_16x16x32_bf16 v[16:19], v[232:235], v[248:251], v[16:19]
	v_mfma_f32_16x16x32_bf16 v[12:15], v[232:235], v[204:207], v[12:15]
	ds_read_b128 v[232:235], v185 offset:6144
	s_waitcnt lgkmcnt(7)
	v_mfma_f32_16x16x32_bf16 v[8:11], v[236:239], v[240:243], v[8:11]
	v_mfma_f32_16x16x32_bf16 v[4:7], v[236:239], v[244:247], v[4:7]
	v_mfma_f32_16x16x32_bf16 v[0:3], v[236:239], v[248:251], v[0:3]
	v_mfma_f32_16x16x32_bf16 v[140:143], v[236:239], v[204:207], v[140:143]
	ds_read_b128 v[236:239], v185 offset:7168
	ds_read_b128 v[240:243], v184
	ds_read_b128 v[244:247], v184 offset:1024
	ds_read_b128 v[248:251], v184 offset:2048
	ds_read_b128 v[204:207], v184 offset:3072
	s_movk_i32 vcc_lo, 0x6000
	s_cmp_eq_u32 m0, 2
	s_cselect_b32 vcc_lo, 0xffff4000, vcc_lo
	s_add_u32 m0, m0, 1
	s_cmp_eq_u32 m0, 3
	s_cselect_b32 m0, 0, m0
	v_add_u32_e32 v185, vcc_lo, v185
	v_add_u32_e32 v184, vcc_lo, v184
	v_xor_b32_e32 v185, 64, v185
	v_xor_b32_e32 v184, 64, v184
	s_waitcnt lgkmcnt(0)
	v_mfma_f32_16x16x32_bf16 v[172:175], v[208:211], v[240:243], v[172:175]
	v_mfma_f32_16x16x32_bf16 v[168:171], v[208:211], v[244:247], v[168:171]
	v_mfma_f32_16x16x32_bf16 v[164:167], v[208:211], v[248:251], v[164:167]
	v_mfma_f32_16x16x32_bf16 v[160:163], v[208:211], v[204:207], v[160:163]
	v_mfma_f32_16x16x32_bf16 v[156:159], v[212:215], v[240:243], v[156:159]
	v_mfma_f32_16x16x32_bf16 v[152:155], v[212:215], v[244:247], v[152:155]
	v_mfma_f32_16x16x32_bf16 v[148:151], v[212:215], v[248:251], v[148:151]
	v_mfma_f32_16x16x32_bf16 v[144:147], v[212:215], v[204:207], v[144:147]
	v_mfma_f32_16x16x32_bf16 v[136:139], v[216:219], v[240:243], v[136:139]
	v_mfma_f32_16x16x32_bf16 v[132:135], v[216:219], v[244:247], v[132:135]
	v_mfma_f32_16x16x32_bf16 v[128:131], v[216:219], v[248:251], v[128:131]
	v_mfma_f32_16x16x32_bf16 v[124:127], v[216:219], v[204:207], v[124:127]
	v_mfma_f32_16x16x32_bf16 v[120:123], v[220:223], v[240:243], v[120:123]
	v_mfma_f32_16x16x32_bf16 v[108:111], v[220:223], v[244:247], v[108:111]
	v_mfma_f32_16x16x32_bf16 v[96:99], v[220:223], v[248:251], v[96:99]
	v_mfma_f32_16x16x32_bf16 v[92:95], v[220:223], v[204:207], v[92:95]
	v_mfma_f32_16x16x32_bf16 v[84:87], v[224:227], v[240:243], v[84:87]
	v_mfma_f32_16x16x32_bf16 v[76:79], v[224:227], v[244:247], v[76:79]
	v_mfma_f32_16x16x32_bf16 v[72:75], v[224:227], v[248:251], v[72:75]
	v_mfma_f32_16x16x32_bf16 v[64:67], v[224:227], v[204:207], v[64:67]
	v_mfma_f32_16x16x32_bf16 v[56:59], v[228:231], v[240:243], v[56:59]
	v_mfma_f32_16x16x32_bf16 v[52:55], v[228:231], v[244:247], v[52:55]
	v_mfma_f32_16x16x32_bf16 v[44:47], v[228:231], v[248:251], v[44:47]
	v_mfma_f32_16x16x32_bf16 v[36:39], v[228:231], v[204:207], v[36:39]
	v_mfma_f32_16x16x32_bf16 v[32:35], v[232:235], v[240:243], v[32:35]
	v_mfma_f32_16x16x32_bf16 v[28:31], v[232:235], v[244:247], v[28:31]
	v_mfma_f32_16x16x32_bf16 v[16:19], v[232:235], v[248:251], v[16:19]
	v_mfma_f32_16x16x32_bf16 v[12:15], v[232:235], v[204:207], v[12:15]
	v_mfma_f32_16x16x32_bf16 v[8:11], v[236:239], v[240:243], v[8:11]
	v_mfma_f32_16x16x32_bf16 v[4:7], v[236:239], v[244:247], v[4:7]
	v_mfma_f32_16x16x32_bf16 v[0:3], v[236:239], v[248:251], v[0:3]
	v_mfma_f32_16x16x32_bf16 v[140:143], v[236:239], v[204:207], v[140:143]
	v_lshrrev_b32_e32 v240, 4, v188
	v_and_b32_e32 v241, 7, v188
	v_bitop3_b32 v242, v240, v241, 3 bitop3:0x6c
	v_lshlrev_b32_e32 v243, 7, v188
	v_bfe_u32 v244, v188, 4, 2
	v_and_b32_e32 v245, 0xffffc780, v243
	v_and_b32_e32 v243, 0x2780, v243
	v_bitop3_b32 v244, v244, v241, 4 bitop3:0x36
	v_lshlrev_b32_e32 v242, 4, v242
	v_lshlrev_b32_e32 v244, 4, v244
	v_or_b32_e32 v185, v245, v242
	v_or_b32_e32 v184, v243, v242
	v_or_b32_e32 v183, v245, v244
	v_or_b32_e32 v182, v243, v244
	s_waitcnt vmcnt(0)
	s_barrier
	s_waitcnt vmcnt(11)
	ds_write_b128 v176, v[116:119]
	s_waitcnt vmcnt(10)
	ds_write_b128 v176, v[112:115] offset:4096
	s_waitcnt vmcnt(9)
	ds_write_b128 v176, v[104:107] offset:8192
	s_waitcnt vmcnt(8)
	ds_write_b128 v176, v[88:91] offset:12288
	s_waitcnt vmcnt(7)
	ds_write_b128 v176, v[80:83] offset:16384
	s_waitcnt vmcnt(6)
	ds_write_b128 v176, v[68:71] offset:20480
	s_waitcnt vmcnt(5)
	ds_write_b128 v176, v[60:63] offset:24576
	s_waitcnt vmcnt(4)
	ds_write_b128 v176, v[48:51] offset:28672
	s_waitcnt vmcnt(3)
	ds_write_b128 v176, v[100:103] offset:32768
	s_waitcnt vmcnt(2)
	ds_write_b128 v176, v[40:43] offset:36864
	s_waitcnt vmcnt(1)
	ds_write_b128 v176, v[24:27] offset:40960
	s_waitcnt vmcnt(0)
	ds_write_b128 v176, v[20:23] offset:45056
	s_waitcnt lgkmcnt(0)
	s_barrier
	ds_read_b128 v[20:23], v185
	ds_read_b128 v[24:27], v185 offset:2048
	ds_read_b128 v[40:43], v185 offset:4096
	ds_read_b128 v[48:51], v185 offset:6144
	ds_read_b128 v[60:63], v185 offset:8192
	ds_read_b128 v[68:71], v185 offset:10240
	ds_read_b128 v[80:83], v185 offset:12288
	ds_read_b128 v[88:91], v185 offset:14336
	ds_read_b128 v[100:103], v184 offset:32768
	ds_read_b128 v[104:107], v184 offset:34816
	ds_read_b128 v[112:115], v184 offset:36864
	ds_read_b128 v[116:119], v184 offset:38912
	s_waitcnt lgkmcnt(3)
	v_mfma_f32_16x16x32_bf16 v[172:175], v[20:23], v[100:103], v[172:175]
	s_waitcnt lgkmcnt(2)
	v_mfma_f32_16x16x32_bf16 v[168:171], v[20:23], v[104:107], v[168:171]
	s_waitcnt lgkmcnt(1)
	v_mfma_f32_16x16x32_bf16 v[164:167], v[20:23], v[112:115], v[164:167]
	s_waitcnt lgkmcnt(0)
	v_mfma_f32_16x16x32_bf16 v[20:23], v[20:23], v[116:119], v[160:163]
	v_mfma_f32_16x16x32_bf16 v[156:159], v[24:27], v[100:103], v[156:159]
	v_mfma_f32_16x16x32_bf16 v[152:155], v[24:27], v[104:107], v[152:155]
	v_mfma_f32_16x16x32_bf16 v[148:151], v[24:27], v[112:115], v[148:151]
	v_mfma_f32_16x16x32_bf16 v[24:27], v[24:27], v[116:119], v[144:147]
	v_mfma_f32_16x16x32_bf16 v[136:139], v[40:43], v[100:103], v[136:139]
	v_mfma_f32_16x16x32_bf16 v[132:135], v[40:43], v[104:107], v[132:135]
	v_mfma_f32_16x16x32_bf16 v[128:131], v[40:43], v[112:115], v[128:131]
	v_mfma_f32_16x16x32_bf16 v[40:43], v[40:43], v[116:119], v[124:127]
	v_mfma_f32_16x16x32_bf16 v[144:147], v[48:51], v[100:103], v[120:123]
	v_mfma_f32_16x16x32_bf16 v[160:163], v[48:51], v[104:107], v[108:111]
	v_mfma_f32_16x16x32_bf16 v[178:181], v[48:51], v[112:115], v[96:99]
	v_mfma_f32_16x16x32_bf16 v[48:51], v[48:51], v[116:119], v[92:95]
	v_mfma_f32_16x16x32_bf16 v[184:187], v[60:63], v[100:103], v[84:87]
	v_mfma_f32_16x16x32_bf16 v[16:19], v[80:83], v[112:115], v[16:19]
	v_mfma_f32_16x16x32_bf16 v[12:15], v[80:83], v[116:119], v[12:15]
	v_mfma_f32_16x16x32_bf16 v[8:11], v[88:91], v[100:103], v[8:11]
	v_mfma_f32_16x16x32_bf16 v[4:7], v[88:91], v[104:107], v[4:7]
	v_mfma_f32_16x16x32_bf16 v[0:3], v[88:91], v[112:115], v[0:3]
	v_mfma_f32_16x16x32_bf16 v[204:207], v[60:63], v[104:107], v[76:79]
	v_mfma_f32_16x16x32_bf16 v[208:211], v[60:63], v[112:115], v[72:75]
	v_mfma_f32_16x16x32_bf16 v[212:215], v[60:63], v[116:119], v[64:67]
	v_mfma_f32_16x16x32_bf16 v[216:219], v[68:71], v[100:103], v[56:59]
	v_mfma_f32_16x16x32_bf16 v[220:223], v[68:71], v[104:107], v[52:55]
	v_mfma_f32_16x16x32_bf16 v[224:227], v[68:71], v[112:115], v[44:47]
	v_mfma_f32_16x16x32_bf16 v[228:231], v[68:71], v[116:119], v[36:39]
	v_mfma_f32_16x16x32_bf16 v[232:235], v[80:83], v[100:103], v[32:35]
	v_mfma_f32_16x16x32_bf16 v[236:239], v[80:83], v[104:107], v[28:31]
	v_mfma_f32_16x16x32_bf16 v[140:143], v[88:91], v[116:119], v[140:143]
	s_nop 1
	ds_read_b128 v[28:31], v183
	ds_read_b128 v[32:35], v183 offset:2048
	ds_read_b128 v[36:39], v183 offset:4096
	ds_read_b128 v[44:47], v183 offset:6144
	ds_read_b128 v[240:243], v183 offset:8192
	ds_read_b128 v[244:247], v183 offset:10240
	ds_read_b128 v[248:251], v183 offset:12288
	ds_read_b128 v[190:193], v183 offset:14336
	ds_read_b128 v[198:201], v182 offset:32768
	ds_read_b128 v[194:197], v182 offset:34816
	ds_read_b128 v[52:55], v182 offset:36864
	ds_read_b128 v[56:59], v182 offset:38912
	s_waitcnt lgkmcnt(3)
	v_mfma_f32_16x16x32_bf16 v[124:127], v[28:31], v[198:201], v[172:175]
	s_waitcnt lgkmcnt(2)
	v_mfma_f32_16x16x32_bf16 v[120:123], v[28:31], v[194:197], v[168:171]
	s_waitcnt lgkmcnt(1)
	v_mfma_f32_16x16x32_bf16 v[116:119], v[28:31], v[52:55], v[164:167]
	s_waitcnt lgkmcnt(0)
	v_mfma_f32_16x16x32_bf16 v[112:115], v[28:31], v[56:59], v[20:23]
	v_mfma_f32_16x16x32_bf16 v[108:111], v[32:35], v[198:201], v[156:159]
	v_mfma_f32_16x16x32_bf16 v[104:107], v[32:35], v[194:197], v[152:155]
	v_mfma_f32_16x16x32_bf16 v[100:103], v[32:35], v[52:55], v[148:151]
	v_mfma_f32_16x16x32_bf16 v[96:99], v[32:35], v[56:59], v[24:27]
	v_mfma_f32_16x16x32_bf16 v[92:95], v[36:39], v[198:201], v[136:139]
	v_mfma_f32_16x16x32_bf16 v[88:91], v[36:39], v[194:197], v[132:135]
	v_mfma_f32_16x16x32_bf16 v[84:87], v[36:39], v[52:55], v[128:131]
	v_mfma_f32_16x16x32_bf16 v[80:83], v[36:39], v[56:59], v[40:43]
	v_mfma_f32_16x16x32_bf16 v[76:79], v[44:47], v[198:201], v[144:147]
	v_mfma_f32_16x16x32_bf16 v[72:75], v[44:47], v[194:197], v[160:163]
	v_mfma_f32_16x16x32_bf16 v[68:71], v[44:47], v[52:55], v[178:181]
	v_mfma_f32_16x16x32_bf16 v[64:67], v[44:47], v[56:59], v[48:51]
	v_mfma_f32_16x16x32_bf16 v[60:63], v[240:243], v[198:201], v[184:187]
	v_mfma_f32_16x16x32_bf16 v[184:187], v[240:243], v[194:197], v[204:207]
	v_mfma_f32_16x16x32_bf16 v[180:183], v[240:243], v[52:55], v[208:211]
	v_mfma_f32_16x16x32_bf16 v[48:51], v[240:243], v[56:59], v[212:215]
	v_xor_b32_e32 v240, 32, v203
	v_mfma_f32_16x16x32_bf16 v[44:47], v[244:247], v[198:201], v[216:219]
	v_mfma_f32_16x16x32_bf16 v[40:43], v[244:247], v[194:197], v[220:223]
	v_mfma_f32_16x16x32_bf16 v[36:39], v[244:247], v[52:55], v[224:227]
	v_mfma_f32_16x16x32_bf16 v[32:35], v[244:247], v[56:59], v[228:231]
	v_mfma_f32_16x16x32_bf16 v[28:31], v[248:251], v[198:201], v[232:235]
	v_mfma_f32_16x16x32_bf16 v[24:27], v[248:251], v[194:197], v[236:239]
	v_mfma_f32_16x16x32_bf16 v[20:23], v[248:251], v[52:55], v[16:19]
	v_mfma_f32_16x16x32_bf16 v[16:19], v[248:251], v[56:59], v[12:15]
	v_mfma_f32_16x16x32_bf16 v[12:15], v[190:193], v[198:201], v[8:11]
	v_mfma_f32_16x16x32_bf16 v[8:11], v[190:193], v[194:197], v[4:7]
	v_mfma_f32_16x16x32_bf16 v[4:7], v[190:193], v[52:55], v[0:3]
	v_mfma_f32_16x16x32_bf16 v[0:3], v[190:193], v[56:59], v[140:143]
